# remove the flag test from steady-state GEMM loop bodies (peeled first iteration keeps it)
# speedup vs baseline: 1.0032x; 1.0032x over previous
.LBB0_295:
	ds_read_b128 v[136:139], v147
	ds_read_b128 v[140:143], v147 offset:1024
	ds_read_b128 v[152:155], v147 offset:2048
	ds_read_b128 v[156:159], v147 offset:3072
	s_add_i32 s10, s7, 0xfffa0080
	s_cmp_eq_u32 s86, 12
	s_cselect_b32 s88, s6, s10
	s_cselect_b32 s87, s59, s79
	s_or_b32 s89, s88, 0x80
	s_add_i32 s10, s7, 0xfffe0000
	s_mov_b32 m0, s39
	ds_read_b128 v[160:163], v148
	ds_read_b128 v[164:167], v148 offset:1024
	ds_read_b128 v[168:171], v148 offset:2048
	ds_read_b128 v[172:175], v148 offset:3072
	ds_read_b128 v[176:179], v148 offset:4096
	ds_read_b128 v[180:183], v148 offset:5120
	ds_read_b128 v[184:187], v148 offset:6144
	ds_read_b128 v[188:191], v148 offset:7168
	buffer_load_dwordx4 v1, s[40:43], s10 offen lds
	s_mov_b32 m0, s45
	s_nop 0
	buffer_load_dwordx4 v1, s[40:43], s7 offen lds
	s_waitcnt lgkmcnt(8)
	s_barrier
	s_waitcnt lgkmcnt(0)
	s_setprio 1
	s_waitcnt lgkmcnt(7)
	v_mfma_f32_16x16x32_bf16 v[126:129], v[136:139], v[160:163], v[126:129]
	v_mfma_f32_16x16x32_bf16 v[122:125], v[152:155], v[160:163], v[122:125]
	s_waitcnt lgkmcnt(5)
	v_mfma_f32_16x16x32_bf16 v[118:121], v[136:139], v[168:171], v[118:121]
	v_mfma_f32_16x16x32_bf16 v[110:113], v[152:155], v[168:171], v[110:113]
	s_waitcnt lgkmcnt(3)
	v_mfma_f32_16x16x32_bf16 v[102:105], v[136:139], v[176:179], v[102:105]
	v_mfma_f32_16x16x32_bf16 v[94:97], v[152:155], v[176:179], v[94:97]
	s_waitcnt lgkmcnt(1)
	v_mfma_f32_16x16x32_bf16 v[86:89], v[136:139], v[184:187], v[86:89]
	v_mfma_f32_16x16x32_bf16 v[78:81], v[152:155], v[184:187], v[78:81]
	v_mfma_f32_16x16x32_bf16 v[126:129], v[140:143], v[164:167], v[126:129]
	v_mfma_f32_16x16x32_bf16 v[122:125], v[156:159], v[164:167], v[122:125]
	v_mfma_f32_16x16x32_bf16 v[118:121], v[140:143], v[172:175], v[118:121]
	v_mfma_f32_16x16x32_bf16 v[110:113], v[156:159], v[172:175], v[110:113]
	v_mfma_f32_16x16x32_bf16 v[102:105], v[140:143], v[180:183], v[102:105]
	v_mfma_f32_16x16x32_bf16 v[94:97], v[156:159], v[180:183], v[94:97]
	s_waitcnt lgkmcnt(0)
	v_mfma_f32_16x16x32_bf16 v[86:89], v[140:143], v[188:191], v[86:89]
	v_mfma_f32_16x16x32_bf16 v[78:81], v[156:159], v[188:191], v[78:81]
	s_setprio 0
	s_barrier
	s_mov_b32 m0, s23
	s_mov_b32 s10, s42
	s_mov_b32 s11, s43
	ds_read_b128 v[192:195], v149
	ds_read_b128 v[196:199], v149 offset:1024
	ds_read_b128 v[200:203], v149 offset:2048
	ds_read_b128 v[204:207], v149 offset:3072
	buffer_load_dwordx4 v144, s[8:11], s87 offen lds
	s_add_i32 s33, s87, 0x20000
	s_mov_b32 m0, s24
	s_nop 0
	buffer_load_dwordx4 v144, s[8:11], s33 offen lds
	s_barrier
	s_waitcnt lgkmcnt(0)
	s_setprio 1
	s_waitcnt lgkmcnt(3)
	v_mfma_f32_16x16x32_bf16 v[114:117], v[192:195], v[160:163], v[114:117]
	s_waitcnt lgkmcnt(1)
	v_mfma_f32_16x16x32_bf16 v[106:109], v[200:203], v[160:163], v[106:109]
	v_mfma_f32_16x16x32_bf16 v[98:101], v[192:195], v[168:171], v[98:101]
	v_mfma_f32_16x16x32_bf16 v[90:93], v[200:203], v[168:171], v[90:93]
	v_mfma_f32_16x16x32_bf16 v[82:85], v[192:195], v[176:179], v[82:85]
	v_mfma_f32_16x16x32_bf16 v[74:77], v[200:203], v[176:179], v[74:77]
	v_mfma_f32_16x16x32_bf16 v[70:73], v[192:195], v[184:187], v[70:73]
	v_mfma_f32_16x16x32_bf16 v[66:69], v[200:203], v[184:187], v[66:69]
	v_mfma_f32_16x16x32_bf16 v[114:117], v[196:199], v[164:167], v[114:117]
	s_waitcnt lgkmcnt(0)
	v_mfma_f32_16x16x32_bf16 v[106:109], v[204:207], v[164:167], v[106:109]
	v_mfma_f32_16x16x32_bf16 v[98:101], v[196:199], v[172:175], v[98:101]
	v_mfma_f32_16x16x32_bf16 v[90:93], v[204:207], v[172:175], v[90:93]
	v_mfma_f32_16x16x32_bf16 v[82:85], v[196:199], v[180:183], v[82:85]
	v_mfma_f32_16x16x32_bf16 v[74:77], v[204:207], v[180:183], v[74:77]
	v_mfma_f32_16x16x32_bf16 v[70:73], v[196:199], v[188:191], v[70:73]
	v_mfma_f32_16x16x32_bf16 v[66:69], v[204:207], v[188:191], v[66:69]
	s_setprio 0
	s_mov_b32 m0, s22
	s_barrier
	ds_read_b128 v[160:163], v148 offset:16384
	ds_read_b128 v[164:167], v148 offset:17408
	ds_read_b128 v[168:171], v148 offset:18432
	ds_read_b128 v[172:175], v148 offset:19456
	ds_read_b128 v[176:179], v148 offset:20480
	ds_read_b128 v[180:183], v148 offset:21504
	ds_read_b128 v[184:187], v148 offset:22528
	ds_read_b128 v[188:191], v148 offset:23552
	buffer_load_dwordx4 v1, s[40:43], s88 offen lds
	s_add_i32 s33, s88, 0x20000
	s_mov_b32 m0, s25
	s_nop 0
	buffer_load_dwordx4 v1, s[40:43], s33 offen lds
	s_barrier
	s_waitcnt lgkmcnt(0)
	s_setprio 1
	s_waitcnt lgkmcnt(7)
	v_mfma_f32_16x16x32_bf16 v[62:65], v[136:139], v[160:163], v[62:65]
	v_mfma_f32_16x16x32_bf16 v[58:61], v[152:155], v[160:163], v[58:61]
	s_waitcnt lgkmcnt(5)
	v_mfma_f32_16x16x32_bf16 v[54:57], v[136:139], v[168:171], v[54:57]
	v_mfma_f32_16x16x32_bf16 v[46:49], v[152:155], v[168:171], v[46:49]
	s_waitcnt lgkmcnt(3)
	v_mfma_f32_16x16x32_bf16 v[38:41], v[136:139], v[176:179], v[38:41]
	v_mfma_f32_16x16x32_bf16 v[30:33], v[152:155], v[176:179], v[30:33]
	s_waitcnt lgkmcnt(1)
	v_mfma_f32_16x16x32_bf16 v[22:25], v[136:139], v[184:187], v[22:25]
	v_mfma_f32_16x16x32_bf16 v[14:17], v[152:155], v[184:187], v[14:17]
	v_mfma_f32_16x16x32_bf16 v[62:65], v[140:143], v[164:167], v[62:65]
	v_mfma_f32_16x16x32_bf16 v[58:61], v[156:159], v[164:167], v[58:61]
	v_mfma_f32_16x16x32_bf16 v[54:57], v[140:143], v[172:175], v[54:57]
	v_mfma_f32_16x16x32_bf16 v[46:49], v[156:159], v[172:175], v[46:49]
	v_mfma_f32_16x16x32_bf16 v[38:41], v[140:143], v[180:183], v[38:41]
	v_mfma_f32_16x16x32_bf16 v[30:33], v[156:159], v[180:183], v[30:33]
	s_waitcnt lgkmcnt(0)
	v_mfma_f32_16x16x32_bf16 v[22:25], v[140:143], v[188:191], v[22:25]
	v_mfma_f32_16x16x32_bf16 v[14:17], v[156:159], v[188:191], v[14:17]
	s_setprio 0
	s_barrier
	s_mov_b32 m0, s26
	s_add_i32 s33, s87, 0x40000
	buffer_load_dwordx4 v144, s[8:11], s33 offen lds
	s_add_i32 s33, s87, 0x60000
	s_mov_b32 m0, s27
	s_nop 0
	buffer_load_dwordx4 v144, s[8:11], s33 offen lds
	s_waitcnt vmcnt(6)
	s_barrier
	s_setprio 1
	v_mfma_f32_16x16x32_bf16 v[50:53], v[192:195], v[160:163], v[50:53]
	v_mfma_f32_16x16x32_bf16 v[42:45], v[200:203], v[160:163], v[42:45]
	v_mfma_f32_16x16x32_bf16 v[34:37], v[192:195], v[168:171], v[34:37]
	v_mfma_f32_16x16x32_bf16 v[26:29], v[200:203], v[168:171], v[26:29]
	v_mfma_f32_16x16x32_bf16 v[18:21], v[192:195], v[176:179], v[18:21]
	v_mfma_f32_16x16x32_bf16 v[10:13], v[200:203], v[176:179], v[10:13]
	v_mfma_f32_16x16x32_bf16 v[6:9], v[192:195], v[184:187], v[6:9]
	v_mfma_f32_16x16x32_bf16 v[2:5], v[200:203], v[184:187], v[2:5]
	v_mfma_f32_16x16x32_bf16 v[50:53], v[196:199], v[164:167], v[50:53]
	v_mfma_f32_16x16x32_bf16 v[42:45], v[204:207], v[164:167], v[42:45]
	v_mfma_f32_16x16x32_bf16 v[34:37], v[196:199], v[172:175], v[34:37]
	v_mfma_f32_16x16x32_bf16 v[26:29], v[204:207], v[172:175], v[26:29]
	v_mfma_f32_16x16x32_bf16 v[18:21], v[196:199], v[180:183], v[18:21]
	v_mfma_f32_16x16x32_bf16 v[10:13], v[204:207], v[180:183], v[10:13]
	v_mfma_f32_16x16x32_bf16 v[6:9], v[196:199], v[188:191], v[6:9]
	v_mfma_f32_16x16x32_bf16 v[2:5], v[204:207], v[188:191], v[2:5]
	s_setprio 0
	s_barrier
	ds_read_b128 v[136:139], v150
	ds_read_b128 v[140:143], v150 offset:1024
	ds_read_b128 v[152:155], v150 offset:2048
	ds_read_b128 v[156:159], v150 offset:3072
	s_mov_b32 m0, s28
	s_add_i32 s33, s88, 0x40000
	ds_read_b128 v[160:163], v148 offset:32768
	ds_read_b128 v[164:167], v148 offset:33792
	ds_read_b128 v[168:171], v148 offset:34816
	ds_read_b128 v[172:175], v148 offset:35840
	ds_read_b128 v[176:179], v148 offset:36864
	ds_read_b128 v[180:183], v148 offset:37888
	ds_read_b128 v[184:187], v148 offset:38912
	ds_read_b128 v[188:191], v148 offset:39936
	buffer_load_dwordx4 v1, s[40:43], s33 offen lds
	s_add_i32 s33, s88, 0x60000
	s_mov_b32 m0, s29
	s_nop 0
	buffer_load_dwordx4 v1, s[40:43], s33 offen lds
	s_waitcnt lgkmcnt(8)
	s_barrier
	s_waitcnt lgkmcnt(0)
	s_setprio 1
	s_waitcnt lgkmcnt(7)
	v_mfma_f32_16x16x32_bf16 v[126:129], v[136:139], v[160:163], v[126:129]
	v_mfma_f32_16x16x32_bf16 v[122:125], v[152:155], v[160:163], v[122:125]
	s_waitcnt lgkmcnt(5)
	v_mfma_f32_16x16x32_bf16 v[118:121], v[136:139], v[168:171], v[118:121]
	v_mfma_f32_16x16x32_bf16 v[110:113], v[152:155], v[168:171], v[110:113]
	s_waitcnt lgkmcnt(3)
	v_mfma_f32_16x16x32_bf16 v[102:105], v[136:139], v[176:179], v[102:105]
	v_mfma_f32_16x16x32_bf16 v[94:97], v[152:155], v[176:179], v[94:97]
	s_waitcnt lgkmcnt(1)
	v_mfma_f32_16x16x32_bf16 v[86:89], v[136:139], v[184:187], v[86:89]
	v_mfma_f32_16x16x32_bf16 v[78:81], v[152:155], v[184:187], v[78:81]
	v_mfma_f32_16x16x32_bf16 v[126:129], v[140:143], v[164:167], v[126:129]
	v_mfma_f32_16x16x32_bf16 v[122:125], v[156:159], v[164:167], v[122:125]
	v_mfma_f32_16x16x32_bf16 v[118:121], v[140:143], v[172:175], v[118:121]
	v_mfma_f32_16x16x32_bf16 v[110:113], v[156:159], v[172:175], v[110:113]
	v_mfma_f32_16x16x32_bf16 v[102:105], v[140:143], v[180:183], v[102:105]
	v_mfma_f32_16x16x32_bf16 v[94:97], v[156:159], v[180:183], v[94:97]
	s_waitcnt lgkmcnt(0)
	v_mfma_f32_16x16x32_bf16 v[86:89], v[140:143], v[188:191], v[86:89]
	v_mfma_f32_16x16x32_bf16 v[78:81], v[156:159], v[188:191], v[78:81]
	s_setprio 0
	s_barrier
	s_mov_b32 m0, s31
	s_or_b32 s33, s87, 0x80
	ds_read_b128 v[192:195], v151
	ds_read_b128 v[196:199], v151 offset:1024
	ds_read_b128 v[200:203], v151 offset:2048
	ds_read_b128 v[204:207], v151 offset:3072
	buffer_load_dwordx4 v144, s[8:11], s33 offen lds
	s_add_i32 s33, s87, 0x20080
	s_mov_b32 m0, s34
	s_nop 0
	buffer_load_dwordx4 v144, s[8:11], s33 offen lds
	s_waitcnt vmcnt(10)
	s_barrier
	s_waitcnt lgkmcnt(0)
	s_setprio 1
	s_waitcnt lgkmcnt(3)
	v_mfma_f32_16x16x32_bf16 v[114:117], v[192:195], v[160:163], v[114:117]
	s_waitcnt lgkmcnt(1)
	v_mfma_f32_16x16x32_bf16 v[106:109], v[200:203], v[160:163], v[106:109]
	v_mfma_f32_16x16x32_bf16 v[98:101], v[192:195], v[168:171], v[98:101]
	v_mfma_f32_16x16x32_bf16 v[90:93], v[200:203], v[168:171], v[90:93]
	v_mfma_f32_16x16x32_bf16 v[82:85], v[192:195], v[176:179], v[82:85]
	v_mfma_f32_16x16x32_bf16 v[74:77], v[200:203], v[176:179], v[74:77]
	v_mfma_f32_16x16x32_bf16 v[70:73], v[192:195], v[184:187], v[70:73]
	v_mfma_f32_16x16x32_bf16 v[66:69], v[200:203], v[184:187], v[66:69]
	v_mfma_f32_16x16x32_bf16 v[114:117], v[196:199], v[164:167], v[114:117]
	s_waitcnt lgkmcnt(0)
	v_mfma_f32_16x16x32_bf16 v[106:109], v[204:207], v[164:167], v[106:109]
	v_mfma_f32_16x16x32_bf16 v[98:101], v[196:199], v[172:175], v[98:101]
	v_mfma_f32_16x16x32_bf16 v[90:93], v[204:207], v[172:175], v[90:93]
	v_mfma_f32_16x16x32_bf16 v[82:85], v[196:199], v[180:183], v[82:85]
	v_mfma_f32_16x16x32_bf16 v[74:77], v[204:207], v[180:183], v[74:77]
	v_mfma_f32_16x16x32_bf16 v[70:73], v[196:199], v[188:191], v[70:73]
	v_mfma_f32_16x16x32_bf16 v[66:69], v[204:207], v[188:191], v[66:69]
	s_setprio 0
	s_mov_b32 m0, s35
	s_barrier
	ds_read_b128 v[160:163], v148 offset:49152
	ds_read_b128 v[164:167], v148 offset:50176
	ds_read_b128 v[168:171], v148 offset:51200
	ds_read_b128 v[172:175], v148 offset:52224
	ds_read_b128 v[176:179], v148 offset:53248
	ds_read_b128 v[180:183], v148 offset:54272
	ds_read_b128 v[184:187], v148 offset:55296
	ds_read_b128 v[188:191], v148 offset:56320
	buffer_load_dwordx4 v1, s[40:43], s89 offen lds
	s_add_i32 s88, s88, 0x20080
	s_mov_b32 m0, s36
	s_nop 0
	buffer_load_dwordx4 v1, s[40:43], s88 offen lds
	s_barrier
	s_waitcnt lgkmcnt(0)
	s_setprio 1
	s_waitcnt lgkmcnt(7)
	v_mfma_f32_16x16x32_bf16 v[62:65], v[136:139], v[160:163], v[62:65]
	v_mfma_f32_16x16x32_bf16 v[58:61], v[152:155], v[160:163], v[58:61]
	s_waitcnt lgkmcnt(5)
	v_mfma_f32_16x16x32_bf16 v[54:57], v[136:139], v[168:171], v[54:57]
	v_mfma_f32_16x16x32_bf16 v[46:49], v[152:155], v[168:171], v[46:49]
	s_waitcnt lgkmcnt(3)
	v_mfma_f32_16x16x32_bf16 v[38:41], v[136:139], v[176:179], v[38:41]
	v_mfma_f32_16x16x32_bf16 v[30:33], v[152:155], v[176:179], v[30:33]
	s_waitcnt lgkmcnt(1)
	v_mfma_f32_16x16x32_bf16 v[22:25], v[136:139], v[184:187], v[22:25]
	v_mfma_f32_16x16x32_bf16 v[14:17], v[152:155], v[184:187], v[14:17]
	v_mfma_f32_16x16x32_bf16 v[62:65], v[140:143], v[164:167], v[62:65]
	v_mfma_f32_16x16x32_bf16 v[58:61], v[156:159], v[164:167], v[58:61]
	v_mfma_f32_16x16x32_bf16 v[54:57], v[140:143], v[172:175], v[54:57]
	v_mfma_f32_16x16x32_bf16 v[46:49], v[156:159], v[172:175], v[46:49]
	v_mfma_f32_16x16x32_bf16 v[38:41], v[140:143], v[180:183], v[38:41]
	v_mfma_f32_16x16x32_bf16 v[30:33], v[156:159], v[180:183], v[30:33]
	s_waitcnt lgkmcnt(0)
	v_mfma_f32_16x16x32_bf16 v[22:25], v[140:143], v[188:191], v[22:25]
	v_mfma_f32_16x16x32_bf16 v[14:17], v[156:159], v[188:191], v[14:17]
	s_setprio 0
	s_barrier
	s_mov_b32 m0, s37
	s_add_i32 s33, s87, 0x40080
	buffer_load_dwordx4 v144, s[8:11], s33 offen lds
	s_add_i32 s87, s87, 0x60080
	s_mov_b32 m0, s38
	s_nop 0
	buffer_load_dwordx4 v144, s[8:11], s87 offen lds
	s_waitcnt vmcnt(6)
	s_barrier
	s_setprio 1
	v_mfma_f32_16x16x32_bf16 v[50:53], v[192:195], v[160:163], v[50:53]
	v_mfma_f32_16x16x32_bf16 v[42:45], v[200:203], v[160:163], v[42:45]
	v_mfma_f32_16x16x32_bf16 v[34:37], v[192:195], v[168:171], v[34:37]
	v_mfma_f32_16x16x32_bf16 v[26:29], v[200:203], v[168:171], v[26:29]
	v_mfma_f32_16x16x32_bf16 v[18:21], v[192:195], v[176:179], v[18:21]
	v_mfma_f32_16x16x32_bf16 v[10:13], v[200:203], v[176:179], v[10:13]
	v_mfma_f32_16x16x32_bf16 v[6:9], v[192:195], v[184:187], v[6:9]
	v_mfma_f32_16x16x32_bf16 v[2:5], v[200:203], v[184:187], v[2:5]
	v_mfma_f32_16x16x32_bf16 v[50:53], v[196:199], v[164:167], v[50:53]
	v_mfma_f32_16x16x32_bf16 v[42:45], v[204:207], v[164:167], v[42:45]
	v_mfma_f32_16x16x32_bf16 v[34:37], v[196:199], v[172:175], v[34:37]
	v_mfma_f32_16x16x32_bf16 v[26:29], v[204:207], v[172:175], v[26:29]
	v_mfma_f32_16x16x32_bf16 v[18:21], v[196:199], v[180:183], v[18:21]
	v_mfma_f32_16x16x32_bf16 v[10:13], v[204:207], v[180:183], v[10:13]
	v_mfma_f32_16x16x32_bf16 v[6:9], v[196:199], v[188:191], v[6:9]
	v_mfma_f32_16x16x32_bf16 v[2:5], v[204:207], v[188:191], v[2:5]
	s_setprio 0
	s_add_i32 s86, s86, 2
	s_addk_i32 s7, 0x100
	s_addk_i32 s79, 0x100
	s_cmp_gt_u32 s86, 13
	s_barrier
	s_cbranch_scc0 .LBB0_295
	v_lshl_add_u32 v142, s78, 8, v145
	v_or_b32_e32 v140, 16, v142
	v_or_b32_e32 v138, 32, v142
	v_or_b32_e32 v136, 48, v142
	s_mov_b64 s[6:7], -1
	s_cmp_gt_i32 s73, 3
	v_ashrrev_i32_e32 v143, 31, v142
	v_ashrrev_i32_e32 v141, 31, v140
	v_ashrrev_i32_e32 v139, 31, v138
	v_ashrrev_i32_e32 v137, 31, v136
	s_cbranch_scc0 .LBB0_298
	v_pk_mul_f32 v[154:155], v[128:129], v[116:117]
	v_pk_mul_f32 v[152:153], v[126:127], v[114:115]
	v_pk_mul_f32 v[156:157], v[124:125], v[108:109]
	v_pk_mul_f32 v[158:159], v[122:123], v[106:107]
	v_cvt_pk_bf16_f32 v152, v152, v153
	v_cvt_pk_bf16_f32 v153, v154, v155
	v_lshlrev_b32_e32 v134, 1, v146
	v_cvt_pk_bf16_f32 v154, v158, v159
	v_cvt_pk_bf16_f32 v155, v156, v157
	v_lshlrev_b64 v[156:157], 12, v[142:143]
	v_lshl_add_u64 v[156:157], s[82:83], 0, v[156:157]
	v_lshl_or_b32 v134, s73, 8, v134
	v_lshl_add_u64 v[156:157], v[156:157], 0, v[134:135]
	global_store_dwordx4 v[156:157], v[152:155], off offset:1024
	s_mov_b32 s100, 1
	v_pk_mul_f32 v[158:159], v[112:113], v[92:93]
	v_pk_mul_f32 v[160:161], v[110:111], v[90:91]
	v_pk_mul_f32 v[154:155], v[120:121], v[100:101]
	v_pk_mul_f32 v[152:153], v[118:119], v[98:99]
	s_mov_b64 s[6:7], 0
	v_cvt_pk_bf16_f32 v152, v152, v153
	v_cvt_pk_bf16_f32 v153, v154, v155
	v_cvt_pk_bf16_f32 v154, v160, v161
	v_cvt_pk_bf16_f32 v155, v158, v159
	v_lshlrev_b64 v[158:159], 12, v[140:141]
	v_lshl_add_u64 v[158:159], s[82:83], 0, v[158:159]
	v_lshl_add_u64 v[158:159], v[158:159], 0, v[134:135]
	global_store_dwordx4 v[158:159], v[152:155], off offset:1024
	s_mov_b32 s100, 1
	v_pk_mul_f32 v[158:159], v[96:97], v[76:77]
	v_pk_mul_f32 v[160:161], v[94:95], v[74:75]
	v_pk_mul_f32 v[154:155], v[104:105], v[84:85]
	v_pk_mul_f32 v[152:153], v[102:103], v[82:83]
	s_nop 0
	v_cvt_pk_bf16_f32 v152, v152, v153
	v_cvt_pk_bf16_f32 v153, v154, v155
	v_cvt_pk_bf16_f32 v154, v160, v161
	v_cvt_pk_bf16_f32 v155, v158, v159
	v_lshlrev_b64 v[158:159], 12, v[138:139]
	v_lshl_add_u64 v[158:159], s[82:83], 0, v[158:159]
	v_lshl_add_u64 v[158:159], v[158:159], 0, v[134:135]
	global_store_dwordx4 v[158:159], v[152:155], off offset:1024
	s_mov_b32 s100, 1
	v_pk_mul_f32 v[158:159], v[80:81], v[68:69]
	v_pk_mul_f32 v[160:161], v[78:79], v[66:67]
	v_pk_mul_f32 v[154:155], v[88:89], v[72:73]
	v_pk_mul_f32 v[152:153], v[86:87], v[70:71]
	s_nop 0
	v_cvt_pk_bf16_f32 v152, v152, v153
	v_cvt_pk_bf16_f32 v153, v154, v155
	v_cvt_pk_bf16_f32 v154, v160, v161
	v_cvt_pk_bf16_f32 v155, v158, v159
	v_lshlrev_b64 v[158:159], 12, v[136:137]
	v_lshl_add_u64 v[158:159], s[82:83], 0, v[158:159]
	v_lshl_add_u64 v[158:159], v[158:159], 0, v[134:135]
	global_store_dwordx4 v[158:159], v[152:155], off offset:1024
	s_mov_b32 s100, 1
	v_pk_mul_f32 v[158:159], v[60:61], v[44:45]
	v_pk_mul_f32 v[160:161], v[58:59], v[42:43]
	v_pk_mul_f32 v[154:155], v[64:65], v[52:53]
	v_pk_mul_f32 v[152:153], v[62:63], v[50:51]
	s_nop 0
	v_cvt_pk_bf16_f32 v152, v152, v153
	v_cvt_pk_bf16_f32 v153, v154, v155
	v_cvt_pk_bf16_f32 v154, v160, v161
	v_cvt_pk_bf16_f32 v155, v158, v159
	v_add_co_u32_e32 v158, vcc, s47, v156
	v_pk_mul_f32 v[160:161], v[46:47], v[26:27]
	s_nop 0
	v_addc_co_u32_e32 v159, vcc, 0, v157, vcc
	global_store_dwordx4 v[158:159], v[152:155], off offset:1024
	s_mov_b32 s100, 1
	v_pk_mul_f32 v[158:159], v[48:49], v[28:29]
	s_nop 0
	v_pk_mul_f32 v[154:155], v[56:57], v[36:37]
	v_pk_mul_f32 v[152:153], v[54:55], v[34:35]
	s_nop 0
	v_cvt_pk_bf16_f32 v152, v152, v153
	v_cvt_pk_bf16_f32 v153, v154, v155
	v_cvt_pk_bf16_f32 v154, v160, v161
	v_cvt_pk_bf16_f32 v155, v158, v159
	v_add_co_u32_e32 v158, vcc, s49, v156
	v_pk_mul_f32 v[160:161], v[30:31], v[10:11]
	s_nop 0
	v_addc_co_u32_e32 v159, vcc, 0, v157, vcc
	global_store_dwordx4 v[158:159], v[152:155], off offset:1024
	s_mov_b32 s100, 1
	v_pk_mul_f32 v[158:159], v[32:33], v[12:13]
	s_nop 0
	v_pk_mul_f32 v[154:155], v[40:41], v[20:21]
	v_pk_mul_f32 v[152:153], v[38:39], v[18:19]
	s_nop 0
	v_cvt_pk_bf16_f32 v152, v152, v153
	v_cvt_pk_bf16_f32 v153, v154, v155
	v_cvt_pk_bf16_f32 v154, v160, v161
	v_cvt_pk_bf16_f32 v155, v158, v159
	v_add_co_u32_e32 v158, vcc, s50, v156
	v_pk_mul_f32 v[160:161], v[14:15], v[2:3]
	s_nop 0
	v_addc_co_u32_e32 v159, vcc, 0, v157, vcc
	v_add_co_u32_e32 v156, vcc, 0xb0000, v156
	global_store_dwordx4 v[158:159], v[152:155], off offset:1024
	s_mov_b32 s100, 1
	s_nop 0
	v_addc_co_u32_e32 v157, vcc, 0, v157, vcc
	v_pk_mul_f32 v[154:155], v[24:25], v[8:9]
	v_pk_mul_f32 v[152:153], v[22:23], v[6:7]
	v_pk_mul_f32 v[158:159], v[16:17], v[4:5]
	v_cvt_pk_bf16_f32 v152, v152, v153
	v_cvt_pk_bf16_f32 v153, v154, v155
	v_cvt_pk_bf16_f32 v154, v160, v161
	s_nop 0
	v_cvt_pk_bf16_f32 v155, v158, v159
	global_store_dwordx4 v[156:157], v[152:155], off offset:1024
	s_mov_b32 s100, 1

.LBB0_450:
	ds_read_b128 v[118:121], v197
	ds_read_b128 v[126:129], v197 offset:1024
	ds_read_b128 v[130:133], v197 offset:2048
	ds_read_b128 v[138:141], v197 offset:3072
	s_add_i32 s10, s7, 0xfffa0080
	s_cmp_eq_u32 s17, 12
	s_cselect_b32 s87, s6, s10
	s_cselect_b32 s86, s72, s16
	s_or_b32 s88, s87, 0x80
	s_add_i32 s10, s7, 0xfffe0000
	s_mov_b32 m0, s41
	ds_read_b128 v[146:149], v198
	ds_read_b128 v[150:153], v198 offset:1024
	ds_read_b128 v[154:157], v198 offset:2048
	ds_read_b128 v[158:161], v198 offset:3072
	ds_read_b128 v[162:165], v198 offset:4096
	ds_read_b128 v[166:169], v198 offset:5120
	ds_read_b128 v[170:173], v198 offset:6144
	ds_read_b128 v[174:177], v198 offset:7168
	buffer_load_dwordx4 v1, s[48:51], s10 offen lds
	s_mov_b32 m0, s42
	s_nop 0
	buffer_load_dwordx4 v1, s[48:51], s7 offen lds
	s_waitcnt lgkmcnt(8)
	s_barrier
	s_waitcnt lgkmcnt(0)
	s_setprio 1
	s_waitcnt lgkmcnt(7)
	v_mfma_f32_16x16x32_bf16 v[142:145], v[118:121], v[146:149], v[142:145]
	v_mfma_f32_16x16x32_bf16 v[134:137], v[130:133], v[146:149], v[134:137]
	s_waitcnt lgkmcnt(5)
	v_mfma_f32_16x16x32_bf16 v[122:125], v[118:121], v[154:157], v[122:125]
	v_mfma_f32_16x16x32_bf16 v[114:117], v[130:133], v[154:157], v[114:117]
	s_waitcnt lgkmcnt(3)
	v_mfma_f32_16x16x32_bf16 v[94:97], v[118:121], v[162:165], v[94:97]
	v_mfma_f32_16x16x32_bf16 v[90:93], v[130:133], v[162:165], v[90:93]
	s_waitcnt lgkmcnt(1)
	v_mfma_f32_16x16x32_bf16 v[82:85], v[118:121], v[170:173], v[82:85]
	v_mfma_f32_16x16x32_bf16 v[74:77], v[130:133], v[170:173], v[74:77]
	v_mfma_f32_16x16x32_bf16 v[142:145], v[126:129], v[150:153], v[142:145]
	v_mfma_f32_16x16x32_bf16 v[134:137], v[138:141], v[150:153], v[134:137]
	v_mfma_f32_16x16x32_bf16 v[122:125], v[126:129], v[158:161], v[122:125]
	v_mfma_f32_16x16x32_bf16 v[114:117], v[138:141], v[158:161], v[114:117]
	v_mfma_f32_16x16x32_bf16 v[94:97], v[126:129], v[166:169], v[94:97]
	v_mfma_f32_16x16x32_bf16 v[90:93], v[138:141], v[166:169], v[90:93]
	s_waitcnt lgkmcnt(0)
	v_mfma_f32_16x16x32_bf16 v[82:85], v[126:129], v[174:177], v[82:85]
	v_mfma_f32_16x16x32_bf16 v[74:77], v[138:141], v[174:177], v[74:77]
	s_setprio 0
	s_barrier
	s_mov_b32 m0, s21
	s_mov_b32 s10, s50
	s_mov_b32 s11, s51
	ds_read_b128 v[178:181], v199
	ds_read_b128 v[182:185], v199 offset:1024
	ds_read_b128 v[190:193], v199 offset:2048
	ds_read_b128 v[202:205], v199 offset:3072
	buffer_load_dwordx4 v194, s[8:11], s86 offen lds
	s_add_i32 s33, s86, 0x20000
	s_mov_b32 m0, s22
	s_nop 0
	buffer_load_dwordx4 v194, s[8:11], s33 offen lds
	s_barrier
	s_waitcnt lgkmcnt(0)
	s_setprio 1
	s_waitcnt lgkmcnt(3)
	v_mfma_f32_16x16x32_bf16 v[110:113], v[178:181], v[146:149], v[110:113]
	s_waitcnt lgkmcnt(1)
	v_mfma_f32_16x16x32_bf16 v[106:109], v[190:193], v[146:149], v[106:109]
	v_mfma_f32_16x16x32_bf16 v[102:105], v[178:181], v[154:157], v[102:105]
	v_mfma_f32_16x16x32_bf16 v[98:101], v[190:193], v[154:157], v[98:101]
	v_mfma_f32_16x16x32_bf16 v[86:89], v[178:181], v[162:165], v[86:89]
	v_mfma_f32_16x16x32_bf16 v[78:81], v[190:193], v[162:165], v[78:81]
	v_mfma_f32_16x16x32_bf16 v[70:73], v[178:181], v[170:173], v[70:73]
	v_mfma_f32_16x16x32_bf16 v[66:69], v[190:193], v[170:173], v[66:69]
	v_mfma_f32_16x16x32_bf16 v[110:113], v[182:185], v[150:153], v[110:113]
	s_waitcnt lgkmcnt(0)
	v_mfma_f32_16x16x32_bf16 v[106:109], v[202:205], v[150:153], v[106:109]
	v_mfma_f32_16x16x32_bf16 v[102:105], v[182:185], v[158:161], v[102:105]
	v_mfma_f32_16x16x32_bf16 v[98:101], v[202:205], v[158:161], v[98:101]
	v_mfma_f32_16x16x32_bf16 v[86:89], v[182:185], v[166:169], v[86:89]
	v_mfma_f32_16x16x32_bf16 v[78:81], v[202:205], v[166:169], v[78:81]
	v_mfma_f32_16x16x32_bf16 v[70:73], v[182:185], v[174:177], v[70:73]
	v_mfma_f32_16x16x32_bf16 v[66:69], v[202:205], v[174:177], v[66:69]
	s_setprio 0
	s_mov_b32 m0, s20
	s_barrier
	ds_read_b128 v[146:149], v198 offset:16384
	ds_read_b128 v[150:153], v198 offset:17408
	ds_read_b128 v[154:157], v198 offset:18432
	ds_read_b128 v[158:161], v198 offset:19456
	ds_read_b128 v[162:165], v198 offset:20480
	ds_read_b128 v[166:169], v198 offset:21504
	ds_read_b128 v[170:173], v198 offset:22528
	ds_read_b128 v[174:177], v198 offset:23552
	buffer_load_dwordx4 v1, s[48:51], s87 offen lds
	s_add_i32 s33, s87, 0x20000
	s_mov_b32 m0, s23
	s_nop 0
	buffer_load_dwordx4 v1, s[48:51], s33 offen lds
	s_barrier
	s_waitcnt lgkmcnt(0)
	s_setprio 1
	s_waitcnt lgkmcnt(7)
	v_mfma_f32_16x16x32_bf16 v[62:65], v[118:121], v[146:149], v[62:65]
	v_mfma_f32_16x16x32_bf16 v[58:61], v[130:133], v[146:149], v[58:61]
	s_waitcnt lgkmcnt(5)
	v_mfma_f32_16x16x32_bf16 v[50:53], v[118:121], v[154:157], v[50:53]
	v_mfma_f32_16x16x32_bf16 v[42:45], v[130:133], v[154:157], v[42:45]
	s_waitcnt lgkmcnt(3)
	v_mfma_f32_16x16x32_bf16 v[34:37], v[118:121], v[162:165], v[34:37]
	v_mfma_f32_16x16x32_bf16 v[26:29], v[130:133], v[162:165], v[26:29]
	s_waitcnt lgkmcnt(1)
	v_mfma_f32_16x16x32_bf16 v[18:21], v[118:121], v[170:173], v[18:21]
	v_mfma_f32_16x16x32_bf16 v[10:13], v[130:133], v[170:173], v[10:13]
	v_mfma_f32_16x16x32_bf16 v[62:65], v[126:129], v[150:153], v[62:65]
	v_mfma_f32_16x16x32_bf16 v[58:61], v[138:141], v[150:153], v[58:61]
	v_mfma_f32_16x16x32_bf16 v[50:53], v[126:129], v[158:161], v[50:53]
	v_mfma_f32_16x16x32_bf16 v[42:45], v[138:141], v[158:161], v[42:45]
	v_mfma_f32_16x16x32_bf16 v[34:37], v[126:129], v[166:169], v[34:37]
	v_mfma_f32_16x16x32_bf16 v[26:29], v[138:141], v[166:169], v[26:29]
	s_waitcnt lgkmcnt(0)
	v_mfma_f32_16x16x32_bf16 v[18:21], v[126:129], v[174:177], v[18:21]
	v_mfma_f32_16x16x32_bf16 v[10:13], v[138:141], v[174:177], v[10:13]
	s_setprio 0
	s_barrier
	s_mov_b32 m0, s24
	s_add_i32 s33, s86, 0x40000
	buffer_load_dwordx4 v194, s[8:11], s33 offen lds
	s_add_i32 s33, s86, 0x60000
	s_mov_b32 m0, s25
	s_nop 0
	buffer_load_dwordx4 v194, s[8:11], s33 offen lds
	s_waitcnt vmcnt(6)
	s_barrier
	s_setprio 1
	v_mfma_f32_16x16x32_bf16 v[54:57], v[178:181], v[146:149], v[54:57]
	v_mfma_f32_16x16x32_bf16 v[46:49], v[190:193], v[146:149], v[46:49]
	v_mfma_f32_16x16x32_bf16 v[38:41], v[178:181], v[154:157], v[38:41]
	v_mfma_f32_16x16x32_bf16 v[30:33], v[190:193], v[154:157], v[30:33]
	v_mfma_f32_16x16x32_bf16 v[22:25], v[178:181], v[162:165], v[22:25]
	v_mfma_f32_16x16x32_bf16 v[14:17], v[190:193], v[162:165], v[14:17]
	v_mfma_f32_16x16x32_bf16 v[6:9], v[178:181], v[170:173], v[6:9]
	v_mfma_f32_16x16x32_bf16 v[2:5], v[190:193], v[170:173], v[2:5]
	v_mfma_f32_16x16x32_bf16 v[54:57], v[182:185], v[150:153], v[54:57]
	v_mfma_f32_16x16x32_bf16 v[46:49], v[202:205], v[150:153], v[46:49]
	v_mfma_f32_16x16x32_bf16 v[38:41], v[182:185], v[158:161], v[38:41]
	v_mfma_f32_16x16x32_bf16 v[30:33], v[202:205], v[158:161], v[30:33]
	v_mfma_f32_16x16x32_bf16 v[22:25], v[182:185], v[166:169], v[22:25]
	v_mfma_f32_16x16x32_bf16 v[14:17], v[202:205], v[166:169], v[14:17]
	v_mfma_f32_16x16x32_bf16 v[6:9], v[182:185], v[174:177], v[6:9]
	v_mfma_f32_16x16x32_bf16 v[2:5], v[202:205], v[174:177], v[2:5]
	s_setprio 0
	s_barrier
	ds_read_b128 v[118:121], v200
	ds_read_b128 v[126:129], v200 offset:1024
	ds_read_b128 v[130:133], v200 offset:2048
	ds_read_b128 v[138:141], v200 offset:3072
	s_mov_b32 m0, s26
	s_add_i32 s33, s87, 0x40000
	ds_read_b128 v[146:149], v198 offset:32768
	ds_read_b128 v[150:153], v198 offset:33792
	ds_read_b128 v[154:157], v198 offset:34816
	ds_read_b128 v[158:161], v198 offset:35840
	ds_read_b128 v[162:165], v198 offset:36864
	ds_read_b128 v[166:169], v198 offset:37888
	ds_read_b128 v[170:173], v198 offset:38912
	ds_read_b128 v[174:177], v198 offset:39936
	buffer_load_dwordx4 v1, s[48:51], s33 offen lds
	s_add_i32 s33, s87, 0x60000
	s_mov_b32 m0, s27
	s_nop 0
	buffer_load_dwordx4 v1, s[48:51], s33 offen lds
	s_waitcnt lgkmcnt(8)
	s_barrier
	s_waitcnt lgkmcnt(0)
	s_setprio 1
	s_waitcnt lgkmcnt(7)
	v_mfma_f32_16x16x32_bf16 v[142:145], v[118:121], v[146:149], v[142:145]
	v_mfma_f32_16x16x32_bf16 v[134:137], v[130:133], v[146:149], v[134:137]
	s_waitcnt lgkmcnt(5)
	v_mfma_f32_16x16x32_bf16 v[122:125], v[118:121], v[154:157], v[122:125]
	v_mfma_f32_16x16x32_bf16 v[114:117], v[130:133], v[154:157], v[114:117]
	s_waitcnt lgkmcnt(3)
	v_mfma_f32_16x16x32_bf16 v[94:97], v[118:121], v[162:165], v[94:97]
	v_mfma_f32_16x16x32_bf16 v[90:93], v[130:133], v[162:165], v[90:93]
	s_waitcnt lgkmcnt(1)
	v_mfma_f32_16x16x32_bf16 v[82:85], v[118:121], v[170:173], v[82:85]
	v_mfma_f32_16x16x32_bf16 v[74:77], v[130:133], v[170:173], v[74:77]
	v_mfma_f32_16x16x32_bf16 v[142:145], v[126:129], v[150:153], v[142:145]
	v_mfma_f32_16x16x32_bf16 v[134:137], v[138:141], v[150:153], v[134:137]
	v_mfma_f32_16x16x32_bf16 v[122:125], v[126:129], v[158:161], v[122:125]
	v_mfma_f32_16x16x32_bf16 v[114:117], v[138:141], v[158:161], v[114:117]
	v_mfma_f32_16x16x32_bf16 v[94:97], v[126:129], v[166:169], v[94:97]
	v_mfma_f32_16x16x32_bf16 v[90:93], v[138:141], v[166:169], v[90:93]
	s_waitcnt lgkmcnt(0)
	v_mfma_f32_16x16x32_bf16 v[82:85], v[126:129], v[174:177], v[82:85]
	v_mfma_f32_16x16x32_bf16 v[74:77], v[138:141], v[174:177], v[74:77]
	s_setprio 0
	s_barrier
	s_mov_b32 m0, s34
	s_add_i32 s33, s86, 0x80
	ds_read_b128 v[178:181], v201
	ds_read_b128 v[182:185], v201 offset:1024
	ds_read_b128 v[190:193], v201 offset:2048
	ds_read_b128 v[202:205], v201 offset:3072
	buffer_load_dwordx4 v194, s[8:11], s33 offen lds
	s_add_i32 s33, s86, 0x20080
	s_mov_b32 m0, s35
	s_nop 0
	buffer_load_dwordx4 v194, s[8:11], s33 offen lds
	s_waitcnt vmcnt(10)
	s_barrier
	s_waitcnt lgkmcnt(0)
	s_setprio 1
	s_waitcnt lgkmcnt(3)
	v_mfma_f32_16x16x32_bf16 v[110:113], v[178:181], v[146:149], v[110:113]
	s_waitcnt lgkmcnt(1)
	v_mfma_f32_16x16x32_bf16 v[106:109], v[190:193], v[146:149], v[106:109]
	v_mfma_f32_16x16x32_bf16 v[102:105], v[178:181], v[154:157], v[102:105]
	v_mfma_f32_16x16x32_bf16 v[98:101], v[190:193], v[154:157], v[98:101]
	v_mfma_f32_16x16x32_bf16 v[86:89], v[178:181], v[162:165], v[86:89]
	v_mfma_f32_16x16x32_bf16 v[78:81], v[190:193], v[162:165], v[78:81]
	v_mfma_f32_16x16x32_bf16 v[70:73], v[178:181], v[170:173], v[70:73]
	v_mfma_f32_16x16x32_bf16 v[66:69], v[190:193], v[170:173], v[66:69]
	v_mfma_f32_16x16x32_bf16 v[110:113], v[182:185], v[150:153], v[110:113]
	s_waitcnt lgkmcnt(0)
	v_mfma_f32_16x16x32_bf16 v[106:109], v[202:205], v[150:153], v[106:109]
	v_mfma_f32_16x16x32_bf16 v[102:105], v[182:185], v[158:161], v[102:105]
	v_mfma_f32_16x16x32_bf16 v[98:101], v[202:205], v[158:161], v[98:101]
	v_mfma_f32_16x16x32_bf16 v[86:89], v[182:185], v[166:169], v[86:89]
	v_mfma_f32_16x16x32_bf16 v[78:81], v[202:205], v[166:169], v[78:81]
	v_mfma_f32_16x16x32_bf16 v[70:73], v[182:185], v[174:177], v[70:73]
	v_mfma_f32_16x16x32_bf16 v[66:69], v[202:205], v[174:177], v[66:69]
	s_setprio 0
	s_mov_b32 m0, s36
	s_barrier
	ds_read_b128 v[146:149], v198 offset:49152
	ds_read_b128 v[150:153], v198 offset:50176
	ds_read_b128 v[154:157], v198 offset:51200
	ds_read_b128 v[158:161], v198 offset:52224
	ds_read_b128 v[162:165], v198 offset:53248
	ds_read_b128 v[166:169], v198 offset:54272
	ds_read_b128 v[170:173], v198 offset:55296
	ds_read_b128 v[174:177], v198 offset:56320
	buffer_load_dwordx4 v1, s[48:51], s88 offen lds
	s_add_i32 s87, s87, 0x20080
	s_mov_b32 m0, s37
	s_nop 0
	buffer_load_dwordx4 v1, s[48:51], s87 offen lds
	s_barrier
	s_waitcnt lgkmcnt(0)
	s_setprio 1
	s_waitcnt lgkmcnt(7)
	v_mfma_f32_16x16x32_bf16 v[62:65], v[118:121], v[146:149], v[62:65]
	v_mfma_f32_16x16x32_bf16 v[58:61], v[130:133], v[146:149], v[58:61]
	s_waitcnt lgkmcnt(5)
	v_mfma_f32_16x16x32_bf16 v[50:53], v[118:121], v[154:157], v[50:53]
	v_mfma_f32_16x16x32_bf16 v[42:45], v[130:133], v[154:157], v[42:45]
	s_waitcnt lgkmcnt(3)
	v_mfma_f32_16x16x32_bf16 v[34:37], v[118:121], v[162:165], v[34:37]
	v_mfma_f32_16x16x32_bf16 v[26:29], v[130:133], v[162:165], v[26:29]
	s_waitcnt lgkmcnt(1)
	v_mfma_f32_16x16x32_bf16 v[18:21], v[118:121], v[170:173], v[18:21]
	v_mfma_f32_16x16x32_bf16 v[10:13], v[130:133], v[170:173], v[10:13]
	v_mfma_f32_16x16x32_bf16 v[62:65], v[126:129], v[150:153], v[62:65]
	v_mfma_f32_16x16x32_bf16 v[58:61], v[138:141], v[150:153], v[58:61]
	v_mfma_f32_16x16x32_bf16 v[50:53], v[126:129], v[158:161], v[50:53]
	v_mfma_f32_16x16x32_bf16 v[42:45], v[138:141], v[158:161], v[42:45]
	v_mfma_f32_16x16x32_bf16 v[34:37], v[126:129], v[166:169], v[34:37]
	v_mfma_f32_16x16x32_bf16 v[26:29], v[138:141], v[166:169], v[26:29]
	s_waitcnt lgkmcnt(0)
	v_mfma_f32_16x16x32_bf16 v[18:21], v[126:129], v[174:177], v[18:21]
	v_mfma_f32_16x16x32_bf16 v[10:13], v[138:141], v[174:177], v[10:13]
	s_setprio 0
	s_barrier
	s_mov_b32 m0, s38
	s_add_i32 s33, s86, 0x40080
	buffer_load_dwordx4 v194, s[8:11], s33 offen lds
	s_add_i32 s86, s86, 0x60080
	s_mov_b32 m0, s39
	s_nop 0
	buffer_load_dwordx4 v194, s[8:11], s86 offen lds
	s_waitcnt vmcnt(6)
	s_barrier
	s_setprio 1
	v_mfma_f32_16x16x32_bf16 v[54:57], v[178:181], v[146:149], v[54:57]
	v_mfma_f32_16x16x32_bf16 v[46:49], v[190:193], v[146:149], v[46:49]
	v_mfma_f32_16x16x32_bf16 v[38:41], v[178:181], v[154:157], v[38:41]
	v_mfma_f32_16x16x32_bf16 v[30:33], v[190:193], v[154:157], v[30:33]
	v_mfma_f32_16x16x32_bf16 v[22:25], v[178:181], v[162:165], v[22:25]
	v_mfma_f32_16x16x32_bf16 v[14:17], v[190:193], v[162:165], v[14:17]
	v_mfma_f32_16x16x32_bf16 v[6:9], v[178:181], v[170:173], v[6:9]
	v_mfma_f32_16x16x32_bf16 v[2:5], v[190:193], v[170:173], v[2:5]
	v_mfma_f32_16x16x32_bf16 v[54:57], v[182:185], v[150:153], v[54:57]
	v_mfma_f32_16x16x32_bf16 v[46:49], v[202:205], v[150:153], v[46:49]
	v_mfma_f32_16x16x32_bf16 v[38:41], v[182:185], v[158:161], v[38:41]
	v_mfma_f32_16x16x32_bf16 v[30:33], v[202:205], v[158:161], v[30:33]
	v_mfma_f32_16x16x32_bf16 v[22:25], v[182:185], v[166:169], v[22:25]
	v_mfma_f32_16x16x32_bf16 v[14:17], v[202:205], v[166:169], v[14:17]
	v_mfma_f32_16x16x32_bf16 v[6:9], v[182:185], v[174:177], v[6:9]
	v_mfma_f32_16x16x32_bf16 v[2:5], v[202:205], v[174:177], v[2:5]
	s_setprio 0
	s_add_i32 s17, s17, 2
	s_addk_i32 s7, 0x100
	s_addk_i32 s16, 0x100
	s_cmp_gt_u32 s17, 13
	s_barrier
	s_cbranch_scc0 .LBB0_450
	s_cmpk_gt_i32 s78, 0x7f
	s_cselect_b64 s[6:7], -1, 0
	s_and_b64 vcc, exec, s[6:7]
	s_cbranch_vccz .LBB0_443
	s_load_dwordx2 s[10:11], s[0:1], 0x10
	s_mov_b64 s[16:17], 0xc000
	s_branch .LBB0_444

.LBB0_774:
	s_and_b64 s[14:15], s[6:7], exec
	s_cselect_b32 s57, 0, s9
	s_add_i32 s14, s50, s9
	s_or_b32 s51, s57, 0x80
	s_waitcnt lgkmcnt(8)
	s_barrier
	s_waitcnt lgkmcnt(0)
	s_and_b64 s[6:7], s[6:7], exec
	s_cselect_b32 s6, s46, s14
	s_add_i32 s7, s6, 0x80
	s_setprio 1
	s_waitcnt lgkmcnt(6)
	v_mfma_f32_16x16x128_f8f6f4 v[174:177], v[2:9], v[42:49], v[174:177]
	v_mfma_f32_16x16x128_f8f6f4 v[166:169], v[10:17], v[42:49], v[166:169]
	s_waitcnt lgkmcnt(4)
	v_mfma_f32_16x16x128_f8f6f4 v[158:161], v[2:9], v[34:41], v[158:161]
	v_mfma_f32_16x16x128_f8f6f4 v[150:153], v[10:17], v[34:41], v[150:153]
	s_waitcnt lgkmcnt(2)
	v_mfma_f32_16x16x128_f8f6f4 v[142:145], v[2:9], v[26:33], v[142:145]
	v_mfma_f32_16x16x128_f8f6f4 v[134:137], v[10:17], v[26:33], v[134:137]
	s_waitcnt lgkmcnt(0)
	v_mfma_f32_16x16x128_f8f6f4 v[126:129], v[2:9], v[18:25], v[126:129]
	v_mfma_f32_16x16x128_f8f6f4 v[118:121], v[10:17], v[18:25], v[118:121]
	s_setprio 0
	s_barrier
	s_mov_b32 m0, s18
	v_add_u32_e32 v210, 0x14000, v189
	s_mov_b32 s14, s42
	s_mov_b32 s15, s43
	ds_read_b128 v[198:201], v210
	ds_read_b128 v[202:205], v210 offset:1024
	ds_read_b128 v[206:209], v210 offset:2048
	ds_read_b128 v[210:213], v210 offset:3072
	buffer_load_dwordx4 v184, s[12:15], s6 offen lds
	s_add_i32 s33, s6, 0x10000
	s_mov_b32 m0, s19
	s_nop 0
	buffer_load_dwordx4 v184, s[12:15], s33 offen lds
	s_barrier
	s_waitcnt lgkmcnt(0)
	s_setprio 1
	s_waitcnt lgkmcnt(2)
	v_mfma_f32_16x16x128_f8f6f4 v[170:173], v[198:205], v[42:49], v[170:173]
	s_waitcnt lgkmcnt(0)
	v_mfma_f32_16x16x128_f8f6f4 v[162:165], v[206:213], v[42:49], v[162:165]
	v_mfma_f32_16x16x128_f8f6f4 v[154:157], v[198:205], v[34:41], v[154:157]
	v_mfma_f32_16x16x128_f8f6f4 v[146:149], v[206:213], v[34:41], v[146:149]
	v_mfma_f32_16x16x128_f8f6f4 v[138:141], v[198:205], v[26:33], v[138:141]
	v_mfma_f32_16x16x128_f8f6f4 v[130:133], v[206:213], v[26:33], v[130:133]
	v_mfma_f32_16x16x128_f8f6f4 v[122:125], v[198:205], v[18:25], v[122:125]
	v_mfma_f32_16x16x128_f8f6f4 v[114:117], v[206:213], v[18:25], v[114:117]
	s_setprio 0
	v_lshlrev_b32_e32 v214, 10, v186
	v_and_b32_e32 v214, 0x3fffc00, v214
	v_lshlrev_b32_e32 v215, 10, v185
	s_mov_b32 m0, s17
	v_add_u32_e32 v214, v214, v1
	v_and_b32_e32 v215, 0x3fffc00, v215
	s_barrier
	ds_read_b128 v[18:21], v191 offset:16384
	ds_read_b128 v[22:25], v191 offset:17408
	ds_read_b128 v[26:29], v191 offset:18432
	ds_read_b128 v[30:33], v191 offset:19456
	ds_read_b128 v[34:37], v191 offset:20480
	ds_read_b128 v[38:41], v191 offset:21504
	ds_read_b128 v[42:45], v191 offset:22528
	ds_read_b128 v[46:49], v191 offset:23552
	buffer_load_dwordx4 v214, s[40:43], s57 offen lds
	v_add_u32_e32 v215, v215, v1
	s_mov_b32 m0, s20
	s_nop 0
	buffer_load_dwordx4 v215, s[40:43], s57 offen lds
	s_barrier
	s_waitcnt lgkmcnt(0)
	s_setprio 1
	s_waitcnt lgkmcnt(6)
	v_mfma_f32_16x16x128_f8f6f4 v[110:113], v[2:9], v[18:25], v[110:113]
	v_mfma_f32_16x16x128_f8f6f4 v[102:105], v[10:17], v[18:25], v[102:105]
	s_waitcnt lgkmcnt(4)
	v_mfma_f32_16x16x128_f8f6f4 v[94:97], v[2:9], v[26:33], v[94:97]
	v_mfma_f32_16x16x128_f8f6f4 v[86:89], v[10:17], v[26:33], v[86:89]
	s_waitcnt lgkmcnt(2)
	v_mfma_f32_16x16x128_f8f6f4 v[78:81], v[2:9], v[34:41], v[78:81]
	v_mfma_f32_16x16x128_f8f6f4 v[70:73], v[10:17], v[34:41], v[70:73]
	s_waitcnt lgkmcnt(0)
	v_mfma_f32_16x16x128_f8f6f4 v[62:65], v[2:9], v[42:49], v[62:65]
	v_mfma_f32_16x16x128_f8f6f4 v[54:57], v[10:17], v[42:49], v[54:57]
	s_setprio 0
	s_barrier
	s_mov_b32 m0, s21
	s_add_i32 s33, s6, 0x20000
	buffer_load_dwordx4 v184, s[12:15], s33 offen lds
	s_add_i32 s33, s6, 0x30000
	s_mov_b32 m0, s22
	s_nop 0
	buffer_load_dwordx4 v184, s[12:15], s33 offen lds
	s_waitcnt vmcnt(6)
	s_barrier
	s_setprio 1
	v_mfma_f32_16x16x128_f8f6f4 v[106:109], v[198:205], v[18:25], v[106:109]
	v_mfma_f32_16x16x128_f8f6f4 v[98:101], v[206:213], v[18:25], v[98:101]
	v_mfma_f32_16x16x128_f8f6f4 v[90:93], v[198:205], v[26:33], v[90:93]
	v_mfma_f32_16x16x128_f8f6f4 v[82:85], v[206:213], v[26:33], v[82:85]
	v_mfma_f32_16x16x128_f8f6f4 v[74:77], v[198:205], v[34:41], v[74:77]
	v_mfma_f32_16x16x128_f8f6f4 v[66:69], v[206:213], v[34:41], v[66:69]
	v_mfma_f32_16x16x128_f8f6f4 v[58:61], v[198:205], v[42:49], v[58:61]
	v_mfma_f32_16x16x128_f8f6f4 v[50:53], v[206:213], v[42:49], v[50:53]
	s_setprio 0
	v_add_u32_e32 v14, 0x18000, v189
	s_barrier
	ds_read_b128 v[2:5], v14
	ds_read_b128 v[6:9], v14 offset:1024
	ds_read_b128 v[10:13], v14 offset:2048
	ds_read_b128 v[14:17], v14 offset:3072
	s_mov_b32 m0, s23
	ds_read_b128 v[18:21], v191 offset:32768
	ds_read_b128 v[22:25], v191 offset:33792
	ds_read_b128 v[26:29], v191 offset:34816
	ds_read_b128 v[30:33], v191 offset:35840
	ds_read_b128 v[34:37], v191 offset:36864
	ds_read_b128 v[38:41], v191 offset:37888
	ds_read_b128 v[42:45], v191 offset:38912
	ds_read_b128 v[46:49], v191 offset:39936
	buffer_load_dwordx4 v196, s[40:43], s57 offen lds
	s_mov_b32 m0, s24
	s_nop 0
	buffer_load_dwordx4 v197, s[40:43], s57 offen lds
	s_waitcnt lgkmcnt(8)
	s_barrier
	s_waitcnt lgkmcnt(0)
	s_setprio 1
	s_waitcnt lgkmcnt(6)
	v_mfma_f32_16x16x128_f8f6f4 v[174:177], v[2:9], v[18:25], v[174:177]
	v_mfma_f32_16x16x128_f8f6f4 v[166:169], v[10:17], v[18:25], v[166:169]
	s_waitcnt lgkmcnt(4)
	v_mfma_f32_16x16x128_f8f6f4 v[158:161], v[2:9], v[26:33], v[158:161]
	v_mfma_f32_16x16x128_f8f6f4 v[150:153], v[10:17], v[26:33], v[150:153]
	s_waitcnt lgkmcnt(2)
	v_mfma_f32_16x16x128_f8f6f4 v[142:145], v[2:9], v[34:41], v[142:145]
	v_mfma_f32_16x16x128_f8f6f4 v[134:137], v[10:17], v[34:41], v[134:137]
	s_waitcnt lgkmcnt(0)
	v_mfma_f32_16x16x128_f8f6f4 v[126:129], v[2:9], v[42:49], v[126:129]
	v_mfma_f32_16x16x128_f8f6f4 v[118:121], v[10:17], v[42:49], v[118:121]
	s_setprio 0
	s_barrier
	s_mov_b32 m0, s26
	v_add_u32_e32 v208, 0x1c000, v189
	ds_read_b128 v[196:199], v208
	ds_read_b128 v[200:203], v208 offset:1024
	ds_read_b128 v[204:207], v208 offset:2048
	ds_read_b128 v[208:211], v208 offset:3072
	buffer_load_dwordx4 v184, s[12:15], s7 offen lds
	s_add_i32 s7, s6, 0x10080
	s_mov_b32 m0, s27
	s_nop 0
	buffer_load_dwordx4 v184, s[12:15], s7 offen lds
	s_waitcnt vmcnt(10)
	s_barrier
	s_waitcnt lgkmcnt(0)
	s_setprio 1
	s_waitcnt lgkmcnt(2)
	v_mfma_f32_16x16x128_f8f6f4 v[170:173], v[196:203], v[18:25], v[170:173]
	s_waitcnt lgkmcnt(0)
	v_mfma_f32_16x16x128_f8f6f4 v[162:165], v[204:211], v[18:25], v[162:165]
	v_mfma_f32_16x16x128_f8f6f4 v[154:157], v[196:203], v[26:33], v[154:157]
	v_mfma_f32_16x16x128_f8f6f4 v[146:149], v[204:211], v[26:33], v[146:149]
	v_mfma_f32_16x16x128_f8f6f4 v[138:141], v[196:203], v[34:41], v[138:141]
	v_mfma_f32_16x16x128_f8f6f4 v[130:133], v[204:211], v[34:41], v[130:133]
	v_mfma_f32_16x16x128_f8f6f4 v[122:125], v[196:203], v[42:49], v[122:125]
	v_mfma_f32_16x16x128_f8f6f4 v[114:117], v[204:211], v[42:49], v[114:117]
	s_setprio 0
	s_mov_b32 m0, s28
	s_barrier
	ds_read_b128 v[18:21], v191 offset:49152
	ds_read_b128 v[22:25], v191 offset:50176
	ds_read_b128 v[26:29], v191 offset:51200
	ds_read_b128 v[30:33], v191 offset:52224
	ds_read_b128 v[34:37], v191 offset:53248
	ds_read_b128 v[38:41], v191 offset:54272
	ds_read_b128 v[42:45], v191 offset:55296
	ds_read_b128 v[46:49], v191 offset:56320
	buffer_load_dwordx4 v214, s[40:43], s51 offen lds
	s_mov_b32 m0, s29
	s_nop 0
	buffer_load_dwordx4 v215, s[40:43], s51 offen lds
	s_barrier
	s_waitcnt lgkmcnt(0)
	s_setprio 1
	s_waitcnt lgkmcnt(6)
	v_mfma_f32_16x16x128_f8f6f4 v[110:113], v[2:9], v[18:25], v[110:113]
	v_mfma_f32_16x16x128_f8f6f4 v[102:105], v[10:17], v[18:25], v[102:105]
	s_waitcnt lgkmcnt(4)
	v_mfma_f32_16x16x128_f8f6f4 v[94:97], v[2:9], v[26:33], v[94:97]
	v_mfma_f32_16x16x128_f8f6f4 v[86:89], v[10:17], v[26:33], v[86:89]
	s_waitcnt lgkmcnt(2)
	v_mfma_f32_16x16x128_f8f6f4 v[78:81], v[2:9], v[34:41], v[78:81]
	v_mfma_f32_16x16x128_f8f6f4 v[70:73], v[10:17], v[34:41], v[70:73]
	s_waitcnt lgkmcnt(0)
	v_mfma_f32_16x16x128_f8f6f4 v[62:65], v[2:9], v[42:49], v[62:65]
	v_mfma_f32_16x16x128_f8f6f4 v[54:57], v[10:17], v[42:49], v[54:57]
	s_setprio 0
	s_barrier
	s_mov_b32 m0, s30
	s_add_i32 s7, s6, 0x20080
	buffer_load_dwordx4 v184, s[12:15], s7 offen lds
	s_add_i32 s6, s6, 0x30080
	s_mov_b32 m0, s31
	s_nop 0
	buffer_load_dwordx4 v184, s[12:15], s6 offen lds
	s_waitcnt vmcnt(6)
	s_barrier
	s_setprio 1
	v_mfma_f32_16x16x128_f8f6f4 v[106:109], v[196:203], v[18:25], v[106:109]
	v_mfma_f32_16x16x128_f8f6f4 v[98:101], v[204:211], v[18:25], v[98:101]
	v_mfma_f32_16x16x128_f8f6f4 v[90:93], v[196:203], v[26:33], v[90:93]
	v_mfma_f32_16x16x128_f8f6f4 v[82:85], v[204:211], v[26:33], v[82:85]
	v_mfma_f32_16x16x128_f8f6f4 v[74:77], v[196:203], v[34:41], v[74:77]
	v_mfma_f32_16x16x128_f8f6f4 v[66:69], v[204:211], v[34:41], v[66:69]
	v_mfma_f32_16x16x128_f8f6f4 v[58:61], v[196:203], v[42:49], v[58:61]
	v_mfma_f32_16x16x128_f8f6f4 v[50:53], v[204:211], v[42:49], v[50:53]
	s_setprio 0
	s_add_i32 s8, s8, 2
	s_addk_i32 s9, 0x100
	s_cmp_gt_u32 s8, 5
	s_barrier
	s_cbranch_scc1 .LBB0_766

.LBB0_840:
	ds_read_b128 v[142:145], v137
	ds_read_b128 v[146:149], v137 offset:1024
	ds_read_b128 v[150:153], v137 offset:2048
	ds_read_b128 v[154:157], v137 offset:3072
	s_add_i32 s10, s7, 0xfffd0800
	s_cmp_eq_u32 s79, 4
	s_cselect_b32 s87, s6, s10
	s_cselect_b32 s86, s58, s78
	s_or_b32 s88, s87, 0x800
	s_add_i32 s10, s7, 0xffff0000
	s_mov_b32 m0, s39
	ds_read_b128 v[158:161], v138
	ds_read_b128 v[162:165], v138 offset:1024
	ds_read_b128 v[166:169], v138 offset:2048
	ds_read_b128 v[170:173], v138 offset:3072
	ds_read_b128 v[174:177], v138 offset:4096
	ds_read_b128 v[178:181], v138 offset:5120
	ds_read_b128 v[182:185], v138 offset:6144
	ds_read_b128 v[186:189], v138 offset:7168
	buffer_load_dwordx4 v1, s[44:47], s10 offen lds
	s_mov_b32 m0, s41
	s_nop 0
	buffer_load_dwordx4 v1, s[44:47], s7 offen lds
	s_waitcnt lgkmcnt(8)
	s_barrier
	s_waitcnt lgkmcnt(0)
	s_setprio 1
	s_waitcnt lgkmcnt(4)
	v_mfma_f32_16x16x128_f8f6f4 v[114:117], v[142:149], v[166:173], v[114:117]
	v_mfma_f32_16x16x128_f8f6f4 v[106:109], v[150:157], v[166:173], v[106:109]
	s_waitcnt lgkmcnt(2)
	v_mfma_f32_16x16x128_f8f6f4 v[98:101], v[142:149], v[174:181], v[98:101]
	v_mfma_f32_16x16x128_f8f6f4 v[198:201], v[142:149], v[158:165], v[126:129]
	v_mfma_f32_16x16x128_f8f6f4 v[202:205], v[150:157], v[158:165], v[122:125]
	v_mfma_f32_16x16x128_f8f6f4 v[206:209], v[150:157], v[174:181], v[90:93]
	s_waitcnt lgkmcnt(0)
	v_mfma_f32_16x16x128_f8f6f4 v[210:213], v[142:149], v[182:189], v[82:85]
	v_mfma_f32_16x16x128_f8f6f4 v[214:217], v[150:157], v[182:189], v[74:77]
	s_setprio 0
	s_barrier
	s_mov_b32 m0, s23
	s_mov_b32 s10, s46
	s_mov_b32 s11, s47
	ds_read_b128 v[122:125], v139
	ds_read_b128 v[126:129], v139 offset:1024
	ds_read_b128 v[190:193], v139 offset:2048
	ds_read_b128 v[194:197], v139 offset:3072
	buffer_load_dwordx4 v134, s[8:11], s86 offen lds
	s_add_i32 s33, s86, 0x20000
	s_mov_b32 m0, s24
	s_nop 0
	buffer_load_dwordx4 v134, s[8:11], s33 offen lds
	s_barrier
	s_waitcnt lgkmcnt(0)
	s_setprio 1
	s_waitcnt lgkmcnt(2)
	v_mfma_f32_16x16x128_f8f6f4 v[118:121], v[122:129], v[158:165], v[118:121]
	s_waitcnt lgkmcnt(0)
	v_mfma_f32_16x16x128_f8f6f4 v[110:113], v[190:197], v[158:165], v[110:113]
	v_mfma_f32_16x16x128_f8f6f4 v[102:105], v[122:129], v[166:173], v[102:105]
	v_mfma_f32_16x16x128_f8f6f4 v[158:161], v[190:197], v[166:173], v[94:97]
	v_mfma_f32_16x16x128_f8f6f4 v[162:165], v[122:129], v[174:181], v[86:89]
	v_mfma_f32_16x16x128_f8f6f4 v[166:169], v[190:197], v[174:181], v[78:81]
	v_mfma_f32_16x16x128_f8f6f4 v[170:173], v[122:129], v[182:189], v[70:73]
	v_mfma_f32_16x16x128_f8f6f4 v[174:177], v[190:197], v[182:189], v[18:21]
	s_setprio 0
	s_mov_b32 m0, s22
	s_barrier
	ds_read_b128 v[66:69], v138 offset:16384
	s_nop 1
	ds_read_b128 v[70:73], v138 offset:17408
	ds_read_b128 v[74:77], v138 offset:18432
	ds_read_b128 v[78:81], v138 offset:19456
	ds_read_b128 v[82:85], v138 offset:20480
	ds_read_b128 v[86:89], v138 offset:21504
	ds_read_b128 v[90:93], v138 offset:22528
	ds_read_b128 v[94:97], v138 offset:23552
	buffer_load_dwordx4 v1, s[44:47], s87 offen lds
	s_add_i32 s33, s87, 0x10000
	s_mov_b32 m0, s25
	s_nop 0
	buffer_load_dwordx4 v1, s[44:47], s33 offen lds
	s_barrier
	s_waitcnt lgkmcnt(0)
	s_setprio 1
	s_waitcnt lgkmcnt(6)
	v_mfma_f32_16x16x128_f8f6f4 v[62:65], v[142:149], v[66:73], v[62:65]
	v_mfma_f32_16x16x128_f8f6f4 v[58:61], v[150:157], v[66:73], v[58:61]
	s_waitcnt lgkmcnt(4)
	v_mfma_f32_16x16x128_f8f6f4 v[50:53], v[142:149], v[74:81], v[50:53]
	s_waitcnt lgkmcnt(0)
	v_mfma_f32_16x16x128_f8f6f4 v[230:233], v[142:149], v[90:97], v[230:233]
	v_mfma_f32_16x16x128_f8f6f4 v[218:221], v[150:157], v[74:81], v[42:45]
	v_mfma_f32_16x16x128_f8f6f4 v[222:225], v[142:149], v[82:89], v[34:37]
	v_mfma_f32_16x16x128_f8f6f4 v[226:229], v[150:157], v[82:89], v[26:29]
	v_mfma_f32_16x16x128_f8f6f4 v[234:237], v[150:157], v[90:97], v[10:13]
	s_setprio 0
	s_barrier
	s_mov_b32 m0, s26
	s_add_i32 s33, s86, 0x2000
	buffer_load_dwordx4 v134, s[8:11], s33 offen lds
	s_add_i32 s33, s86, 0x22000
	s_mov_b32 m0, s27
	s_nop 0
	buffer_load_dwordx4 v134, s[8:11], s33 offen lds
	s_waitcnt vmcnt(6)
	s_barrier
	s_setprio 1
	v_mfma_f32_16x16x128_f8f6f4 v[54:57], v[122:129], v[66:73], v[54:57]
	v_mfma_f32_16x16x128_f8f6f4 v[238:241], v[190:197], v[66:73], v[46:49]
	v_mfma_f32_16x16x128_f8f6f4 v[242:245], v[122:129], v[74:81], v[38:41]
	v_mfma_f32_16x16x128_f8f6f4 v[246:249], v[190:197], v[74:81], v[30:33]
	v_mfma_f32_16x16x128_f8f6f4 v[250:253], v[122:129], v[82:89], v[22:25]
	v_mfma_f32_16x16x128_f8f6f4 v[130:133], v[190:197], v[82:89], v[14:17]
	v_mfma_f32_16x16x128_f8f6f4 v[66:69], v[122:129], v[90:97], v[6:9]
	v_mfma_f32_16x16x128_f8f6f4 v[190:193], v[190:197], v[90:97], v[2:5]
	s_setprio 0
	s_barrier
	s_nop 4
	ds_read_b128 v[2:5], v140
	ds_read_b128 v[6:9], v140 offset:1024
	ds_read_b128 v[10:13], v140 offset:2048
	ds_read_b128 v[14:17], v140 offset:3072
	s_mov_b32 m0, s28
	s_add_i32 s33, s87, 0x20000
	ds_read_b128 v[18:21], v138 offset:32768
	ds_read_b128 v[22:25], v138 offset:33792
	ds_read_b128 v[26:29], v138 offset:34816
	ds_read_b128 v[30:33], v138 offset:35840
	ds_read_b128 v[34:37], v138 offset:36864
	ds_read_b128 v[38:41], v138 offset:37888
	ds_read_b128 v[42:45], v138 offset:38912
	ds_read_b128 v[46:49], v138 offset:39936
	buffer_load_dwordx4 v1, s[44:47], s33 offen lds
	s_add_i32 s33, s87, 0x30000
	s_mov_b32 m0, s29
	s_nop 0
	buffer_load_dwordx4 v1, s[44:47], s33 offen lds
	s_waitcnt lgkmcnt(8)
	s_barrier
	s_waitcnt lgkmcnt(0)
	s_setprio 1
	s_waitcnt lgkmcnt(6)
	v_mfma_f32_16x16x128_f8f6f4 v[126:129], v[2:9], v[18:25], v[198:201]
	v_mfma_f32_16x16x128_f8f6f4 v[122:125], v[10:17], v[18:25], v[202:205]
	s_waitcnt lgkmcnt(4)
	v_mfma_f32_16x16x128_f8f6f4 v[114:117], v[2:9], v[26:33], v[114:117]
	v_mfma_f32_16x16x128_f8f6f4 v[106:109], v[10:17], v[26:33], v[106:109]
	s_waitcnt lgkmcnt(2)
	v_mfma_f32_16x16x128_f8f6f4 v[98:101], v[2:9], v[34:41], v[98:101]
	v_mfma_f32_16x16x128_f8f6f4 v[90:93], v[10:17], v[34:41], v[206:209]
	s_waitcnt lgkmcnt(0)
	v_mfma_f32_16x16x128_f8f6f4 v[82:85], v[2:9], v[42:49], v[210:213]
	v_mfma_f32_16x16x128_f8f6f4 v[74:77], v[10:17], v[42:49], v[214:217]
	s_setprio 0
	s_barrier
	s_mov_b32 m0, s31
	s_add_i32 s33, s86, 0x80
	ds_read_b128 v[142:145], v141
	ds_read_b128 v[146:149], v141 offset:1024
	ds_read_b128 v[150:153], v141 offset:2048
	ds_read_b128 v[154:157], v141 offset:3072
	buffer_load_dwordx4 v134, s[8:11], s33 offen lds
	s_add_i32 s33, s86, 0x20080
	s_mov_b32 m0, s34
	s_nop 0
	buffer_load_dwordx4 v134, s[8:11], s33 offen lds
	s_waitcnt vmcnt(10)
	s_barrier
	s_waitcnt lgkmcnt(0)
	s_setprio 1
	s_waitcnt lgkmcnt(2)
	v_mfma_f32_16x16x128_f8f6f4 v[118:121], v[142:149], v[18:25], v[118:121]
	s_waitcnt lgkmcnt(0)
	v_mfma_f32_16x16x128_f8f6f4 v[110:113], v[150:157], v[18:25], v[110:113]
	v_mfma_f32_16x16x128_f8f6f4 v[102:105], v[142:149], v[26:33], v[102:105]
	v_mfma_f32_16x16x128_f8f6f4 v[94:97], v[150:157], v[26:33], v[158:161]
	v_mfma_f32_16x16x128_f8f6f4 v[86:89], v[142:149], v[34:41], v[162:165]
	v_mfma_f32_16x16x128_f8f6f4 v[78:81], v[150:157], v[34:41], v[166:169]
	v_mfma_f32_16x16x128_f8f6f4 v[70:73], v[142:149], v[42:49], v[170:173]
	v_mfma_f32_16x16x128_f8f6f4 v[18:21], v[150:157], v[42:49], v[174:177]
	s_setprio 0
	s_mov_b32 m0, s35
	s_barrier
	ds_read_b128 v[158:161], v138 offset:49152
	ds_read_b128 v[162:165], v138 offset:50176
	ds_read_b128 v[166:169], v138 offset:51200
	ds_read_b128 v[170:173], v138 offset:52224
	ds_read_b128 v[174:177], v138 offset:53248
	ds_read_b128 v[178:181], v138 offset:54272
	ds_read_b128 v[182:185], v138 offset:55296
	ds_read_b128 v[186:189], v138 offset:56320
	buffer_load_dwordx4 v1, s[44:47], s88 offen lds
	s_add_i32 s87, s87, 0x10800
	s_mov_b32 m0, s36
	s_nop 0
	buffer_load_dwordx4 v1, s[44:47], s87 offen lds
	s_barrier
	s_waitcnt lgkmcnt(0)
	s_setprio 1
	s_waitcnt lgkmcnt(6)
	v_mfma_f32_16x16x128_f8f6f4 v[62:65], v[2:9], v[158:165], v[62:65]
	v_mfma_f32_16x16x128_f8f6f4 v[58:61], v[10:17], v[158:165], v[58:61]
	s_waitcnt lgkmcnt(4)
	v_mfma_f32_16x16x128_f8f6f4 v[50:53], v[2:9], v[166:173], v[50:53]
	v_mfma_f32_16x16x128_f8f6f4 v[42:45], v[10:17], v[166:173], v[218:221]
	s_waitcnt lgkmcnt(2)
	v_mfma_f32_16x16x128_f8f6f4 v[34:37], v[2:9], v[174:181], v[222:225]
	v_mfma_f32_16x16x128_f8f6f4 v[26:29], v[10:17], v[174:181], v[226:229]
	s_waitcnt lgkmcnt(0)
	v_mfma_f32_16x16x128_f8f6f4 v[230:233], v[2:9], v[182:189], v[230:233]
	v_mfma_f32_16x16x128_f8f6f4 v[10:13], v[10:17], v[182:189], v[234:237]
	s_setprio 0
	s_barrier
	s_mov_b32 m0, s37
	s_add_i32 s33, s86, 0x2080
	buffer_load_dwordx4 v134, s[8:11], s33 offen lds
	s_add_i32 s86, s86, 0x22080
	s_mov_b32 m0, s38
	s_nop 0
	buffer_load_dwordx4 v134, s[8:11], s86 offen lds
	s_waitcnt vmcnt(6)
	s_barrier
	s_setprio 1
	v_mfma_f32_16x16x128_f8f6f4 v[54:57], v[142:149], v[158:165], v[54:57]
	v_mfma_f32_16x16x128_f8f6f4 v[46:49], v[150:157], v[158:165], v[238:241]
	v_mfma_f32_16x16x128_f8f6f4 v[38:41], v[142:149], v[166:173], v[242:245]
	v_mfma_f32_16x16x128_f8f6f4 v[30:33], v[150:157], v[166:173], v[246:249]
	v_mfma_f32_16x16x128_f8f6f4 v[22:25], v[142:149], v[174:181], v[250:253]
	v_mfma_f32_16x16x128_f8f6f4 v[14:17], v[150:157], v[174:181], v[130:133]
	v_mfma_f32_16x16x128_f8f6f4 v[6:9], v[142:149], v[182:189], v[66:69]
	v_mfma_f32_16x16x128_f8f6f4 v[2:5], v[150:157], v[182:189], v[190:193]
	s_setprio 0
	s_add_i32 s79, s79, 2
	s_addk_i32 s7, 0x1000
	s_addk_i32 s78, 0x100
	s_cmp_gt_u32 s79, 5
	s_barrier
	s_cbranch_scc0 .LBB0_840
	v_lshl_add_u32 v152, s73, 8, v135
	v_lshlrev_b32_e32 v153, 1, v136
	v_lshl_or_b32 v153, s72, 8, v153
	v_lshl_add_u32 v152, v152, 10, v153
	s_mov_b32 s72, s51
	s_mov_b32 s73, s57
	s_mov_b32 s78, s58
	s_mov_b32 s79, s59
	v_pk_mul_f32 v[126:127], v[126:127], 0.5 op_sel_hi:[1,0]
	v_pk_mul_f32 v[128:129], v[128:129], 0.5 op_sel_hi:[1,0]
	v_pk_mul_f32 v[122:123], v[122:123], 0.5 op_sel_hi:[1,0]
	v_pk_mul_f32 v[124:125], v[124:125], 0.5 op_sel_hi:[1,0]
	v_pk_mul_f32 v[118:119], v[118:119], 0.5 op_sel_hi:[1,0]
	v_pk_mul_f32 v[120:121], v[120:121], 0.5 op_sel_hi:[1,0]
	v_pk_mul_f32 v[110:111], v[110:111], 0.5 op_sel_hi:[1,0]
	v_pk_mul_f32 v[112:113], v[112:113], 0.5 op_sel_hi:[1,0]
	v_cvt_pk_fp8_f32 v144, v126, v127
	v_cvt_pk_fp8_f32 v145, v122, v123
	v_cvt_pk_fp8_f32 v146, v118, v119
	v_cvt_pk_fp8_f32 v147, v110, v111
	v_cvt_pk_fp8_f32 v144, v128, v129 op_sel:[0,0,1]
	v_cvt_pk_fp8_f32 v145, v124, v125 op_sel:[0,0,1]
	v_cvt_pk_fp8_f32 v146, v120, v121 op_sel:[0,0,1]
	v_cvt_pk_fp8_f32 v147, v112, v113 op_sel:[0,0,1]
	v_mov_b32_e32 v154, v152
	s_nop 0
	global_store_dwordx4 v154, v[144:147], s[68:69]
	s_mov_b32 s100, 1
	v_pk_mul_f32 v[114:115], v[114:115], 0.5 op_sel_hi:[1,0]
	v_pk_mul_f32 v[116:117], v[116:117], 0.5 op_sel_hi:[1,0]
	v_pk_mul_f32 v[106:107], v[106:107], 0.5 op_sel_hi:[1,0]
	v_pk_mul_f32 v[108:109], v[108:109], 0.5 op_sel_hi:[1,0]
	v_pk_mul_f32 v[102:103], v[102:103], 0.5 op_sel_hi:[1,0]
	v_pk_mul_f32 v[104:105], v[104:105], 0.5 op_sel_hi:[1,0]
	v_pk_mul_f32 v[94:95], v[94:95], 0.5 op_sel_hi:[1,0]
	v_pk_mul_f32 v[96:97], v[96:97], 0.5 op_sel_hi:[1,0]
	v_cvt_pk_fp8_f32 v148, v114, v115
	v_cvt_pk_fp8_f32 v149, v106, v107
	v_cvt_pk_fp8_f32 v150, v102, v103
	v_cvt_pk_fp8_f32 v151, v94, v95
	v_cvt_pk_fp8_f32 v148, v116, v117 op_sel:[0,0,1]
	v_cvt_pk_fp8_f32 v149, v108, v109 op_sel:[0,0,1]
	v_cvt_pk_fp8_f32 v150, v104, v105 op_sel:[0,0,1]
	v_cvt_pk_fp8_f32 v151, v96, v97 op_sel:[0,0,1]
	v_add_u32_e32 v155, 0x4000, v152
	s_nop 0
	global_store_dwordx4 v155, v[148:151], s[68:69]
	s_mov_b32 s100, 1
	v_pk_mul_f32 v[98:99], v[98:99], 0.5 op_sel_hi:[1,0]
	v_pk_mul_f32 v[100:101], v[100:101], 0.5 op_sel_hi:[1,0]
	v_pk_mul_f32 v[90:91], v[90:91], 0.5 op_sel_hi:[1,0]
	v_pk_mul_f32 v[92:93], v[92:93], 0.5 op_sel_hi:[1,0]
	v_pk_mul_f32 v[86:87], v[86:87], 0.5 op_sel_hi:[1,0]
	v_pk_mul_f32 v[88:89], v[88:89], 0.5 op_sel_hi:[1,0]
	v_pk_mul_f32 v[78:79], v[78:79], 0.5 op_sel_hi:[1,0]
	v_pk_mul_f32 v[80:81], v[80:81], 0.5 op_sel_hi:[1,0]
	v_cvt_pk_fp8_f32 v144, v98, v99
	v_cvt_pk_fp8_f32 v145, v90, v91
	v_cvt_pk_fp8_f32 v146, v86, v87
	v_cvt_pk_fp8_f32 v147, v78, v79
	v_cvt_pk_fp8_f32 v144, v100, v101 op_sel:[0,0,1]
	v_cvt_pk_fp8_f32 v145, v92, v93 op_sel:[0,0,1]
	v_cvt_pk_fp8_f32 v146, v88, v89 op_sel:[0,0,1]
	v_cvt_pk_fp8_f32 v147, v80, v81 op_sel:[0,0,1]
	v_add_u32_e32 v154, 0x8000, v152
	s_nop 0
	global_store_dwordx4 v154, v[144:147], s[68:69]
	s_mov_b32 s100, 1
	v_pk_mul_f32 v[82:83], v[82:83], 0.5 op_sel_hi:[1,0]
	v_pk_mul_f32 v[84:85], v[84:85], 0.5 op_sel_hi:[1,0]
	v_pk_mul_f32 v[74:75], v[74:75], 0.5 op_sel_hi:[1,0]
	v_pk_mul_f32 v[76:77], v[76:77], 0.5 op_sel_hi:[1,0]
	v_pk_mul_f32 v[70:71], v[70:71], 0.5 op_sel_hi:[1,0]
	v_pk_mul_f32 v[72:73], v[72:73], 0.5 op_sel_hi:[1,0]
	v_pk_mul_f32 v[18:19], v[18:19], 0.5 op_sel_hi:[1,0]
	v_pk_mul_f32 v[20:21], v[20:21], 0.5 op_sel_hi:[1,0]
	v_cvt_pk_fp8_f32 v148, v82, v83
	v_cvt_pk_fp8_f32 v149, v74, v75
	v_cvt_pk_fp8_f32 v150, v70, v71
	v_cvt_pk_fp8_f32 v151, v18, v19
	v_cvt_pk_fp8_f32 v148, v84, v85 op_sel:[0,0,1]
	v_cvt_pk_fp8_f32 v149, v76, v77 op_sel:[0,0,1]
	v_cvt_pk_fp8_f32 v150, v72, v73 op_sel:[0,0,1]
	v_cvt_pk_fp8_f32 v151, v20, v21 op_sel:[0,0,1]
	v_add_u32_e32 v155, 0xc000, v152
	s_nop 0
	global_store_dwordx4 v155, v[148:151], s[68:69]
	s_mov_b32 s100, 1
	v_pk_mul_f32 v[62:63], v[62:63], 0.5 op_sel_hi:[1,0]
	v_pk_mul_f32 v[64:65], v[64:65], 0.5 op_sel_hi:[1,0]
	v_pk_mul_f32 v[58:59], v[58:59], 0.5 op_sel_hi:[1,0]
	v_pk_mul_f32 v[60:61], v[60:61], 0.5 op_sel_hi:[1,0]
	v_pk_mul_f32 v[54:55], v[54:55], 0.5 op_sel_hi:[1,0]
	v_pk_mul_f32 v[56:57], v[56:57], 0.5 op_sel_hi:[1,0]
	v_pk_mul_f32 v[46:47], v[46:47], 0.5 op_sel_hi:[1,0]
	v_pk_mul_f32 v[48:49], v[48:49], 0.5 op_sel_hi:[1,0]
	v_cvt_pk_fp8_f32 v144, v62, v63
	v_cvt_pk_fp8_f32 v145, v58, v59
	v_cvt_pk_fp8_f32 v146, v54, v55
	v_cvt_pk_fp8_f32 v147, v46, v47
	v_cvt_pk_fp8_f32 v144, v64, v65 op_sel:[0,0,1]
	v_cvt_pk_fp8_f32 v145, v60, v61 op_sel:[0,0,1]
	v_cvt_pk_fp8_f32 v146, v56, v57 op_sel:[0,0,1]
	v_cvt_pk_fp8_f32 v147, v48, v49 op_sel:[0,0,1]
	v_add_u32_e32 v154, 0x20000, v152
	s_nop 0
	global_store_dwordx4 v154, v[144:147], s[68:69]
	s_mov_b32 s100, 1
	v_pk_mul_f32 v[50:51], v[50:51], 0.5 op_sel_hi:[1,0]
	v_pk_mul_f32 v[52:53], v[52:53], 0.5 op_sel_hi:[1,0]
	v_pk_mul_f32 v[42:43], v[42:43], 0.5 op_sel_hi:[1,0]
	v_pk_mul_f32 v[44:45], v[44:45], 0.5 op_sel_hi:[1,0]
	v_pk_mul_f32 v[38:39], v[38:39], 0.5 op_sel_hi:[1,0]
	v_pk_mul_f32 v[40:41], v[40:41], 0.5 op_sel_hi:[1,0]
	v_pk_mul_f32 v[30:31], v[30:31], 0.5 op_sel_hi:[1,0]
	v_pk_mul_f32 v[32:33], v[32:33], 0.5 op_sel_hi:[1,0]
	v_cvt_pk_fp8_f32 v148, v50, v51
	v_cvt_pk_fp8_f32 v149, v42, v43
	v_cvt_pk_fp8_f32 v150, v38, v39
	v_cvt_pk_fp8_f32 v151, v30, v31
	v_cvt_pk_fp8_f32 v148, v52, v53 op_sel:[0,0,1]
	v_cvt_pk_fp8_f32 v149, v44, v45 op_sel:[0,0,1]
	v_cvt_pk_fp8_f32 v150, v40, v41 op_sel:[0,0,1]
	v_cvt_pk_fp8_f32 v151, v32, v33 op_sel:[0,0,1]
	v_add_u32_e32 v155, 0x24000, v152
	s_nop 0
	global_store_dwordx4 v155, v[148:151], s[68:69]
	s_mov_b32 s100, 1
	v_pk_mul_f32 v[34:35], v[34:35], 0.5 op_sel_hi:[1,0]
	v_pk_mul_f32 v[36:37], v[36:37], 0.5 op_sel_hi:[1,0]
	v_pk_mul_f32 v[26:27], v[26:27], 0.5 op_sel_hi:[1,0]
	v_pk_mul_f32 v[28:29], v[28:29], 0.5 op_sel_hi:[1,0]
	v_pk_mul_f32 v[22:23], v[22:23], 0.5 op_sel_hi:[1,0]
	v_pk_mul_f32 v[24:25], v[24:25], 0.5 op_sel_hi:[1,0]
	v_pk_mul_f32 v[14:15], v[14:15], 0.5 op_sel_hi:[1,0]
	v_pk_mul_f32 v[16:17], v[16:17], 0.5 op_sel_hi:[1,0]
	v_cvt_pk_fp8_f32 v144, v34, v35
	v_cvt_pk_fp8_f32 v145, v26, v27
	v_cvt_pk_fp8_f32 v146, v22, v23
	v_cvt_pk_fp8_f32 v147, v14, v15
	v_cvt_pk_fp8_f32 v144, v36, v37 op_sel:[0,0,1]
	v_cvt_pk_fp8_f32 v145, v28, v29 op_sel:[0,0,1]
	v_cvt_pk_fp8_f32 v146, v24, v25 op_sel:[0,0,1]
	v_cvt_pk_fp8_f32 v147, v16, v17 op_sel:[0,0,1]
	v_add_u32_e32 v154, 0x28000, v152
	s_nop 0
	global_store_dwordx4 v154, v[144:147], s[68:69]
	s_mov_b32 s100, 1
	v_pk_mul_f32 v[230:231], v[230:231], 0.5 op_sel_hi:[1,0]
	v_pk_mul_f32 v[232:233], v[232:233], 0.5 op_sel_hi:[1,0]
	v_pk_mul_f32 v[10:11], v[10:11], 0.5 op_sel_hi:[1,0]
	v_pk_mul_f32 v[12:13], v[12:13], 0.5 op_sel_hi:[1,0]
	v_pk_mul_f32 v[6:7], v[6:7], 0.5 op_sel_hi:[1,0]
	v_pk_mul_f32 v[8:9], v[8:9], 0.5 op_sel_hi:[1,0]
	v_pk_mul_f32 v[2:3], v[2:3], 0.5 op_sel_hi:[1,0]
	v_pk_mul_f32 v[4:5], v[4:5], 0.5 op_sel_hi:[1,0]
	v_cvt_pk_fp8_f32 v148, v230, v231
	v_cvt_pk_fp8_f32 v149, v10, v11
	v_cvt_pk_fp8_f32 v150, v6, v7
	v_cvt_pk_fp8_f32 v151, v2, v3
	v_cvt_pk_fp8_f32 v148, v232, v233 op_sel:[0,0,1]
	v_cvt_pk_fp8_f32 v149, v12, v13 op_sel:[0,0,1]
	v_cvt_pk_fp8_f32 v150, v8, v9 op_sel:[0,0,1]
	v_cvt_pk_fp8_f32 v151, v4, v5 op_sel:[0,0,1]
	v_add_u32_e32 v155, 0x2c000, v152
	s_nop 0
	global_store_dwordx4 v155, v[148:151], s[68:69]
	s_mov_b32 s100, 1
	s_and_b64 vcc, exec, s[4:5]
	s_cbranch_vccz .LBB0_835
	s_waitcnt vmcnt(0)
	s_cmpk_gt_u32 s3, 0xff
	s_cbranch_scc1 .LBB0_844
	s_barrier

.LBB0_1020:
	ds_read_b128 v[134:137], v141
	ds_read_b128 v[146:149], v141 offset:1024
	ds_read_b128 v[150:153], v141 offset:2048
	ds_read_b128 v[154:157], v141 offset:3072
	s_add_i32 s10, s7, 0xfffa0080
	s_cmp_eq_u32 s47, 12
	s_cselect_b32 s50, s6, s10
	s_cselect_b32 s49, s37, s46
	s_or_b32 s51, s50, 0x80
	s_add_i32 s10, s7, 0xfffe0000
	s_mov_b32 m0, s29
	ds_read_b128 v[158:161], v142
	ds_read_b128 v[162:165], v142 offset:1024
	ds_read_b128 v[166:169], v142 offset:2048
	ds_read_b128 v[170:173], v142 offset:3072
	ds_read_b128 v[174:177], v142 offset:4096
	ds_read_b128 v[178:181], v142 offset:5120
	ds_read_b128 v[182:185], v142 offset:6144
	ds_read_b128 v[186:189], v142 offset:7168
	buffer_load_dwordx4 v1, s[40:43], s10 offen lds
	s_mov_b32 m0, s30
	s_nop 0
	buffer_load_dwordx4 v1, s[40:43], s7 offen lds
	s_waitcnt lgkmcnt(8)
	s_barrier
	s_waitcnt lgkmcnt(0)
	s_setprio 1
	s_waitcnt lgkmcnt(7)
	v_mfma_f32_16x16x32_bf16 v[126:129], v[134:137], v[158:161], v[126:129]
	v_mfma_f32_16x16x32_bf16 v[122:125], v[150:153], v[158:161], v[122:125]
	s_waitcnt lgkmcnt(5)
	v_mfma_f32_16x16x32_bf16 v[118:121], v[134:137], v[166:169], v[118:121]
	v_mfma_f32_16x16x32_bf16 v[110:113], v[150:153], v[166:169], v[110:113]
	s_waitcnt lgkmcnt(3)
	v_mfma_f32_16x16x32_bf16 v[102:105], v[134:137], v[174:177], v[102:105]
	v_mfma_f32_16x16x32_bf16 v[94:97], v[150:153], v[174:177], v[94:97]
	s_waitcnt lgkmcnt(1)
	v_mfma_f32_16x16x32_bf16 v[86:89], v[134:137], v[182:185], v[86:89]
	v_mfma_f32_16x16x32_bf16 v[78:81], v[150:153], v[182:185], v[78:81]
	v_mfma_f32_16x16x32_bf16 v[126:129], v[146:149], v[162:165], v[126:129]
	v_mfma_f32_16x16x32_bf16 v[122:125], v[154:157], v[162:165], v[122:125]
	v_mfma_f32_16x16x32_bf16 v[118:121], v[146:149], v[170:173], v[118:121]
	v_mfma_f32_16x16x32_bf16 v[110:113], v[154:157], v[170:173], v[110:113]
	v_mfma_f32_16x16x32_bf16 v[102:105], v[146:149], v[178:181], v[102:105]
	v_mfma_f32_16x16x32_bf16 v[94:97], v[154:157], v[178:181], v[94:97]
	s_waitcnt lgkmcnt(0)
	v_mfma_f32_16x16x32_bf16 v[86:89], v[146:149], v[186:189], v[86:89]
	v_mfma_f32_16x16x32_bf16 v[78:81], v[154:157], v[186:189], v[78:81]
	s_setprio 0
	s_barrier
	s_mov_b32 m0, s15
	s_mov_b32 s10, s42
	s_mov_b32 s11, s43
	ds_read_b128 v[190:193], v143
	ds_read_b128 v[194:197], v143 offset:1024
	ds_read_b128 v[198:201], v143 offset:2048
	ds_read_b128 v[202:205], v143 offset:3072
	buffer_load_dwordx4 v138, s[8:11], s49 offen lds
	s_add_i32 s33, s49, 0x20000
	s_mov_b32 m0, s16
	s_nop 0
	buffer_load_dwordx4 v138, s[8:11], s33 offen lds
	s_barrier
	s_waitcnt lgkmcnt(0)
	s_setprio 1
	s_waitcnt lgkmcnt(3)
	v_mfma_f32_16x16x32_bf16 v[114:117], v[190:193], v[158:161], v[114:117]
	s_waitcnt lgkmcnt(1)
	v_mfma_f32_16x16x32_bf16 v[106:109], v[198:201], v[158:161], v[106:109]
	v_mfma_f32_16x16x32_bf16 v[98:101], v[190:193], v[166:169], v[98:101]
	v_mfma_f32_16x16x32_bf16 v[90:93], v[198:201], v[166:169], v[90:93]
	v_mfma_f32_16x16x32_bf16 v[82:85], v[190:193], v[174:177], v[82:85]
	v_mfma_f32_16x16x32_bf16 v[74:77], v[198:201], v[174:177], v[74:77]
	v_mfma_f32_16x16x32_bf16 v[70:73], v[190:193], v[182:185], v[70:73]
	v_mfma_f32_16x16x32_bf16 v[66:69], v[198:201], v[182:185], v[66:69]
	v_mfma_f32_16x16x32_bf16 v[114:117], v[194:197], v[162:165], v[114:117]
	s_waitcnt lgkmcnt(0)
	v_mfma_f32_16x16x32_bf16 v[106:109], v[202:205], v[162:165], v[106:109]
	v_mfma_f32_16x16x32_bf16 v[98:101], v[194:197], v[170:173], v[98:101]
	v_mfma_f32_16x16x32_bf16 v[90:93], v[202:205], v[170:173], v[90:93]
	v_mfma_f32_16x16x32_bf16 v[82:85], v[194:197], v[178:181], v[82:85]
	v_mfma_f32_16x16x32_bf16 v[74:77], v[202:205], v[178:181], v[74:77]
	v_mfma_f32_16x16x32_bf16 v[70:73], v[194:197], v[186:189], v[70:73]
	v_mfma_f32_16x16x32_bf16 v[66:69], v[202:205], v[186:189], v[66:69]
	s_setprio 0
	s_mov_b32 m0, s14
	s_barrier
	ds_read_b128 v[158:161], v142 offset:16384
	ds_read_b128 v[162:165], v142 offset:17408
	ds_read_b128 v[166:169], v142 offset:18432
	ds_read_b128 v[170:173], v142 offset:19456
	ds_read_b128 v[174:177], v142 offset:20480
	ds_read_b128 v[178:181], v142 offset:21504
	ds_read_b128 v[182:185], v142 offset:22528
	ds_read_b128 v[186:189], v142 offset:23552
	buffer_load_dwordx4 v1, s[40:43], s50 offen lds
	s_add_i32 s33, s50, 0x20000
	s_mov_b32 m0, s17
	s_nop 0
	buffer_load_dwordx4 v1, s[40:43], s33 offen lds
	s_barrier
	s_waitcnt lgkmcnt(0)
	s_setprio 1
	s_waitcnt lgkmcnt(7)
	v_mfma_f32_16x16x32_bf16 v[62:65], v[134:137], v[158:161], v[62:65]
	v_mfma_f32_16x16x32_bf16 v[58:61], v[150:153], v[158:161], v[58:61]
	s_waitcnt lgkmcnt(5)
	v_mfma_f32_16x16x32_bf16 v[54:57], v[134:137], v[166:169], v[54:57]
	v_mfma_f32_16x16x32_bf16 v[46:49], v[150:153], v[166:169], v[46:49]
	s_waitcnt lgkmcnt(3)
	v_mfma_f32_16x16x32_bf16 v[38:41], v[134:137], v[174:177], v[38:41]
	v_mfma_f32_16x16x32_bf16 v[30:33], v[150:153], v[174:177], v[30:33]
	s_waitcnt lgkmcnt(1)
	v_mfma_f32_16x16x32_bf16 v[22:25], v[134:137], v[182:185], v[22:25]
	v_mfma_f32_16x16x32_bf16 v[14:17], v[150:153], v[182:185], v[14:17]
	v_mfma_f32_16x16x32_bf16 v[62:65], v[146:149], v[162:165], v[62:65]
	v_mfma_f32_16x16x32_bf16 v[58:61], v[154:157], v[162:165], v[58:61]
	v_mfma_f32_16x16x32_bf16 v[54:57], v[146:149], v[170:173], v[54:57]
	v_mfma_f32_16x16x32_bf16 v[46:49], v[154:157], v[170:173], v[46:49]
	v_mfma_f32_16x16x32_bf16 v[38:41], v[146:149], v[178:181], v[38:41]
	v_mfma_f32_16x16x32_bf16 v[30:33], v[154:157], v[178:181], v[30:33]
	s_waitcnt lgkmcnt(0)
	v_mfma_f32_16x16x32_bf16 v[22:25], v[146:149], v[186:189], v[22:25]
	v_mfma_f32_16x16x32_bf16 v[14:17], v[154:157], v[186:189], v[14:17]
	s_setprio 0
	s_barrier
	s_mov_b32 m0, s18
	s_add_i32 s33, s49, 0x40000
	buffer_load_dwordx4 v138, s[8:11], s33 offen lds
	s_add_i32 s33, s49, 0x60000
	s_mov_b32 m0, s19
	s_nop 0
	buffer_load_dwordx4 v138, s[8:11], s33 offen lds
	s_waitcnt vmcnt(6)
	s_barrier
	s_setprio 1
	v_mfma_f32_16x16x32_bf16 v[50:53], v[190:193], v[158:161], v[50:53]
	v_mfma_f32_16x16x32_bf16 v[42:45], v[198:201], v[158:161], v[42:45]
	v_mfma_f32_16x16x32_bf16 v[34:37], v[190:193], v[166:169], v[34:37]
	v_mfma_f32_16x16x32_bf16 v[26:29], v[198:201], v[166:169], v[26:29]
	v_mfma_f32_16x16x32_bf16 v[18:21], v[190:193], v[174:177], v[18:21]
	v_mfma_f32_16x16x32_bf16 v[10:13], v[198:201], v[174:177], v[10:13]
	v_mfma_f32_16x16x32_bf16 v[6:9], v[190:193], v[182:185], v[6:9]
	v_mfma_f32_16x16x32_bf16 v[2:5], v[198:201], v[182:185], v[2:5]
	v_mfma_f32_16x16x32_bf16 v[50:53], v[194:197], v[162:165], v[50:53]
	v_mfma_f32_16x16x32_bf16 v[42:45], v[202:205], v[162:165], v[42:45]
	v_mfma_f32_16x16x32_bf16 v[34:37], v[194:197], v[170:173], v[34:37]
	v_mfma_f32_16x16x32_bf16 v[26:29], v[202:205], v[170:173], v[26:29]
	v_mfma_f32_16x16x32_bf16 v[18:21], v[194:197], v[178:181], v[18:21]
	v_mfma_f32_16x16x32_bf16 v[10:13], v[202:205], v[178:181], v[10:13]
	v_mfma_f32_16x16x32_bf16 v[6:9], v[194:197], v[186:189], v[6:9]
	v_mfma_f32_16x16x32_bf16 v[2:5], v[202:205], v[186:189], v[2:5]
	s_setprio 0
	s_barrier
	ds_read_b128 v[134:137], v144
	ds_read_b128 v[146:149], v144 offset:1024
	ds_read_b128 v[150:153], v144 offset:2048
	ds_read_b128 v[154:157], v144 offset:3072
	s_mov_b32 m0, s20
	s_add_i32 s33, s50, 0x40000
	ds_read_b128 v[158:161], v142 offset:32768
	ds_read_b128 v[162:165], v142 offset:33792
	ds_read_b128 v[166:169], v142 offset:34816
	ds_read_b128 v[170:173], v142 offset:35840
	ds_read_b128 v[174:177], v142 offset:36864
	ds_read_b128 v[178:181], v142 offset:37888
	ds_read_b128 v[182:185], v142 offset:38912
	ds_read_b128 v[186:189], v142 offset:39936
	buffer_load_dwordx4 v1, s[40:43], s33 offen lds
	s_add_i32 s33, s50, 0x60000
	s_mov_b32 m0, s21
	s_nop 0
	buffer_load_dwordx4 v1, s[40:43], s33 offen lds
	s_waitcnt lgkmcnt(8)
	s_barrier
	s_waitcnt lgkmcnt(0)
	s_setprio 1
	s_waitcnt lgkmcnt(7)
	v_mfma_f32_16x16x32_bf16 v[126:129], v[134:137], v[158:161], v[126:129]
	v_mfma_f32_16x16x32_bf16 v[122:125], v[150:153], v[158:161], v[122:125]
	s_waitcnt lgkmcnt(5)
	v_mfma_f32_16x16x32_bf16 v[118:121], v[134:137], v[166:169], v[118:121]
	v_mfma_f32_16x16x32_bf16 v[110:113], v[150:153], v[166:169], v[110:113]
	s_waitcnt lgkmcnt(3)
	v_mfma_f32_16x16x32_bf16 v[102:105], v[134:137], v[174:177], v[102:105]
	v_mfma_f32_16x16x32_bf16 v[94:97], v[150:153], v[174:177], v[94:97]
	s_waitcnt lgkmcnt(1)
	v_mfma_f32_16x16x32_bf16 v[86:89], v[134:137], v[182:185], v[86:89]
	v_mfma_f32_16x16x32_bf16 v[78:81], v[150:153], v[182:185], v[78:81]
	v_mfma_f32_16x16x32_bf16 v[126:129], v[146:149], v[162:165], v[126:129]
	v_mfma_f32_16x16x32_bf16 v[122:125], v[154:157], v[162:165], v[122:125]
	v_mfma_f32_16x16x32_bf16 v[118:121], v[146:149], v[170:173], v[118:121]
	v_mfma_f32_16x16x32_bf16 v[110:113], v[154:157], v[170:173], v[110:113]
	v_mfma_f32_16x16x32_bf16 v[102:105], v[146:149], v[178:181], v[102:105]
	v_mfma_f32_16x16x32_bf16 v[94:97], v[154:157], v[178:181], v[94:97]
	s_waitcnt lgkmcnt(0)
	v_mfma_f32_16x16x32_bf16 v[86:89], v[146:149], v[186:189], v[86:89]
	v_mfma_f32_16x16x32_bf16 v[78:81], v[154:157], v[186:189], v[78:81]
	s_setprio 0
	s_barrier
	s_mov_b32 m0, s23
	s_or_b32 s33, s49, 0x80
	ds_read_b128 v[190:193], v145
	ds_read_b128 v[194:197], v145 offset:1024
	ds_read_b128 v[198:201], v145 offset:2048
	ds_read_b128 v[202:205], v145 offset:3072
	buffer_load_dwordx4 v138, s[8:11], s33 offen lds
	s_add_i32 s33, s49, 0x20080
	s_mov_b32 m0, s24
	s_nop 0
	buffer_load_dwordx4 v138, s[8:11], s33 offen lds
	s_waitcnt vmcnt(10)
	s_barrier
	s_waitcnt lgkmcnt(0)
	s_setprio 1
	s_waitcnt lgkmcnt(3)
	v_mfma_f32_16x16x32_bf16 v[114:117], v[190:193], v[158:161], v[114:117]
	s_waitcnt lgkmcnt(1)
	v_mfma_f32_16x16x32_bf16 v[106:109], v[198:201], v[158:161], v[106:109]
	v_mfma_f32_16x16x32_bf16 v[98:101], v[190:193], v[166:169], v[98:101]
	v_mfma_f32_16x16x32_bf16 v[90:93], v[198:201], v[166:169], v[90:93]
	v_mfma_f32_16x16x32_bf16 v[82:85], v[190:193], v[174:177], v[82:85]
	v_mfma_f32_16x16x32_bf16 v[74:77], v[198:201], v[174:177], v[74:77]
	v_mfma_f32_16x16x32_bf16 v[70:73], v[190:193], v[182:185], v[70:73]
	v_mfma_f32_16x16x32_bf16 v[66:69], v[198:201], v[182:185], v[66:69]
	v_mfma_f32_16x16x32_bf16 v[114:117], v[194:197], v[162:165], v[114:117]
	s_waitcnt lgkmcnt(0)
	v_mfma_f32_16x16x32_bf16 v[106:109], v[202:205], v[162:165], v[106:109]
	v_mfma_f32_16x16x32_bf16 v[98:101], v[194:197], v[170:173], v[98:101]
	v_mfma_f32_16x16x32_bf16 v[90:93], v[202:205], v[170:173], v[90:93]
	v_mfma_f32_16x16x32_bf16 v[82:85], v[194:197], v[178:181], v[82:85]
	v_mfma_f32_16x16x32_bf16 v[74:77], v[202:205], v[178:181], v[74:77]
	v_mfma_f32_16x16x32_bf16 v[70:73], v[194:197], v[186:189], v[70:73]
	v_mfma_f32_16x16x32_bf16 v[66:69], v[202:205], v[186:189], v[66:69]
	s_setprio 0
	s_mov_b32 m0, s25
	s_barrier
	ds_read_b128 v[158:161], v142 offset:49152
	ds_read_b128 v[162:165], v142 offset:50176
	ds_read_b128 v[166:169], v142 offset:51200
	ds_read_b128 v[170:173], v142 offset:52224
	ds_read_b128 v[174:177], v142 offset:53248
	ds_read_b128 v[178:181], v142 offset:54272
	ds_read_b128 v[182:185], v142 offset:55296
	ds_read_b128 v[186:189], v142 offset:56320
	buffer_load_dwordx4 v1, s[40:43], s51 offen lds
	s_add_i32 s50, s50, 0x20080
	s_mov_b32 m0, s26
	s_nop 0
	buffer_load_dwordx4 v1, s[40:43], s50 offen lds
	s_barrier
	s_waitcnt lgkmcnt(0)
	s_setprio 1
	s_waitcnt lgkmcnt(7)
	v_mfma_f32_16x16x32_bf16 v[62:65], v[134:137], v[158:161], v[62:65]
	v_mfma_f32_16x16x32_bf16 v[58:61], v[150:153], v[158:161], v[58:61]
	s_waitcnt lgkmcnt(5)
	v_mfma_f32_16x16x32_bf16 v[54:57], v[134:137], v[166:169], v[54:57]
	v_mfma_f32_16x16x32_bf16 v[46:49], v[150:153], v[166:169], v[46:49]
	s_waitcnt lgkmcnt(3)
	v_mfma_f32_16x16x32_bf16 v[38:41], v[134:137], v[174:177], v[38:41]
	v_mfma_f32_16x16x32_bf16 v[30:33], v[150:153], v[174:177], v[30:33]
	s_waitcnt lgkmcnt(1)
	v_mfma_f32_16x16x32_bf16 v[22:25], v[134:137], v[182:185], v[22:25]
	v_mfma_f32_16x16x32_bf16 v[14:17], v[150:153], v[182:185], v[14:17]
	v_mfma_f32_16x16x32_bf16 v[62:65], v[146:149], v[162:165], v[62:65]
	v_mfma_f32_16x16x32_bf16 v[58:61], v[154:157], v[162:165], v[58:61]
	v_mfma_f32_16x16x32_bf16 v[54:57], v[146:149], v[170:173], v[54:57]
	v_mfma_f32_16x16x32_bf16 v[46:49], v[154:157], v[170:173], v[46:49]
	v_mfma_f32_16x16x32_bf16 v[38:41], v[146:149], v[178:181], v[38:41]
	v_mfma_f32_16x16x32_bf16 v[30:33], v[154:157], v[178:181], v[30:33]
	s_waitcnt lgkmcnt(0)
	v_mfma_f32_16x16x32_bf16 v[22:25], v[146:149], v[186:189], v[22:25]
	v_mfma_f32_16x16x32_bf16 v[14:17], v[154:157], v[186:189], v[14:17]
	s_setprio 0
	s_barrier
	s_mov_b32 m0, s27
	s_add_i32 s33, s49, 0x40080
	buffer_load_dwordx4 v138, s[8:11], s33 offen lds
	s_add_i32 s49, s49, 0x60080
	s_mov_b32 m0, s28
	s_nop 0
	buffer_load_dwordx4 v138, s[8:11], s49 offen lds
	s_waitcnt vmcnt(6)
	s_barrier
	s_setprio 1
	v_mfma_f32_16x16x32_bf16 v[50:53], v[190:193], v[158:161], v[50:53]
	v_mfma_f32_16x16x32_bf16 v[42:45], v[198:201], v[158:161], v[42:45]
	v_mfma_f32_16x16x32_bf16 v[34:37], v[190:193], v[166:169], v[34:37]
	v_mfma_f32_16x16x32_bf16 v[26:29], v[198:201], v[166:169], v[26:29]
	v_mfma_f32_16x16x32_bf16 v[18:21], v[190:193], v[174:177], v[18:21]
	v_mfma_f32_16x16x32_bf16 v[10:13], v[198:201], v[174:177], v[10:13]
	v_mfma_f32_16x16x32_bf16 v[6:9], v[190:193], v[182:185], v[6:9]
	v_mfma_f32_16x16x32_bf16 v[2:5], v[198:201], v[182:185], v[2:5]
	v_mfma_f32_16x16x32_bf16 v[50:53], v[194:197], v[162:165], v[50:53]
	v_mfma_f32_16x16x32_bf16 v[42:45], v[202:205], v[162:165], v[42:45]
	v_mfma_f32_16x16x32_bf16 v[34:37], v[194:197], v[170:173], v[34:37]
	v_mfma_f32_16x16x32_bf16 v[26:29], v[202:205], v[170:173], v[26:29]
	v_mfma_f32_16x16x32_bf16 v[18:21], v[194:197], v[178:181], v[18:21]
	v_mfma_f32_16x16x32_bf16 v[10:13], v[202:205], v[178:181], v[10:13]
	v_mfma_f32_16x16x32_bf16 v[6:9], v[194:197], v[186:189], v[6:9]
	v_mfma_f32_16x16x32_bf16 v[2:5], v[202:205], v[186:189], v[2:5]
	s_setprio 0
	s_add_i32 s47, s47, 2
	s_addk_i32 s7, 0x100
	s_addk_i32 s46, 0x100
	s_cmp_gt_u32 s47, 13
	s_barrier
	s_cbranch_scc0 .LBB0_1020
	v_lshl_or_b32 v136, s39, 8, v140
	v_lshl_add_u32 v148, s45, 8, v139
	v_ashrrev_i32_e32 v137, 31, v136
	v_mov_b64_e32 v[134:135], s[82:83]
	v_mad_i64_i32 v[146:147], s[6:7], v148, s34, v[134:135]
	v_lshlrev_b64 v[136:137], 1, v[136:137]
	v_lshl_add_u64 v[146:147], v[146:147], 0, v[136:137]
	v_cvt_pk_bf16_f32 v126, v126, v127
	v_cvt_pk_bf16_f32 v127, v128, v129
	v_cvt_pk_bf16_f32 v128, v122, v123
	v_cvt_pk_bf16_f32 v129, v124, v125
	global_store_dwordx4 v[146:147], v[126:129], off
	s_mov_b32 s100, 1
	v_cvt_pk_bf16_f32 v114, v114, v115
	v_cvt_pk_bf16_f32 v115, v116, v117
	v_cvt_pk_bf16_f32 v116, v106, v107
	v_or_b32_e32 v106, 16, v148
	v_mad_i64_i32 v[106:107], s[6:7], v106, s34, v[134:135]
	v_cvt_pk_bf16_f32 v117, v108, v109
	global_store_dwordx4 v[146:147], v[114:117], off offset:256
	s_mov_b32 s100, 1
	s_and_b64 vcc, exec, s[4:5]
	s_mov_b32 s39, s35
	v_lshl_add_u64 v[114:115], v[106:107], 0, v[136:137]
	v_cvt_pk_bf16_f32 v106, v118, v119
	v_cvt_pk_bf16_f32 v107, v120, v121
	v_cvt_pk_bf16_f32 v108, v110, v111
	v_cvt_pk_bf16_f32 v109, v112, v113
	global_store_dwordx4 v[114:115], v[106:109], off
	s_mov_b32 s100, 1
	v_cvt_pk_bf16_f32 v98, v98, v99
	v_cvt_pk_bf16_f32 v99, v100, v101
	v_cvt_pk_bf16_f32 v100, v90, v91
	v_or_b32_e32 v90, 32, v148
	v_mad_i64_i32 v[90:91], s[6:7], v90, s34, v[134:135]
	v_cvt_pk_bf16_f32 v101, v92, v93
	global_store_dwordx4 v[114:115], v[98:101], off offset:256
	s_mov_b32 s100, 1
	s_mov_b32 s45, s36
	s_mov_b32 s46, s37
	v_lshl_add_u64 v[98:99], v[90:91], 0, v[136:137]
	v_cvt_pk_bf16_f32 v90, v102, v103
	v_cvt_pk_bf16_f32 v91, v104, v105
	v_cvt_pk_bf16_f32 v92, v94, v95
	v_cvt_pk_bf16_f32 v93, v96, v97
	global_store_dwordx4 v[98:99], v[90:93], off
	s_mov_b32 s100, 1
	v_cvt_pk_bf16_f32 v82, v82, v83
	v_cvt_pk_bf16_f32 v83, v84, v85
	v_cvt_pk_bf16_f32 v84, v74, v75
	v_or_b32_e32 v74, 48, v148
	v_mad_i64_i32 v[74:75], s[6:7], v74, s34, v[134:135]
	v_cvt_pk_bf16_f32 v85, v76, v77
	global_store_dwordx4 v[98:99], v[82:85], off offset:256
	s_mov_b32 s100, 1
	s_mov_b32 s47, s38
	s_nop 0
	v_lshl_add_u64 v[82:83], v[74:75], 0, v[136:137]
	v_cvt_pk_bf16_f32 v74, v86, v87
	v_cvt_pk_bf16_f32 v75, v88, v89
	v_cvt_pk_bf16_f32 v76, v78, v79
	v_cvt_pk_bf16_f32 v77, v80, v81
	global_store_dwordx4 v[82:83], v[74:77], off
	s_mov_b32 s100, 1
	v_cvt_pk_bf16_f32 v70, v70, v71
	v_cvt_pk_bf16_f32 v71, v72, v73
	v_cvt_pk_bf16_f32 v72, v66, v67
	v_add_u32_e32 v66, 0x80, v148
	v_mad_i64_i32 v[66:67], s[6:7], v66, s34, v[134:135]
	v_lshl_add_u64 v[66:67], v[66:67], 0, v[136:137]
	v_cvt_pk_bf16_f32 v73, v68, v69
	global_store_dwordx4 v[82:83], v[70:73], off offset:256
	s_mov_b32 s100, 1
	v_cvt_pk_bf16_f32 v62, v62, v63
	v_cvt_pk_bf16_f32 v63, v64, v65
	v_cvt_pk_bf16_f32 v64, v58, v59
	v_cvt_pk_bf16_f32 v65, v60, v61
	global_store_dwordx4 v[66:67], v[62:65], off
	s_mov_b32 s100, 1
	v_cvt_pk_bf16_f32 v50, v50, v51
	v_cvt_pk_bf16_f32 v51, v52, v53
	v_cvt_pk_bf16_f32 v52, v42, v43
	v_add_u32_e32 v42, 0x90, v148
	v_mad_i64_i32 v[42:43], s[6:7], v42, s34, v[134:135]
	v_cvt_pk_bf16_f32 v53, v44, v45
	global_store_dwordx4 v[66:67], v[50:53], off offset:256
	s_mov_b32 s100, 1
	s_nop 1
	v_lshl_add_u64 v[50:51], v[42:43], 0, v[136:137]
	v_cvt_pk_bf16_f32 v42, v54, v55
	v_cvt_pk_bf16_f32 v43, v56, v57
	v_cvt_pk_bf16_f32 v44, v46, v47
	v_cvt_pk_bf16_f32 v45, v48, v49
	global_store_dwordx4 v[50:51], v[42:45], off
	s_mov_b32 s100, 1
	v_cvt_pk_bf16_f32 v34, v34, v35
	v_cvt_pk_bf16_f32 v35, v36, v37
	v_cvt_pk_bf16_f32 v36, v26, v27
	v_add_u32_e32 v26, 0xa0, v148
	v_mad_i64_i32 v[26:27], s[6:7], v26, s34, v[134:135]
	v_cvt_pk_bf16_f32 v37, v28, v29
	global_store_dwordx4 v[50:51], v[34:37], off offset:256
	s_mov_b32 s100, 1
	s_nop 1
	v_lshl_add_u64 v[34:35], v[26:27], 0, v[136:137]
	v_cvt_pk_bf16_f32 v26, v38, v39
	v_cvt_pk_bf16_f32 v27, v40, v41
	v_cvt_pk_bf16_f32 v28, v30, v31
	v_cvt_pk_bf16_f32 v29, v32, v33
	global_store_dwordx4 v[34:35], v[26:29], off
	s_mov_b32 s100, 1
	v_cvt_pk_bf16_f32 v18, v18, v19
	v_cvt_pk_bf16_f32 v19, v20, v21
	v_cvt_pk_bf16_f32 v20, v10, v11
	v_add_u32_e32 v10, 0xb0, v148
	v_mad_i64_i32 v[10:11], s[6:7], v10, s34, v[134:135]
	v_cvt_pk_bf16_f32 v21, v12, v13
	global_store_dwordx4 v[34:35], v[18:21], off offset:256
	s_mov_b32 s100, 1
	s_nop 1
	v_lshl_add_u64 v[18:19], v[10:11], 0, v[136:137]
	v_cvt_pk_bf16_f32 v10, v22, v23
	v_cvt_pk_bf16_f32 v11, v24, v25
	v_cvt_pk_bf16_f32 v12, v14, v15
	v_cvt_pk_bf16_f32 v13, v16, v17
	global_store_dwordx4 v[18:19], v[10:13], off
	s_mov_b32 s100, 1
	v_cvt_pk_bf16_f32 v6, v6, v7
	v_cvt_pk_bf16_f32 v7, v8, v9
	v_cvt_pk_bf16_f32 v8, v2, v3
	v_cvt_pk_bf16_f32 v9, v4, v5
	global_store_dwordx4 v[18:19], v[6:9], off offset:256
	s_mov_b32 s100, 1
	s_cbranch_vccz .LBB0_1015
	s_waitcnt vmcnt(0)
	s_cmpk_gt_u32 s3, 0xff
	s_cbranch_scc1 .LBB0_1024
	s_barrier

.LBB0_1334:
	ds_read_b128 v[130:133], v195
	ds_read_b128 v[134:137], v195 offset:1024
	ds_read_b128 v[138:141], v195 offset:2048
	ds_read_b128 v[142:145], v195 offset:3072
	s_add_i32 s10, s7, 0xfffa0080
	s_cmp_eq_u32 s13, 12
	s_cselect_b32 s79, s6, s10
	s_cselect_b32 s78, s58, s12
	s_or_b32 s84, s79, 0x80
	s_add_i32 s10, s7, 0xfffe0000
	s_mov_b32 m0, s39
	ds_read_b128 v[146:149], v196
	ds_read_b128 v[150:153], v196 offset:1024
	ds_read_b128 v[154:157], v196 offset:2048
	ds_read_b128 v[158:161], v196 offset:3072
	ds_read_b128 v[162:165], v196 offset:4096
	ds_read_b128 v[166:169], v196 offset:5120
	ds_read_b128 v[170:173], v196 offset:6144
	ds_read_b128 v[174:177], v196 offset:7168
	buffer_load_dwordx4 v1, s[48:51], s10 offen lds
	s_mov_b32 m0, s41
	s_nop 0
	buffer_load_dwordx4 v1, s[48:51], s7 offen lds
	s_waitcnt lgkmcnt(8)
	s_barrier
	s_waitcnt lgkmcnt(0)
	s_setprio 1
	s_waitcnt lgkmcnt(7)
	v_mfma_f32_16x16x32_bf16 v[126:129], v[130:133], v[146:149], v[126:129]
	v_mfma_f32_16x16x32_bf16 v[122:125], v[138:141], v[146:149], v[122:125]
	s_waitcnt lgkmcnt(5)
	v_mfma_f32_16x16x32_bf16 v[110:113], v[130:133], v[154:157], v[110:113]
	v_mfma_f32_16x16x32_bf16 v[106:109], v[138:141], v[154:157], v[106:109]
	s_waitcnt lgkmcnt(3)
	v_mfma_f32_16x16x32_bf16 v[94:97], v[130:133], v[162:165], v[94:97]
	v_mfma_f32_16x16x32_bf16 v[90:93], v[138:141], v[162:165], v[90:93]
	s_waitcnt lgkmcnt(1)
	v_mfma_f32_16x16x32_bf16 v[78:81], v[130:133], v[170:173], v[78:81]
	v_mfma_f32_16x16x32_bf16 v[74:77], v[138:141], v[170:173], v[74:77]
	v_mfma_f32_16x16x32_bf16 v[126:129], v[134:137], v[150:153], v[126:129]
	v_mfma_f32_16x16x32_bf16 v[122:125], v[142:145], v[150:153], v[122:125]
	v_mfma_f32_16x16x32_bf16 v[110:113], v[134:137], v[158:161], v[110:113]
	v_mfma_f32_16x16x32_bf16 v[106:109], v[142:145], v[158:161], v[106:109]
	v_mfma_f32_16x16x32_bf16 v[94:97], v[134:137], v[166:169], v[94:97]
	v_mfma_f32_16x16x32_bf16 v[90:93], v[142:145], v[166:169], v[90:93]
	s_waitcnt lgkmcnt(0)
	v_mfma_f32_16x16x32_bf16 v[78:81], v[134:137], v[174:177], v[78:81]
	v_mfma_f32_16x16x32_bf16 v[74:77], v[142:145], v[174:177], v[74:77]
	s_setprio 0
	s_barrier
	s_mov_b32 m0, s17
	s_mov_b32 s10, s50
	s_mov_b32 s11, s51
	ds_read_b128 v[178:181], v197
	ds_read_b128 v[182:185], v197 offset:1024
	ds_read_b128 v[200:203], v197 offset:2048
	ds_read_b128 v[204:207], v197 offset:3072
	buffer_load_dwordx4 v192, s[8:11], s78 offen lds
	s_add_i32 s33, s78, 0x20000
	s_mov_b32 m0, s18
	s_nop 0
	buffer_load_dwordx4 v192, s[8:11], s33 offen lds
	s_barrier
	s_waitcnt lgkmcnt(0)
	s_setprio 1
	s_waitcnt lgkmcnt(3)
	v_mfma_f32_16x16x32_bf16 v[118:121], v[178:181], v[146:149], v[118:121]
	s_waitcnt lgkmcnt(1)
	v_mfma_f32_16x16x32_bf16 v[114:117], v[200:203], v[146:149], v[114:117]
	v_mfma_f32_16x16x32_bf16 v[102:105], v[178:181], v[154:157], v[102:105]
	v_mfma_f32_16x16x32_bf16 v[98:101], v[200:203], v[154:157], v[98:101]
	v_mfma_f32_16x16x32_bf16 v[86:89], v[178:181], v[162:165], v[86:89]
	v_mfma_f32_16x16x32_bf16 v[82:85], v[200:203], v[162:165], v[82:85]
	v_mfma_f32_16x16x32_bf16 v[70:73], v[178:181], v[170:173], v[70:73]
	v_mfma_f32_16x16x32_bf16 v[66:69], v[200:203], v[170:173], v[66:69]
	v_mfma_f32_16x16x32_bf16 v[118:121], v[182:185], v[150:153], v[118:121]
	s_waitcnt lgkmcnt(0)
	v_mfma_f32_16x16x32_bf16 v[114:117], v[204:207], v[150:153], v[114:117]
	v_mfma_f32_16x16x32_bf16 v[102:105], v[182:185], v[158:161], v[102:105]
	v_mfma_f32_16x16x32_bf16 v[98:101], v[204:207], v[158:161], v[98:101]
	v_mfma_f32_16x16x32_bf16 v[86:89], v[182:185], v[166:169], v[86:89]
	v_mfma_f32_16x16x32_bf16 v[82:85], v[204:207], v[166:169], v[82:85]
	v_mfma_f32_16x16x32_bf16 v[70:73], v[182:185], v[174:177], v[70:73]
	v_mfma_f32_16x16x32_bf16 v[66:69], v[204:207], v[174:177], v[66:69]
	s_setprio 0
	s_mov_b32 m0, s16
	s_barrier
	ds_read_b128 v[146:149], v196 offset:16384
	ds_read_b128 v[150:153], v196 offset:17408
	ds_read_b128 v[154:157], v196 offset:18432
	ds_read_b128 v[158:161], v196 offset:19456
	ds_read_b128 v[162:165], v196 offset:20480
	ds_read_b128 v[166:169], v196 offset:21504
	ds_read_b128 v[170:173], v196 offset:22528
	ds_read_b128 v[174:177], v196 offset:23552
	buffer_load_dwordx4 v1, s[48:51], s79 offen lds
	s_add_i32 s33, s79, 0x20000
	s_mov_b32 m0, s19
	s_nop 0
	buffer_load_dwordx4 v1, s[48:51], s33 offen lds
	s_barrier
	s_waitcnt lgkmcnt(0)
	s_setprio 1
	s_waitcnt lgkmcnt(7)
	v_mfma_f32_16x16x32_bf16 v[62:65], v[130:133], v[146:149], v[62:65]
	v_mfma_f32_16x16x32_bf16 v[58:61], v[138:141], v[146:149], v[58:61]
	s_waitcnt lgkmcnt(5)
	v_mfma_f32_16x16x32_bf16 v[46:49], v[130:133], v[154:157], v[46:49]
	v_mfma_f32_16x16x32_bf16 v[42:45], v[138:141], v[154:157], v[42:45]
	s_waitcnt lgkmcnt(3)
	v_mfma_f32_16x16x32_bf16 v[30:33], v[130:133], v[162:165], v[30:33]
	v_mfma_f32_16x16x32_bf16 v[26:29], v[138:141], v[162:165], v[26:29]
	s_waitcnt lgkmcnt(1)
	v_mfma_f32_16x16x32_bf16 v[14:17], v[130:133], v[170:173], v[14:17]
	v_mfma_f32_16x16x32_bf16 v[10:13], v[138:141], v[170:173], v[10:13]
	v_mfma_f32_16x16x32_bf16 v[62:65], v[134:137], v[150:153], v[62:65]
	v_mfma_f32_16x16x32_bf16 v[58:61], v[142:145], v[150:153], v[58:61]
	v_mfma_f32_16x16x32_bf16 v[46:49], v[134:137], v[158:161], v[46:49]
	v_mfma_f32_16x16x32_bf16 v[42:45], v[142:145], v[158:161], v[42:45]
	v_mfma_f32_16x16x32_bf16 v[30:33], v[134:137], v[166:169], v[30:33]
	v_mfma_f32_16x16x32_bf16 v[26:29], v[142:145], v[166:169], v[26:29]
	s_waitcnt lgkmcnt(0)
	v_mfma_f32_16x16x32_bf16 v[14:17], v[134:137], v[174:177], v[14:17]
	v_mfma_f32_16x16x32_bf16 v[10:13], v[142:145], v[174:177], v[10:13]
	s_setprio 0
	s_barrier
	s_mov_b32 m0, s20
	s_add_i32 s33, s78, 0x40000
	buffer_load_dwordx4 v192, s[8:11], s33 offen lds
	s_add_i32 s33, s78, 0x60000
	s_mov_b32 m0, s21
	s_nop 0
	buffer_load_dwordx4 v192, s[8:11], s33 offen lds
	s_waitcnt vmcnt(6)
	s_barrier
	s_setprio 1
	v_mfma_f32_16x16x32_bf16 v[54:57], v[178:181], v[146:149], v[54:57]
	v_mfma_f32_16x16x32_bf16 v[50:53], v[200:203], v[146:149], v[50:53]
	v_mfma_f32_16x16x32_bf16 v[38:41], v[178:181], v[154:157], v[38:41]
	v_mfma_f32_16x16x32_bf16 v[34:37], v[200:203], v[154:157], v[34:37]
	v_mfma_f32_16x16x32_bf16 v[22:25], v[178:181], v[162:165], v[22:25]
	v_mfma_f32_16x16x32_bf16 v[18:21], v[200:203], v[162:165], v[18:21]
	v_mfma_f32_16x16x32_bf16 v[6:9], v[178:181], v[170:173], v[6:9]
	v_mfma_f32_16x16x32_bf16 v[2:5], v[200:203], v[170:173], v[2:5]
	v_mfma_f32_16x16x32_bf16 v[54:57], v[182:185], v[150:153], v[54:57]
	v_mfma_f32_16x16x32_bf16 v[50:53], v[204:207], v[150:153], v[50:53]
	v_mfma_f32_16x16x32_bf16 v[38:41], v[182:185], v[158:161], v[38:41]
	v_mfma_f32_16x16x32_bf16 v[34:37], v[204:207], v[158:161], v[34:37]
	v_mfma_f32_16x16x32_bf16 v[22:25], v[182:185], v[166:169], v[22:25]
	v_mfma_f32_16x16x32_bf16 v[18:21], v[204:207], v[166:169], v[18:21]
	v_mfma_f32_16x16x32_bf16 v[6:9], v[182:185], v[174:177], v[6:9]
	v_mfma_f32_16x16x32_bf16 v[2:5], v[204:207], v[174:177], v[2:5]
	s_setprio 0
	s_barrier
	ds_read_b128 v[130:133], v198
	ds_read_b128 v[134:137], v198 offset:1024
	ds_read_b128 v[138:141], v198 offset:2048
	ds_read_b128 v[142:145], v198 offset:3072
	s_mov_b32 m0, s22
	s_add_i32 s33, s79, 0x40000
	ds_read_b128 v[146:149], v196 offset:32768
	ds_read_b128 v[150:153], v196 offset:33792
	ds_read_b128 v[154:157], v196 offset:34816
	ds_read_b128 v[158:161], v196 offset:35840
	ds_read_b128 v[162:165], v196 offset:36864
	ds_read_b128 v[166:169], v196 offset:37888
	ds_read_b128 v[170:173], v196 offset:38912
	ds_read_b128 v[174:177], v196 offset:39936
	buffer_load_dwordx4 v1, s[48:51], s33 offen lds
	s_add_i32 s33, s79, 0x60000
	s_mov_b32 m0, s23
	s_nop 0
	buffer_load_dwordx4 v1, s[48:51], s33 offen lds
	s_waitcnt lgkmcnt(8)
	s_barrier
	s_waitcnt lgkmcnt(0)
	s_setprio 1
	s_waitcnt lgkmcnt(7)
	v_mfma_f32_16x16x32_bf16 v[126:129], v[130:133], v[146:149], v[126:129]
	v_mfma_f32_16x16x32_bf16 v[122:125], v[138:141], v[146:149], v[122:125]
	s_waitcnt lgkmcnt(5)
	v_mfma_f32_16x16x32_bf16 v[110:113], v[130:133], v[154:157], v[110:113]
	v_mfma_f32_16x16x32_bf16 v[106:109], v[138:141], v[154:157], v[106:109]
	s_waitcnt lgkmcnt(3)
	v_mfma_f32_16x16x32_bf16 v[94:97], v[130:133], v[162:165], v[94:97]
	v_mfma_f32_16x16x32_bf16 v[90:93], v[138:141], v[162:165], v[90:93]
	s_waitcnt lgkmcnt(1)
	v_mfma_f32_16x16x32_bf16 v[78:81], v[130:133], v[170:173], v[78:81]
	v_mfma_f32_16x16x32_bf16 v[74:77], v[138:141], v[170:173], v[74:77]
	v_mfma_f32_16x16x32_bf16 v[126:129], v[134:137], v[150:153], v[126:129]
	v_mfma_f32_16x16x32_bf16 v[122:125], v[142:145], v[150:153], v[122:125]
	v_mfma_f32_16x16x32_bf16 v[110:113], v[134:137], v[158:161], v[110:113]
	v_mfma_f32_16x16x32_bf16 v[106:109], v[142:145], v[158:161], v[106:109]
	v_mfma_f32_16x16x32_bf16 v[94:97], v[134:137], v[166:169], v[94:97]
	v_mfma_f32_16x16x32_bf16 v[90:93], v[142:145], v[166:169], v[90:93]
	s_waitcnt lgkmcnt(0)
	v_mfma_f32_16x16x32_bf16 v[78:81], v[134:137], v[174:177], v[78:81]
	v_mfma_f32_16x16x32_bf16 v[74:77], v[142:145], v[174:177], v[74:77]
	s_setprio 0
	s_barrier
	s_mov_b32 m0, s29
	s_add_i32 s33, s78, 0x80
	ds_read_b128 v[178:181], v199
	ds_read_b128 v[182:185], v199 offset:1024
	ds_read_b128 v[200:203], v199 offset:2048
	ds_read_b128 v[204:207], v199 offset:3072
	buffer_load_dwordx4 v192, s[8:11], s33 offen lds
	s_add_i32 s33, s78, 0x20080
	s_mov_b32 m0, s30
	s_nop 0
	buffer_load_dwordx4 v192, s[8:11], s33 offen lds
	s_waitcnt vmcnt(10)
	s_barrier
	s_waitcnt lgkmcnt(0)
	s_setprio 1
	s_waitcnt lgkmcnt(3)
	v_mfma_f32_16x16x32_bf16 v[118:121], v[178:181], v[146:149], v[118:121]
	s_waitcnt lgkmcnt(1)
	v_mfma_f32_16x16x32_bf16 v[114:117], v[200:203], v[146:149], v[114:117]
	v_mfma_f32_16x16x32_bf16 v[102:105], v[178:181], v[154:157], v[102:105]
	v_mfma_f32_16x16x32_bf16 v[98:101], v[200:203], v[154:157], v[98:101]
	v_mfma_f32_16x16x32_bf16 v[86:89], v[178:181], v[162:165], v[86:89]
	v_mfma_f32_16x16x32_bf16 v[82:85], v[200:203], v[162:165], v[82:85]
	v_mfma_f32_16x16x32_bf16 v[70:73], v[178:181], v[170:173], v[70:73]
	v_mfma_f32_16x16x32_bf16 v[66:69], v[200:203], v[170:173], v[66:69]
	v_mfma_f32_16x16x32_bf16 v[118:121], v[182:185], v[150:153], v[118:121]
	s_waitcnt lgkmcnt(0)
	v_mfma_f32_16x16x32_bf16 v[114:117], v[204:207], v[150:153], v[114:117]
	v_mfma_f32_16x16x32_bf16 v[102:105], v[182:185], v[158:161], v[102:105]
	v_mfma_f32_16x16x32_bf16 v[98:101], v[204:207], v[158:161], v[98:101]
	v_mfma_f32_16x16x32_bf16 v[86:89], v[182:185], v[166:169], v[86:89]
	v_mfma_f32_16x16x32_bf16 v[82:85], v[204:207], v[166:169], v[82:85]
	v_mfma_f32_16x16x32_bf16 v[70:73], v[182:185], v[174:177], v[70:73]
	v_mfma_f32_16x16x32_bf16 v[66:69], v[204:207], v[174:177], v[66:69]
	s_setprio 0
	s_mov_b32 m0, s31
	s_barrier
	ds_read_b128 v[146:149], v196 offset:49152
	ds_read_b128 v[150:153], v196 offset:50176
	ds_read_b128 v[154:157], v196 offset:51200
	ds_read_b128 v[158:161], v196 offset:52224
	ds_read_b128 v[162:165], v196 offset:53248
	ds_read_b128 v[166:169], v196 offset:54272
	ds_read_b128 v[170:173], v196 offset:55296
	ds_read_b128 v[174:177], v196 offset:56320
	buffer_load_dwordx4 v1, s[48:51], s84 offen lds
	s_add_i32 s79, s79, 0x20080
	s_mov_b32 m0, s34
	s_nop 0
	buffer_load_dwordx4 v1, s[48:51], s79 offen lds
	s_barrier
	s_waitcnt lgkmcnt(0)
	s_setprio 1
	s_waitcnt lgkmcnt(7)
	v_mfma_f32_16x16x32_bf16 v[62:65], v[130:133], v[146:149], v[62:65]
	v_mfma_f32_16x16x32_bf16 v[58:61], v[138:141], v[146:149], v[58:61]
	s_waitcnt lgkmcnt(5)
	v_mfma_f32_16x16x32_bf16 v[46:49], v[130:133], v[154:157], v[46:49]
	v_mfma_f32_16x16x32_bf16 v[42:45], v[138:141], v[154:157], v[42:45]
	s_waitcnt lgkmcnt(3)
	v_mfma_f32_16x16x32_bf16 v[30:33], v[130:133], v[162:165], v[30:33]
	v_mfma_f32_16x16x32_bf16 v[26:29], v[138:141], v[162:165], v[26:29]
	s_waitcnt lgkmcnt(1)
	v_mfma_f32_16x16x32_bf16 v[14:17], v[130:133], v[170:173], v[14:17]
	v_mfma_f32_16x16x32_bf16 v[10:13], v[138:141], v[170:173], v[10:13]
	v_mfma_f32_16x16x32_bf16 v[62:65], v[134:137], v[150:153], v[62:65]
	v_mfma_f32_16x16x32_bf16 v[58:61], v[142:145], v[150:153], v[58:61]
	v_mfma_f32_16x16x32_bf16 v[46:49], v[134:137], v[158:161], v[46:49]
	v_mfma_f32_16x16x32_bf16 v[42:45], v[142:145], v[158:161], v[42:45]
	v_mfma_f32_16x16x32_bf16 v[30:33], v[134:137], v[166:169], v[30:33]
	v_mfma_f32_16x16x32_bf16 v[26:29], v[142:145], v[166:169], v[26:29]
	s_waitcnt lgkmcnt(0)
	v_mfma_f32_16x16x32_bf16 v[14:17], v[134:137], v[174:177], v[14:17]
	v_mfma_f32_16x16x32_bf16 v[10:13], v[142:145], v[174:177], v[10:13]
	s_setprio 0
	s_barrier
	s_mov_b32 m0, s35
	s_add_i32 s33, s78, 0x40080
	buffer_load_dwordx4 v192, s[8:11], s33 offen lds
	s_add_i32 s78, s78, 0x60080
	s_mov_b32 m0, s36
	s_nop 0
	buffer_load_dwordx4 v192, s[8:11], s78 offen lds
	s_waitcnt vmcnt(6)
	s_barrier
	s_setprio 1
	v_mfma_f32_16x16x32_bf16 v[54:57], v[178:181], v[146:149], v[54:57]
	v_mfma_f32_16x16x32_bf16 v[50:53], v[200:203], v[146:149], v[50:53]
	v_mfma_f32_16x16x32_bf16 v[38:41], v[178:181], v[154:157], v[38:41]
	v_mfma_f32_16x16x32_bf16 v[34:37], v[200:203], v[154:157], v[34:37]
	v_mfma_f32_16x16x32_bf16 v[22:25], v[178:181], v[162:165], v[22:25]
	v_mfma_f32_16x16x32_bf16 v[18:21], v[200:203], v[162:165], v[18:21]
	v_mfma_f32_16x16x32_bf16 v[6:9], v[178:181], v[170:173], v[6:9]
	v_mfma_f32_16x16x32_bf16 v[2:5], v[200:203], v[170:173], v[2:5]
	v_mfma_f32_16x16x32_bf16 v[54:57], v[182:185], v[150:153], v[54:57]
	v_mfma_f32_16x16x32_bf16 v[50:53], v[204:207], v[150:153], v[50:53]
	v_mfma_f32_16x16x32_bf16 v[38:41], v[182:185], v[158:161], v[38:41]
	v_mfma_f32_16x16x32_bf16 v[34:37], v[204:207], v[158:161], v[34:37]
	v_mfma_f32_16x16x32_bf16 v[22:25], v[182:185], v[166:169], v[22:25]
	v_mfma_f32_16x16x32_bf16 v[18:21], v[204:207], v[166:169], v[18:21]
	v_mfma_f32_16x16x32_bf16 v[6:9], v[182:185], v[174:177], v[6:9]
	v_mfma_f32_16x16x32_bf16 v[2:5], v[204:207], v[174:177], v[2:5]
	s_setprio 0
	s_add_i32 s13, s13, 2
	s_addk_i32 s7, 0x100
	s_addk_i32 s12, 0x100
	s_cmp_gt_u32 s13, 13
	s_barrier
	s_cbranch_scc0 .LBB0_1334
	s_cmpk_gt_i32 s72, 0x7f
	s_cselect_b64 s[6:7], -1, 0
	s_and_b64 vcc, exec, s[6:7]
	s_cbranch_vccz .LBB0_1327
	s_mov_b64 s[10:11], 0xc000
	s_mov_b64 s[12:13], 0xcb00000
	s_branch .LBB0_1328

.LBB0_1658:
	s_and_b64 s[14:15], s[6:7], exec
	s_cselect_b32 s59, 0, s9
	s_add_i32 s14, s57, s9
	s_or_b32 s58, s59, 0x80
	s_waitcnt lgkmcnt(8)
	s_barrier
	s_waitcnt lgkmcnt(0)
	s_and_b64 s[6:7], s[6:7], exec
	s_cselect_b32 s6, s46, s14
	s_add_i32 s7, s6, 0x80
	s_setprio 1
	s_waitcnt lgkmcnt(6)
	v_mfma_f32_16x16x128_f8f6f4 v[174:177], v[2:9], v[42:49], v[174:177]
	v_mfma_f32_16x16x128_f8f6f4 v[166:169], v[10:17], v[42:49], v[166:169]
	s_waitcnt lgkmcnt(4)
	v_mfma_f32_16x16x128_f8f6f4 v[158:161], v[2:9], v[34:41], v[158:161]
	v_mfma_f32_16x16x128_f8f6f4 v[150:153], v[10:17], v[34:41], v[150:153]
	s_waitcnt lgkmcnt(2)
	v_mfma_f32_16x16x128_f8f6f4 v[142:145], v[2:9], v[26:33], v[142:145]
	v_mfma_f32_16x16x128_f8f6f4 v[134:137], v[10:17], v[26:33], v[134:137]
	s_waitcnt lgkmcnt(0)
	v_mfma_f32_16x16x128_f8f6f4 v[126:129], v[2:9], v[18:25], v[126:129]
	v_mfma_f32_16x16x128_f8f6f4 v[118:121], v[10:17], v[18:25], v[118:121]
	s_setprio 0
	s_barrier
	s_mov_b32 m0, s18
	v_add_u32_e32 v210, 0x14000, v189
	s_mov_b32 s14, s42
	s_mov_b32 s15, s43
	ds_read_b128 v[198:201], v210
	ds_read_b128 v[202:205], v210 offset:1024
	ds_read_b128 v[206:209], v210 offset:2048
	ds_read_b128 v[210:213], v210 offset:3072
	buffer_load_dwordx4 v184, s[12:15], s6 offen lds
	s_add_i32 s33, s6, 0x10000
	s_mov_b32 m0, s19
	s_nop 0
	buffer_load_dwordx4 v184, s[12:15], s33 offen lds
	s_barrier
	s_waitcnt lgkmcnt(0)
	s_setprio 1
	s_waitcnt lgkmcnt(2)
	v_mfma_f32_16x16x128_f8f6f4 v[170:173], v[198:205], v[42:49], v[170:173]
	s_waitcnt lgkmcnt(0)
	v_mfma_f32_16x16x128_f8f6f4 v[162:165], v[206:213], v[42:49], v[162:165]
	v_mfma_f32_16x16x128_f8f6f4 v[154:157], v[198:205], v[34:41], v[154:157]
	v_mfma_f32_16x16x128_f8f6f4 v[146:149], v[206:213], v[34:41], v[146:149]
	v_mfma_f32_16x16x128_f8f6f4 v[138:141], v[198:205], v[26:33], v[138:141]
	v_mfma_f32_16x16x128_f8f6f4 v[130:133], v[206:213], v[26:33], v[130:133]
	v_mfma_f32_16x16x128_f8f6f4 v[122:125], v[198:205], v[18:25], v[122:125]
	v_mfma_f32_16x16x128_f8f6f4 v[114:117], v[206:213], v[18:25], v[114:117]
	s_setprio 0
	v_lshlrev_b32_e32 v214, 10, v186
	v_and_b32_e32 v214, 0x3fffc00, v214
	v_lshlrev_b32_e32 v215, 10, v185
	s_mov_b32 m0, s17
	v_add_u32_e32 v214, v214, v1
	v_and_b32_e32 v215, 0x3fffc00, v215
	s_barrier
	ds_read_b128 v[18:21], v191 offset:16384
	ds_read_b128 v[22:25], v191 offset:17408
	ds_read_b128 v[26:29], v191 offset:18432
	ds_read_b128 v[30:33], v191 offset:19456
	ds_read_b128 v[34:37], v191 offset:20480
	ds_read_b128 v[38:41], v191 offset:21504
	ds_read_b128 v[42:45], v191 offset:22528
	ds_read_b128 v[46:49], v191 offset:23552
	buffer_load_dwordx4 v214, s[40:43], s59 offen lds
	v_add_u32_e32 v215, v215, v1
	s_mov_b32 m0, s20
	s_nop 0
	buffer_load_dwordx4 v215, s[40:43], s59 offen lds
	s_barrier
	s_waitcnt lgkmcnt(0)
	s_setprio 1
	s_waitcnt lgkmcnt(6)
	v_mfma_f32_16x16x128_f8f6f4 v[110:113], v[2:9], v[18:25], v[110:113]
	v_mfma_f32_16x16x128_f8f6f4 v[102:105], v[10:17], v[18:25], v[102:105]
	s_waitcnt lgkmcnt(4)
	v_mfma_f32_16x16x128_f8f6f4 v[94:97], v[2:9], v[26:33], v[94:97]
	v_mfma_f32_16x16x128_f8f6f4 v[86:89], v[10:17], v[26:33], v[86:89]
	s_waitcnt lgkmcnt(2)
	v_mfma_f32_16x16x128_f8f6f4 v[78:81], v[2:9], v[34:41], v[78:81]
	v_mfma_f32_16x16x128_f8f6f4 v[70:73], v[10:17], v[34:41], v[70:73]
	s_waitcnt lgkmcnt(0)
	v_mfma_f32_16x16x128_f8f6f4 v[62:65], v[2:9], v[42:49], v[62:65]
	v_mfma_f32_16x16x128_f8f6f4 v[54:57], v[10:17], v[42:49], v[54:57]
	s_setprio 0
	s_barrier
	s_mov_b32 m0, s21
	s_add_i32 s33, s6, 0x20000
	buffer_load_dwordx4 v184, s[12:15], s33 offen lds
	s_add_i32 s33, s6, 0x30000
	s_mov_b32 m0, s22
	s_nop 0
	buffer_load_dwordx4 v184, s[12:15], s33 offen lds
	s_waitcnt vmcnt(6)
	s_barrier
	s_setprio 1
	v_mfma_f32_16x16x128_f8f6f4 v[106:109], v[198:205], v[18:25], v[106:109]
	v_mfma_f32_16x16x128_f8f6f4 v[98:101], v[206:213], v[18:25], v[98:101]
	v_mfma_f32_16x16x128_f8f6f4 v[90:93], v[198:205], v[26:33], v[90:93]
	v_mfma_f32_16x16x128_f8f6f4 v[82:85], v[206:213], v[26:33], v[82:85]
	v_mfma_f32_16x16x128_f8f6f4 v[74:77], v[198:205], v[34:41], v[74:77]
	v_mfma_f32_16x16x128_f8f6f4 v[66:69], v[206:213], v[34:41], v[66:69]
	v_mfma_f32_16x16x128_f8f6f4 v[58:61], v[198:205], v[42:49], v[58:61]
	v_mfma_f32_16x16x128_f8f6f4 v[50:53], v[206:213], v[42:49], v[50:53]
	s_setprio 0
	v_add_u32_e32 v14, 0x18000, v189
	s_barrier
	ds_read_b128 v[2:5], v14
	ds_read_b128 v[6:9], v14 offset:1024
	ds_read_b128 v[10:13], v14 offset:2048
	ds_read_b128 v[14:17], v14 offset:3072
	s_mov_b32 m0, s23
	ds_read_b128 v[18:21], v191 offset:32768
	ds_read_b128 v[22:25], v191 offset:33792
	ds_read_b128 v[26:29], v191 offset:34816
	ds_read_b128 v[30:33], v191 offset:35840
	ds_read_b128 v[34:37], v191 offset:36864
	ds_read_b128 v[38:41], v191 offset:37888
	ds_read_b128 v[42:45], v191 offset:38912
	ds_read_b128 v[46:49], v191 offset:39936
	buffer_load_dwordx4 v196, s[40:43], s59 offen lds
	s_mov_b32 m0, s24
	s_nop 0
	buffer_load_dwordx4 v197, s[40:43], s59 offen lds
	s_waitcnt lgkmcnt(8)
	s_barrier
	s_waitcnt lgkmcnt(0)
	s_setprio 1
	s_waitcnt lgkmcnt(6)
	v_mfma_f32_16x16x128_f8f6f4 v[174:177], v[2:9], v[18:25], v[174:177]
	v_mfma_f32_16x16x128_f8f6f4 v[166:169], v[10:17], v[18:25], v[166:169]
	s_waitcnt lgkmcnt(4)
	v_mfma_f32_16x16x128_f8f6f4 v[158:161], v[2:9], v[26:33], v[158:161]
	v_mfma_f32_16x16x128_f8f6f4 v[150:153], v[10:17], v[26:33], v[150:153]
	s_waitcnt lgkmcnt(2)
	v_mfma_f32_16x16x128_f8f6f4 v[142:145], v[2:9], v[34:41], v[142:145]
	v_mfma_f32_16x16x128_f8f6f4 v[134:137], v[10:17], v[34:41], v[134:137]
	s_waitcnt lgkmcnt(0)
	v_mfma_f32_16x16x128_f8f6f4 v[126:129], v[2:9], v[42:49], v[126:129]
	v_mfma_f32_16x16x128_f8f6f4 v[118:121], v[10:17], v[42:49], v[118:121]
	s_setprio 0
	s_barrier
	s_mov_b32 m0, s26
	v_add_u32_e32 v208, 0x1c000, v189
	ds_read_b128 v[196:199], v208
	ds_read_b128 v[200:203], v208 offset:1024
	ds_read_b128 v[204:207], v208 offset:2048
	ds_read_b128 v[208:211], v208 offset:3072
	buffer_load_dwordx4 v184, s[12:15], s7 offen lds
	s_add_i32 s7, s6, 0x10080
	s_mov_b32 m0, s27
	s_nop 0
	buffer_load_dwordx4 v184, s[12:15], s7 offen lds
	s_waitcnt vmcnt(10)
	s_barrier
	s_waitcnt lgkmcnt(0)
	s_setprio 1
	s_waitcnt lgkmcnt(2)
	v_mfma_f32_16x16x128_f8f6f4 v[170:173], v[196:203], v[18:25], v[170:173]
	s_waitcnt lgkmcnt(0)
	v_mfma_f32_16x16x128_f8f6f4 v[162:165], v[204:211], v[18:25], v[162:165]
	v_mfma_f32_16x16x128_f8f6f4 v[154:157], v[196:203], v[26:33], v[154:157]
	v_mfma_f32_16x16x128_f8f6f4 v[146:149], v[204:211], v[26:33], v[146:149]
	v_mfma_f32_16x16x128_f8f6f4 v[138:141], v[196:203], v[34:41], v[138:141]
	v_mfma_f32_16x16x128_f8f6f4 v[130:133], v[204:211], v[34:41], v[130:133]
	v_mfma_f32_16x16x128_f8f6f4 v[122:125], v[196:203], v[42:49], v[122:125]
	v_mfma_f32_16x16x128_f8f6f4 v[114:117], v[204:211], v[42:49], v[114:117]
	s_setprio 0
	s_mov_b32 m0, s28
	s_barrier
	ds_read_b128 v[18:21], v191 offset:49152
	ds_read_b128 v[22:25], v191 offset:50176
	ds_read_b128 v[26:29], v191 offset:51200
	ds_read_b128 v[30:33], v191 offset:52224
	ds_read_b128 v[34:37], v191 offset:53248
	ds_read_b128 v[38:41], v191 offset:54272
	ds_read_b128 v[42:45], v191 offset:55296
	ds_read_b128 v[46:49], v191 offset:56320
	buffer_load_dwordx4 v214, s[40:43], s58 offen lds
	s_mov_b32 m0, s29
	s_nop 0
	buffer_load_dwordx4 v215, s[40:43], s58 offen lds
	s_barrier
	s_waitcnt lgkmcnt(0)
	s_setprio 1
	s_waitcnt lgkmcnt(6)
	v_mfma_f32_16x16x128_f8f6f4 v[110:113], v[2:9], v[18:25], v[110:113]
	v_mfma_f32_16x16x128_f8f6f4 v[102:105], v[10:17], v[18:25], v[102:105]
	s_waitcnt lgkmcnt(4)
	v_mfma_f32_16x16x128_f8f6f4 v[94:97], v[2:9], v[26:33], v[94:97]
	v_mfma_f32_16x16x128_f8f6f4 v[86:89], v[10:17], v[26:33], v[86:89]
	s_waitcnt lgkmcnt(2)
	v_mfma_f32_16x16x128_f8f6f4 v[78:81], v[2:9], v[34:41], v[78:81]
	v_mfma_f32_16x16x128_f8f6f4 v[70:73], v[10:17], v[34:41], v[70:73]
	s_waitcnt lgkmcnt(0)
	v_mfma_f32_16x16x128_f8f6f4 v[62:65], v[2:9], v[42:49], v[62:65]
	v_mfma_f32_16x16x128_f8f6f4 v[54:57], v[10:17], v[42:49], v[54:57]
	s_setprio 0
	s_barrier
	s_mov_b32 m0, s30
	s_add_i32 s7, s6, 0x20080
	buffer_load_dwordx4 v184, s[12:15], s7 offen lds
	s_add_i32 s6, s6, 0x30080
	s_mov_b32 m0, s31
	s_nop 0
	buffer_load_dwordx4 v184, s[12:15], s6 offen lds
	s_waitcnt vmcnt(6)
	s_barrier
	s_setprio 1
	v_mfma_f32_16x16x128_f8f6f4 v[106:109], v[196:203], v[18:25], v[106:109]
	v_mfma_f32_16x16x128_f8f6f4 v[98:101], v[204:211], v[18:25], v[98:101]
	v_mfma_f32_16x16x128_f8f6f4 v[90:93], v[196:203], v[26:33], v[90:93]
	v_mfma_f32_16x16x128_f8f6f4 v[82:85], v[204:211], v[26:33], v[82:85]
	v_mfma_f32_16x16x128_f8f6f4 v[74:77], v[196:203], v[34:41], v[74:77]
	v_mfma_f32_16x16x128_f8f6f4 v[66:69], v[204:211], v[34:41], v[66:69]
	v_mfma_f32_16x16x128_f8f6f4 v[58:61], v[196:203], v[42:49], v[58:61]
	v_mfma_f32_16x16x128_f8f6f4 v[50:53], v[204:211], v[42:49], v[50:53]
	s_setprio 0
	s_add_i32 s8, s8, 2
	s_addk_i32 s9, 0x100
	s_cmp_gt_u32 s8, 5
	s_barrier
	s_cbranch_scc1 .LBB0_1650

.LBB0_1724:
	ds_read_b128 v[142:145], v137
	ds_read_b128 v[146:149], v137 offset:1024
	ds_read_b128 v[150:153], v137 offset:2048
	ds_read_b128 v[154:157], v137 offset:3072
	s_add_i32 s10, s7, 0xfffd0800
	s_cmp_eq_u32 s85, 4
	s_cselect_b32 s87, s6, s10
	s_cselect_b32 s86, s72, s84
	s_or_b32 s88, s87, 0x800
	s_add_i32 s10, s7, 0xffff0000
	s_mov_b32 m0, s39
	ds_read_b128 v[158:161], v138
	ds_read_b128 v[162:165], v138 offset:1024
	ds_read_b128 v[166:169], v138 offset:2048
	ds_read_b128 v[170:173], v138 offset:3072
	ds_read_b128 v[174:177], v138 offset:4096
	ds_read_b128 v[178:181], v138 offset:5120
	ds_read_b128 v[182:185], v138 offset:6144
	ds_read_b128 v[186:189], v138 offset:7168
	buffer_load_dwordx4 v1, s[44:47], s10 offen lds
	s_mov_b32 m0, s41
	s_nop 0
	buffer_load_dwordx4 v1, s[44:47], s7 offen lds
	s_waitcnt lgkmcnt(8)
	s_barrier
	s_waitcnt lgkmcnt(0)
	s_setprio 1
	s_waitcnt lgkmcnt(4)
	v_mfma_f32_16x16x128_f8f6f4 v[114:117], v[142:149], v[166:173], v[114:117]
	v_mfma_f32_16x16x128_f8f6f4 v[106:109], v[150:157], v[166:173], v[106:109]
	s_waitcnt lgkmcnt(2)
	v_mfma_f32_16x16x128_f8f6f4 v[98:101], v[142:149], v[174:181], v[98:101]
	v_mfma_f32_16x16x128_f8f6f4 v[198:201], v[142:149], v[158:165], v[126:129]
	v_mfma_f32_16x16x128_f8f6f4 v[202:205], v[150:157], v[158:165], v[122:125]
	v_mfma_f32_16x16x128_f8f6f4 v[206:209], v[150:157], v[174:181], v[90:93]
	s_waitcnt lgkmcnt(0)
	v_mfma_f32_16x16x128_f8f6f4 v[210:213], v[142:149], v[182:189], v[82:85]
	v_mfma_f32_16x16x128_f8f6f4 v[214:217], v[150:157], v[182:189], v[74:77]
	s_setprio 0
	s_barrier
	s_mov_b32 m0, s23
	s_mov_b32 s10, s46
	s_mov_b32 s11, s47
	ds_read_b128 v[122:125], v139
	ds_read_b128 v[126:129], v139 offset:1024
	ds_read_b128 v[190:193], v139 offset:2048
	ds_read_b128 v[194:197], v139 offset:3072
	buffer_load_dwordx4 v134, s[8:11], s86 offen lds
	s_add_i32 s33, s86, 0x20000
	s_mov_b32 m0, s24
	s_nop 0
	buffer_load_dwordx4 v134, s[8:11], s33 offen lds
	s_barrier
	s_waitcnt lgkmcnt(0)
	s_setprio 1
	s_waitcnt lgkmcnt(2)
	v_mfma_f32_16x16x128_f8f6f4 v[118:121], v[122:129], v[158:165], v[118:121]
	s_waitcnt lgkmcnt(0)
	v_mfma_f32_16x16x128_f8f6f4 v[110:113], v[190:197], v[158:165], v[110:113]
	v_mfma_f32_16x16x128_f8f6f4 v[102:105], v[122:129], v[166:173], v[102:105]
	v_mfma_f32_16x16x128_f8f6f4 v[158:161], v[190:197], v[166:173], v[94:97]
	v_mfma_f32_16x16x128_f8f6f4 v[162:165], v[122:129], v[174:181], v[86:89]
	v_mfma_f32_16x16x128_f8f6f4 v[166:169], v[190:197], v[174:181], v[78:81]
	v_mfma_f32_16x16x128_f8f6f4 v[170:173], v[122:129], v[182:189], v[70:73]
	v_mfma_f32_16x16x128_f8f6f4 v[174:177], v[190:197], v[182:189], v[18:21]
	s_setprio 0
	s_mov_b32 m0, s22
	s_barrier
	ds_read_b128 v[66:69], v138 offset:16384
	s_nop 1
	ds_read_b128 v[70:73], v138 offset:17408
	ds_read_b128 v[74:77], v138 offset:18432
	ds_read_b128 v[78:81], v138 offset:19456
	ds_read_b128 v[82:85], v138 offset:20480
	ds_read_b128 v[86:89], v138 offset:21504
	ds_read_b128 v[90:93], v138 offset:22528
	ds_read_b128 v[94:97], v138 offset:23552
	buffer_load_dwordx4 v1, s[44:47], s87 offen lds
	s_add_i32 s33, s87, 0x10000
	s_mov_b32 m0, s25
	s_nop 0
	buffer_load_dwordx4 v1, s[44:47], s33 offen lds
	s_barrier
	s_waitcnt lgkmcnt(0)
	s_setprio 1
	s_waitcnt lgkmcnt(6)
	v_mfma_f32_16x16x128_f8f6f4 v[62:65], v[142:149], v[66:73], v[62:65]
	v_mfma_f32_16x16x128_f8f6f4 v[58:61], v[150:157], v[66:73], v[58:61]
	s_waitcnt lgkmcnt(4)
	v_mfma_f32_16x16x128_f8f6f4 v[50:53], v[142:149], v[74:81], v[50:53]
	s_waitcnt lgkmcnt(0)
	v_mfma_f32_16x16x128_f8f6f4 v[230:233], v[142:149], v[90:97], v[230:233]
	v_mfma_f32_16x16x128_f8f6f4 v[218:221], v[150:157], v[74:81], v[42:45]
	v_mfma_f32_16x16x128_f8f6f4 v[222:225], v[142:149], v[82:89], v[34:37]
	v_mfma_f32_16x16x128_f8f6f4 v[226:229], v[150:157], v[82:89], v[26:29]
	v_mfma_f32_16x16x128_f8f6f4 v[234:237], v[150:157], v[90:97], v[10:13]
	s_setprio 0
	s_barrier
	s_mov_b32 m0, s26
	s_add_i32 s33, s86, 0x2000
	buffer_load_dwordx4 v134, s[8:11], s33 offen lds
	s_add_i32 s33, s86, 0x22000
	s_mov_b32 m0, s27
	s_nop 0
	buffer_load_dwordx4 v134, s[8:11], s33 offen lds
	s_waitcnt vmcnt(6)
	s_barrier
	s_setprio 1
	v_mfma_f32_16x16x128_f8f6f4 v[54:57], v[122:129], v[66:73], v[54:57]
	v_mfma_f32_16x16x128_f8f6f4 v[238:241], v[190:197], v[66:73], v[46:49]
	v_mfma_f32_16x16x128_f8f6f4 v[242:245], v[122:129], v[74:81], v[38:41]
	v_mfma_f32_16x16x128_f8f6f4 v[246:249], v[190:197], v[74:81], v[30:33]
	v_mfma_f32_16x16x128_f8f6f4 v[250:253], v[122:129], v[82:89], v[22:25]
	v_mfma_f32_16x16x128_f8f6f4 v[130:133], v[190:197], v[82:89], v[14:17]
	v_mfma_f32_16x16x128_f8f6f4 v[66:69], v[122:129], v[90:97], v[6:9]
	v_mfma_f32_16x16x128_f8f6f4 v[190:193], v[190:197], v[90:97], v[2:5]
	s_setprio 0
	s_barrier
	s_nop 4
	ds_read_b128 v[2:5], v140
	ds_read_b128 v[6:9], v140 offset:1024
	ds_read_b128 v[10:13], v140 offset:2048
	ds_read_b128 v[14:17], v140 offset:3072
	s_mov_b32 m0, s28
	s_add_i32 s33, s87, 0x20000
	ds_read_b128 v[18:21], v138 offset:32768
	ds_read_b128 v[22:25], v138 offset:33792
	ds_read_b128 v[26:29], v138 offset:34816
	ds_read_b128 v[30:33], v138 offset:35840
	ds_read_b128 v[34:37], v138 offset:36864
	ds_read_b128 v[38:41], v138 offset:37888
	ds_read_b128 v[42:45], v138 offset:38912
	ds_read_b128 v[46:49], v138 offset:39936
	buffer_load_dwordx4 v1, s[44:47], s33 offen lds
	s_add_i32 s33, s87, 0x30000
	s_mov_b32 m0, s29
	s_nop 0
	buffer_load_dwordx4 v1, s[44:47], s33 offen lds
	s_waitcnt lgkmcnt(8)
	s_barrier
	s_waitcnt lgkmcnt(0)
	s_setprio 1
	s_waitcnt lgkmcnt(6)
	v_mfma_f32_16x16x128_f8f6f4 v[126:129], v[2:9], v[18:25], v[198:201]
	v_mfma_f32_16x16x128_f8f6f4 v[122:125], v[10:17], v[18:25], v[202:205]
	s_waitcnt lgkmcnt(4)
	v_mfma_f32_16x16x128_f8f6f4 v[114:117], v[2:9], v[26:33], v[114:117]
	v_mfma_f32_16x16x128_f8f6f4 v[106:109], v[10:17], v[26:33], v[106:109]
	s_waitcnt lgkmcnt(2)
	v_mfma_f32_16x16x128_f8f6f4 v[98:101], v[2:9], v[34:41], v[98:101]
	v_mfma_f32_16x16x128_f8f6f4 v[90:93], v[10:17], v[34:41], v[206:209]
	s_waitcnt lgkmcnt(0)
	v_mfma_f32_16x16x128_f8f6f4 v[82:85], v[2:9], v[42:49], v[210:213]
	v_mfma_f32_16x16x128_f8f6f4 v[74:77], v[10:17], v[42:49], v[214:217]
	s_setprio 0
	s_barrier
	s_mov_b32 m0, s31
	s_add_i32 s33, s86, 0x80
	ds_read_b128 v[142:145], v141
	ds_read_b128 v[146:149], v141 offset:1024
	ds_read_b128 v[150:153], v141 offset:2048
	ds_read_b128 v[154:157], v141 offset:3072
	buffer_load_dwordx4 v134, s[8:11], s33 offen lds
	s_add_i32 s33, s86, 0x20080
	s_mov_b32 m0, s34
	s_nop 0
	buffer_load_dwordx4 v134, s[8:11], s33 offen lds
	s_waitcnt vmcnt(10)
	s_barrier
	s_waitcnt lgkmcnt(0)
	s_setprio 1
	s_waitcnt lgkmcnt(2)
	v_mfma_f32_16x16x128_f8f6f4 v[118:121], v[142:149], v[18:25], v[118:121]
	s_waitcnt lgkmcnt(0)
	v_mfma_f32_16x16x128_f8f6f4 v[110:113], v[150:157], v[18:25], v[110:113]
	v_mfma_f32_16x16x128_f8f6f4 v[102:105], v[142:149], v[26:33], v[102:105]
	v_mfma_f32_16x16x128_f8f6f4 v[94:97], v[150:157], v[26:33], v[158:161]
	v_mfma_f32_16x16x128_f8f6f4 v[86:89], v[142:149], v[34:41], v[162:165]
	v_mfma_f32_16x16x128_f8f6f4 v[78:81], v[150:157], v[34:41], v[166:169]
	v_mfma_f32_16x16x128_f8f6f4 v[70:73], v[142:149], v[42:49], v[170:173]
	v_mfma_f32_16x16x128_f8f6f4 v[18:21], v[150:157], v[42:49], v[174:177]
	s_setprio 0
	s_mov_b32 m0, s35
	s_barrier
	ds_read_b128 v[158:161], v138 offset:49152
	ds_read_b128 v[162:165], v138 offset:50176
	ds_read_b128 v[166:169], v138 offset:51200
	ds_read_b128 v[170:173], v138 offset:52224
	ds_read_b128 v[174:177], v138 offset:53248
	ds_read_b128 v[178:181], v138 offset:54272
	ds_read_b128 v[182:185], v138 offset:55296
	ds_read_b128 v[186:189], v138 offset:56320
	buffer_load_dwordx4 v1, s[44:47], s88 offen lds
	s_add_i32 s87, s87, 0x10800
	s_mov_b32 m0, s36
	s_nop 0
	buffer_load_dwordx4 v1, s[44:47], s87 offen lds
	s_barrier
	s_waitcnt lgkmcnt(0)
	s_setprio 1
	s_waitcnt lgkmcnt(6)
	v_mfma_f32_16x16x128_f8f6f4 v[62:65], v[2:9], v[158:165], v[62:65]
	v_mfma_f32_16x16x128_f8f6f4 v[58:61], v[10:17], v[158:165], v[58:61]
	s_waitcnt lgkmcnt(4)
	v_mfma_f32_16x16x128_f8f6f4 v[50:53], v[2:9], v[166:173], v[50:53]
	v_mfma_f32_16x16x128_f8f6f4 v[42:45], v[10:17], v[166:173], v[218:221]
	s_waitcnt lgkmcnt(2)
	v_mfma_f32_16x16x128_f8f6f4 v[34:37], v[2:9], v[174:181], v[222:225]
	v_mfma_f32_16x16x128_f8f6f4 v[26:29], v[10:17], v[174:181], v[226:229]
	s_waitcnt lgkmcnt(0)
	v_mfma_f32_16x16x128_f8f6f4 v[230:233], v[2:9], v[182:189], v[230:233]
	v_mfma_f32_16x16x128_f8f6f4 v[10:13], v[10:17], v[182:189], v[234:237]
	s_setprio 0
	s_barrier
	s_mov_b32 m0, s37
	s_add_i32 s33, s86, 0x2080
	buffer_load_dwordx4 v134, s[8:11], s33 offen lds
	s_add_i32 s86, s86, 0x22080
	s_mov_b32 m0, s38
	s_nop 0
	buffer_load_dwordx4 v134, s[8:11], s86 offen lds
	s_waitcnt vmcnt(6)
	s_barrier
	s_setprio 1
	v_mfma_f32_16x16x128_f8f6f4 v[54:57], v[142:149], v[158:165], v[54:57]
	v_mfma_f32_16x16x128_f8f6f4 v[46:49], v[150:157], v[158:165], v[238:241]
	v_mfma_f32_16x16x128_f8f6f4 v[38:41], v[142:149], v[166:173], v[242:245]
	v_mfma_f32_16x16x128_f8f6f4 v[30:33], v[150:157], v[166:173], v[246:249]
	v_mfma_f32_16x16x128_f8f6f4 v[22:25], v[142:149], v[174:181], v[250:253]
	v_mfma_f32_16x16x128_f8f6f4 v[14:17], v[150:157], v[174:181], v[130:133]
	v_mfma_f32_16x16x128_f8f6f4 v[6:9], v[142:149], v[182:189], v[66:69]
	v_mfma_f32_16x16x128_f8f6f4 v[2:5], v[150:157], v[182:189], v[190:193]
	s_setprio 0
	s_add_i32 s85, s85, 2
	s_addk_i32 s7, 0x1000
	s_addk_i32 s84, 0x100
	s_cmp_gt_u32 s85, 5
	s_barrier
	s_cbranch_scc0 .LBB0_1724
	v_lshl_add_u32 v152, s79, 8, v135
	v_lshlrev_b32_e32 v153, 1, v136
	v_lshl_or_b32 v153, s78, 8, v153
	v_lshl_add_u32 v152, v152, 10, v153
	s_mov_b32 s78, s58
	s_mov_b32 s79, s59
	s_mov_b32 s84, s72
	s_mov_b32 s85, s73
	v_pk_mul_f32 v[126:127], v[126:127], 0.5 op_sel_hi:[1,0]
	v_pk_mul_f32 v[128:129], v[128:129], 0.5 op_sel_hi:[1,0]
	v_pk_mul_f32 v[122:123], v[122:123], 0.5 op_sel_hi:[1,0]
	v_pk_mul_f32 v[124:125], v[124:125], 0.5 op_sel_hi:[1,0]
	v_pk_mul_f32 v[118:119], v[118:119], 0.5 op_sel_hi:[1,0]
	v_pk_mul_f32 v[120:121], v[120:121], 0.5 op_sel_hi:[1,0]
	v_pk_mul_f32 v[110:111], v[110:111], 0.5 op_sel_hi:[1,0]
	v_pk_mul_f32 v[112:113], v[112:113], 0.5 op_sel_hi:[1,0]
	v_cvt_pk_fp8_f32 v144, v126, v127
	v_cvt_pk_fp8_f32 v145, v122, v123
	v_cvt_pk_fp8_f32 v146, v118, v119
	v_cvt_pk_fp8_f32 v147, v110, v111
	v_cvt_pk_fp8_f32 v144, v128, v129 op_sel:[0,0,1]
	v_cvt_pk_fp8_f32 v145, v124, v125 op_sel:[0,0,1]
	v_cvt_pk_fp8_f32 v146, v120, v121 op_sel:[0,0,1]
	v_cvt_pk_fp8_f32 v147, v112, v113 op_sel:[0,0,1]
	v_mov_b32_e32 v154, v152
	s_nop 0
	global_store_dwordx4 v154, v[144:147], s[68:69]
	s_mov_b32 s100, 1
	v_pk_mul_f32 v[114:115], v[114:115], 0.5 op_sel_hi:[1,0]
	v_pk_mul_f32 v[116:117], v[116:117], 0.5 op_sel_hi:[1,0]
	v_pk_mul_f32 v[106:107], v[106:107], 0.5 op_sel_hi:[1,0]
	v_pk_mul_f32 v[108:109], v[108:109], 0.5 op_sel_hi:[1,0]
	v_pk_mul_f32 v[102:103], v[102:103], 0.5 op_sel_hi:[1,0]
	v_pk_mul_f32 v[104:105], v[104:105], 0.5 op_sel_hi:[1,0]
	v_pk_mul_f32 v[94:95], v[94:95], 0.5 op_sel_hi:[1,0]
	v_pk_mul_f32 v[96:97], v[96:97], 0.5 op_sel_hi:[1,0]
	v_cvt_pk_fp8_f32 v148, v114, v115
	v_cvt_pk_fp8_f32 v149, v106, v107
	v_cvt_pk_fp8_f32 v150, v102, v103
	v_cvt_pk_fp8_f32 v151, v94, v95
	v_cvt_pk_fp8_f32 v148, v116, v117 op_sel:[0,0,1]
	v_cvt_pk_fp8_f32 v149, v108, v109 op_sel:[0,0,1]
	v_cvt_pk_fp8_f32 v150, v104, v105 op_sel:[0,0,1]
	v_cvt_pk_fp8_f32 v151, v96, v97 op_sel:[0,0,1]
	v_add_u32_e32 v155, 0x4000, v152
	s_nop 0
	global_store_dwordx4 v155, v[148:151], s[68:69]
	s_mov_b32 s100, 1
	v_pk_mul_f32 v[98:99], v[98:99], 0.5 op_sel_hi:[1,0]
	v_pk_mul_f32 v[100:101], v[100:101], 0.5 op_sel_hi:[1,0]
	v_pk_mul_f32 v[90:91], v[90:91], 0.5 op_sel_hi:[1,0]
	v_pk_mul_f32 v[92:93], v[92:93], 0.5 op_sel_hi:[1,0]
	v_pk_mul_f32 v[86:87], v[86:87], 0.5 op_sel_hi:[1,0]
	v_pk_mul_f32 v[88:89], v[88:89], 0.5 op_sel_hi:[1,0]
	v_pk_mul_f32 v[78:79], v[78:79], 0.5 op_sel_hi:[1,0]
	v_pk_mul_f32 v[80:81], v[80:81], 0.5 op_sel_hi:[1,0]
	v_cvt_pk_fp8_f32 v144, v98, v99
	v_cvt_pk_fp8_f32 v145, v90, v91
	v_cvt_pk_fp8_f32 v146, v86, v87
	v_cvt_pk_fp8_f32 v147, v78, v79
	v_cvt_pk_fp8_f32 v144, v100, v101 op_sel:[0,0,1]
	v_cvt_pk_fp8_f32 v145, v92, v93 op_sel:[0,0,1]
	v_cvt_pk_fp8_f32 v146, v88, v89 op_sel:[0,0,1]
	v_cvt_pk_fp8_f32 v147, v80, v81 op_sel:[0,0,1]
	v_add_u32_e32 v154, 0x8000, v152
	s_nop 0
	global_store_dwordx4 v154, v[144:147], s[68:69]
	s_mov_b32 s100, 1
	v_pk_mul_f32 v[82:83], v[82:83], 0.5 op_sel_hi:[1,0]
	v_pk_mul_f32 v[84:85], v[84:85], 0.5 op_sel_hi:[1,0]
	v_pk_mul_f32 v[74:75], v[74:75], 0.5 op_sel_hi:[1,0]
	v_pk_mul_f32 v[76:77], v[76:77], 0.5 op_sel_hi:[1,0]
	v_pk_mul_f32 v[70:71], v[70:71], 0.5 op_sel_hi:[1,0]
	v_pk_mul_f32 v[72:73], v[72:73], 0.5 op_sel_hi:[1,0]
	v_pk_mul_f32 v[18:19], v[18:19], 0.5 op_sel_hi:[1,0]
	v_pk_mul_f32 v[20:21], v[20:21], 0.5 op_sel_hi:[1,0]
	v_cvt_pk_fp8_f32 v148, v82, v83
	v_cvt_pk_fp8_f32 v149, v74, v75
	v_cvt_pk_fp8_f32 v150, v70, v71
	v_cvt_pk_fp8_f32 v151, v18, v19
	v_cvt_pk_fp8_f32 v148, v84, v85 op_sel:[0,0,1]
	v_cvt_pk_fp8_f32 v149, v76, v77 op_sel:[0,0,1]
	v_cvt_pk_fp8_f32 v150, v72, v73 op_sel:[0,0,1]
	v_cvt_pk_fp8_f32 v151, v20, v21 op_sel:[0,0,1]
	v_add_u32_e32 v155, 0xc000, v152
	s_nop 0
	global_store_dwordx4 v155, v[148:151], s[68:69]
	s_mov_b32 s100, 1
	v_pk_mul_f32 v[62:63], v[62:63], 0.5 op_sel_hi:[1,0]
	v_pk_mul_f32 v[64:65], v[64:65], 0.5 op_sel_hi:[1,0]
	v_pk_mul_f32 v[58:59], v[58:59], 0.5 op_sel_hi:[1,0]
	v_pk_mul_f32 v[60:61], v[60:61], 0.5 op_sel_hi:[1,0]
	v_pk_mul_f32 v[54:55], v[54:55], 0.5 op_sel_hi:[1,0]
	v_pk_mul_f32 v[56:57], v[56:57], 0.5 op_sel_hi:[1,0]
	v_pk_mul_f32 v[46:47], v[46:47], 0.5 op_sel_hi:[1,0]
	v_pk_mul_f32 v[48:49], v[48:49], 0.5 op_sel_hi:[1,0]
	v_cvt_pk_fp8_f32 v144, v62, v63
	v_cvt_pk_fp8_f32 v145, v58, v59
	v_cvt_pk_fp8_f32 v146, v54, v55
	v_cvt_pk_fp8_f32 v147, v46, v47
	v_cvt_pk_fp8_f32 v144, v64, v65 op_sel:[0,0,1]
	v_cvt_pk_fp8_f32 v145, v60, v61 op_sel:[0,0,1]
	v_cvt_pk_fp8_f32 v146, v56, v57 op_sel:[0,0,1]
	v_cvt_pk_fp8_f32 v147, v48, v49 op_sel:[0,0,1]
	v_add_u32_e32 v154, 0x20000, v152
	s_nop 0
	global_store_dwordx4 v154, v[144:147], s[68:69]
	s_mov_b32 s100, 1
	v_pk_mul_f32 v[50:51], v[50:51], 0.5 op_sel_hi:[1,0]
	v_pk_mul_f32 v[52:53], v[52:53], 0.5 op_sel_hi:[1,0]
	v_pk_mul_f32 v[42:43], v[42:43], 0.5 op_sel_hi:[1,0]
	v_pk_mul_f32 v[44:45], v[44:45], 0.5 op_sel_hi:[1,0]
	v_pk_mul_f32 v[38:39], v[38:39], 0.5 op_sel_hi:[1,0]
	v_pk_mul_f32 v[40:41], v[40:41], 0.5 op_sel_hi:[1,0]
	v_pk_mul_f32 v[30:31], v[30:31], 0.5 op_sel_hi:[1,0]
	v_pk_mul_f32 v[32:33], v[32:33], 0.5 op_sel_hi:[1,0]
	v_cvt_pk_fp8_f32 v148, v50, v51
	v_cvt_pk_fp8_f32 v149, v42, v43
	v_cvt_pk_fp8_f32 v150, v38, v39
	v_cvt_pk_fp8_f32 v151, v30, v31
	v_cvt_pk_fp8_f32 v148, v52, v53 op_sel:[0,0,1]
	v_cvt_pk_fp8_f32 v149, v44, v45 op_sel:[0,0,1]
	v_cvt_pk_fp8_f32 v150, v40, v41 op_sel:[0,0,1]
	v_cvt_pk_fp8_f32 v151, v32, v33 op_sel:[0,0,1]
	v_add_u32_e32 v155, 0x24000, v152
	s_nop 0
	global_store_dwordx4 v155, v[148:151], s[68:69]
	s_mov_b32 s100, 1
	v_pk_mul_f32 v[34:35], v[34:35], 0.5 op_sel_hi:[1,0]
	v_pk_mul_f32 v[36:37], v[36:37], 0.5 op_sel_hi:[1,0]
	v_pk_mul_f32 v[26:27], v[26:27], 0.5 op_sel_hi:[1,0]
	v_pk_mul_f32 v[28:29], v[28:29], 0.5 op_sel_hi:[1,0]
	v_pk_mul_f32 v[22:23], v[22:23], 0.5 op_sel_hi:[1,0]
	v_pk_mul_f32 v[24:25], v[24:25], 0.5 op_sel_hi:[1,0]
	v_pk_mul_f32 v[14:15], v[14:15], 0.5 op_sel_hi:[1,0]
	v_pk_mul_f32 v[16:17], v[16:17], 0.5 op_sel_hi:[1,0]
	v_cvt_pk_fp8_f32 v144, v34, v35
	v_cvt_pk_fp8_f32 v145, v26, v27
	v_cvt_pk_fp8_f32 v146, v22, v23
	v_cvt_pk_fp8_f32 v147, v14, v15
	v_cvt_pk_fp8_f32 v144, v36, v37 op_sel:[0,0,1]
	v_cvt_pk_fp8_f32 v145, v28, v29 op_sel:[0,0,1]
	v_cvt_pk_fp8_f32 v146, v24, v25 op_sel:[0,0,1]
	v_cvt_pk_fp8_f32 v147, v16, v17 op_sel:[0,0,1]
	v_add_u32_e32 v154, 0x28000, v152
	s_nop 0
	global_store_dwordx4 v154, v[144:147], s[68:69]
	s_mov_b32 s100, 1
	v_pk_mul_f32 v[230:231], v[230:231], 0.5 op_sel_hi:[1,0]
	v_pk_mul_f32 v[232:233], v[232:233], 0.5 op_sel_hi:[1,0]
	v_pk_mul_f32 v[10:11], v[10:11], 0.5 op_sel_hi:[1,0]
	v_pk_mul_f32 v[12:13], v[12:13], 0.5 op_sel_hi:[1,0]
	v_pk_mul_f32 v[6:7], v[6:7], 0.5 op_sel_hi:[1,0]
	v_pk_mul_f32 v[8:9], v[8:9], 0.5 op_sel_hi:[1,0]
	v_pk_mul_f32 v[2:3], v[2:3], 0.5 op_sel_hi:[1,0]
	v_pk_mul_f32 v[4:5], v[4:5], 0.5 op_sel_hi:[1,0]
	v_cvt_pk_fp8_f32 v148, v230, v231
	v_cvt_pk_fp8_f32 v149, v10, v11
	v_cvt_pk_fp8_f32 v150, v6, v7
	v_cvt_pk_fp8_f32 v151, v2, v3
	v_cvt_pk_fp8_f32 v148, v232, v233 op_sel:[0,0,1]
	v_cvt_pk_fp8_f32 v149, v12, v13 op_sel:[0,0,1]
	v_cvt_pk_fp8_f32 v150, v8, v9 op_sel:[0,0,1]
	v_cvt_pk_fp8_f32 v151, v4, v5 op_sel:[0,0,1]
	v_add_u32_e32 v155, 0x2c000, v152
	s_nop 0
	global_store_dwordx4 v155, v[148:151], s[68:69]
	s_mov_b32 s100, 1
	s_and_b64 vcc, exec, s[4:5]
	s_cbranch_vccz .LBB0_1719
	s_waitcnt vmcnt(0)
	s_cmpk_gt_u32 s3, 0xff
	s_cbranch_scc1 .LBB0_1728
	s_barrier

.LBB0_2151:
	ds_read_b128 v[130:133], v195
	ds_read_b128 v[134:137], v195 offset:1024
	ds_read_b128 v[138:141], v195 offset:2048
	ds_read_b128 v[142:145], v195 offset:3072
	s_add_i32 s10, s7, 0xfffa0080
	s_cmp_eq_u32 s13, 12
	s_cselect_b32 s78, s6, s10
	s_cselect_b32 s73, s57, s12
	s_or_b32 s79, s78, 0x80
	s_add_i32 s10, s7, 0xfffe0000
	s_mov_b32 m0, s38
	ds_read_b128 v[146:149], v196
	ds_read_b128 v[150:153], v196 offset:1024
	ds_read_b128 v[154:157], v196 offset:2048
	ds_read_b128 v[158:161], v196 offset:3072
	ds_read_b128 v[162:165], v196 offset:4096
	ds_read_b128 v[166:169], v196 offset:5120
	ds_read_b128 v[170:173], v196 offset:6144
	ds_read_b128 v[174:177], v196 offset:7168
	buffer_load_dwordx4 v1, s[48:51], s10 offen lds
	s_mov_b32 m0, s39
	s_nop 0
	buffer_load_dwordx4 v1, s[48:51], s7 offen lds
	s_waitcnt lgkmcnt(8)
	s_barrier
	s_waitcnt lgkmcnt(0)
	s_setprio 1
	s_waitcnt lgkmcnt(7)
	v_mfma_f32_16x16x32_bf16 v[126:129], v[130:133], v[146:149], v[126:129]
	v_mfma_f32_16x16x32_bf16 v[122:125], v[138:141], v[146:149], v[122:125]
	s_waitcnt lgkmcnt(5)
	v_mfma_f32_16x16x32_bf16 v[110:113], v[130:133], v[154:157], v[110:113]
	v_mfma_f32_16x16x32_bf16 v[106:109], v[138:141], v[154:157], v[106:109]
	s_waitcnt lgkmcnt(3)
	v_mfma_f32_16x16x32_bf16 v[94:97], v[130:133], v[162:165], v[94:97]
	v_mfma_f32_16x16x32_bf16 v[90:93], v[138:141], v[162:165], v[90:93]
	s_waitcnt lgkmcnt(1)
	v_mfma_f32_16x16x32_bf16 v[78:81], v[130:133], v[170:173], v[78:81]
	v_mfma_f32_16x16x32_bf16 v[74:77], v[138:141], v[170:173], v[74:77]
	v_mfma_f32_16x16x32_bf16 v[126:129], v[134:137], v[150:153], v[126:129]
	v_mfma_f32_16x16x32_bf16 v[122:125], v[142:145], v[150:153], v[122:125]
	v_mfma_f32_16x16x32_bf16 v[110:113], v[134:137], v[158:161], v[110:113]
	v_mfma_f32_16x16x32_bf16 v[106:109], v[142:145], v[158:161], v[106:109]
	v_mfma_f32_16x16x32_bf16 v[94:97], v[134:137], v[166:169], v[94:97]
	v_mfma_f32_16x16x32_bf16 v[90:93], v[142:145], v[166:169], v[90:93]
	s_waitcnt lgkmcnt(0)
	v_mfma_f32_16x16x32_bf16 v[78:81], v[134:137], v[174:177], v[78:81]
	v_mfma_f32_16x16x32_bf16 v[74:77], v[142:145], v[174:177], v[74:77]
	s_setprio 0
	s_barrier
	s_mov_b32 m0, s16
	s_mov_b32 s10, s50
	s_mov_b32 s11, s51
	ds_read_b128 v[178:181], v197
	ds_read_b128 v[182:185], v197 offset:1024
	ds_read_b128 v[200:203], v197 offset:2048
	ds_read_b128 v[204:207], v197 offset:3072
	buffer_load_dwordx4 v192, s[8:11], s73 offen lds
	s_add_i32 s33, s73, 0x20000
	s_mov_b32 m0, s17
	s_nop 0
	buffer_load_dwordx4 v192, s[8:11], s33 offen lds
	s_barrier
	s_waitcnt lgkmcnt(0)
	s_setprio 1
	s_waitcnt lgkmcnt(3)
	v_mfma_f32_16x16x32_bf16 v[118:121], v[178:181], v[146:149], v[118:121]
	s_waitcnt lgkmcnt(1)
	v_mfma_f32_16x16x32_bf16 v[114:117], v[200:203], v[146:149], v[114:117]
	v_mfma_f32_16x16x32_bf16 v[102:105], v[178:181], v[154:157], v[102:105]
	v_mfma_f32_16x16x32_bf16 v[98:101], v[200:203], v[154:157], v[98:101]
	v_mfma_f32_16x16x32_bf16 v[86:89], v[178:181], v[162:165], v[86:89]
	v_mfma_f32_16x16x32_bf16 v[82:85], v[200:203], v[162:165], v[82:85]
	v_mfma_f32_16x16x32_bf16 v[70:73], v[178:181], v[170:173], v[70:73]
	v_mfma_f32_16x16x32_bf16 v[66:69], v[200:203], v[170:173], v[66:69]
	v_mfma_f32_16x16x32_bf16 v[118:121], v[182:185], v[150:153], v[118:121]
	s_waitcnt lgkmcnt(0)
	v_mfma_f32_16x16x32_bf16 v[114:117], v[204:207], v[150:153], v[114:117]
	v_mfma_f32_16x16x32_bf16 v[102:105], v[182:185], v[158:161], v[102:105]
	v_mfma_f32_16x16x32_bf16 v[98:101], v[204:207], v[158:161], v[98:101]
	v_mfma_f32_16x16x32_bf16 v[86:89], v[182:185], v[166:169], v[86:89]
	v_mfma_f32_16x16x32_bf16 v[82:85], v[204:207], v[166:169], v[82:85]
	v_mfma_f32_16x16x32_bf16 v[70:73], v[182:185], v[174:177], v[70:73]
	v_mfma_f32_16x16x32_bf16 v[66:69], v[204:207], v[174:177], v[66:69]
	s_setprio 0
	s_mov_b32 m0, s15
	s_barrier
	ds_read_b128 v[146:149], v196 offset:16384
	ds_read_b128 v[150:153], v196 offset:17408
	ds_read_b128 v[154:157], v196 offset:18432
	ds_read_b128 v[158:161], v196 offset:19456
	ds_read_b128 v[162:165], v196 offset:20480
	ds_read_b128 v[166:169], v196 offset:21504
	ds_read_b128 v[170:173], v196 offset:22528
	ds_read_b128 v[174:177], v196 offset:23552
	buffer_load_dwordx4 v1, s[48:51], s78 offen lds
	s_add_i32 s33, s78, 0x20000
	s_mov_b32 m0, s18
	s_nop 0
	buffer_load_dwordx4 v1, s[48:51], s33 offen lds
	s_barrier
	s_waitcnt lgkmcnt(0)
	s_setprio 1
	s_waitcnt lgkmcnt(7)
	v_mfma_f32_16x16x32_bf16 v[62:65], v[130:133], v[146:149], v[62:65]
	v_mfma_f32_16x16x32_bf16 v[58:61], v[138:141], v[146:149], v[58:61]
	s_waitcnt lgkmcnt(5)
	v_mfma_f32_16x16x32_bf16 v[46:49], v[130:133], v[154:157], v[46:49]
	v_mfma_f32_16x16x32_bf16 v[42:45], v[138:141], v[154:157], v[42:45]
	s_waitcnt lgkmcnt(3)
	v_mfma_f32_16x16x32_bf16 v[30:33], v[130:133], v[162:165], v[30:33]
	v_mfma_f32_16x16x32_bf16 v[26:29], v[138:141], v[162:165], v[26:29]
	s_waitcnt lgkmcnt(1)
	v_mfma_f32_16x16x32_bf16 v[14:17], v[130:133], v[170:173], v[14:17]
	v_mfma_f32_16x16x32_bf16 v[10:13], v[138:141], v[170:173], v[10:13]
	v_mfma_f32_16x16x32_bf16 v[62:65], v[134:137], v[150:153], v[62:65]
	v_mfma_f32_16x16x32_bf16 v[58:61], v[142:145], v[150:153], v[58:61]
	v_mfma_f32_16x16x32_bf16 v[46:49], v[134:137], v[158:161], v[46:49]
	v_mfma_f32_16x16x32_bf16 v[42:45], v[142:145], v[158:161], v[42:45]
	v_mfma_f32_16x16x32_bf16 v[30:33], v[134:137], v[166:169], v[30:33]
	v_mfma_f32_16x16x32_bf16 v[26:29], v[142:145], v[166:169], v[26:29]
	s_waitcnt lgkmcnt(0)
	v_mfma_f32_16x16x32_bf16 v[14:17], v[134:137], v[174:177], v[14:17]
	v_mfma_f32_16x16x32_bf16 v[10:13], v[142:145], v[174:177], v[10:13]
	s_setprio 0
	s_barrier
	s_mov_b32 m0, s19
	s_add_i32 s33, s73, 0x40000
	buffer_load_dwordx4 v192, s[8:11], s33 offen lds
	s_add_i32 s33, s73, 0x60000
	s_mov_b32 m0, s20
	s_nop 0
	buffer_load_dwordx4 v192, s[8:11], s33 offen lds
	s_waitcnt vmcnt(6)
	s_barrier
	s_setprio 1
	v_mfma_f32_16x16x32_bf16 v[54:57], v[178:181], v[146:149], v[54:57]
	v_mfma_f32_16x16x32_bf16 v[50:53], v[200:203], v[146:149], v[50:53]
	v_mfma_f32_16x16x32_bf16 v[38:41], v[178:181], v[154:157], v[38:41]
	v_mfma_f32_16x16x32_bf16 v[34:37], v[200:203], v[154:157], v[34:37]
	v_mfma_f32_16x16x32_bf16 v[22:25], v[178:181], v[162:165], v[22:25]
	v_mfma_f32_16x16x32_bf16 v[18:21], v[200:203], v[162:165], v[18:21]
	v_mfma_f32_16x16x32_bf16 v[6:9], v[178:181], v[170:173], v[6:9]
	v_mfma_f32_16x16x32_bf16 v[2:5], v[200:203], v[170:173], v[2:5]
	v_mfma_f32_16x16x32_bf16 v[54:57], v[182:185], v[150:153], v[54:57]
	v_mfma_f32_16x16x32_bf16 v[50:53], v[204:207], v[150:153], v[50:53]
	v_mfma_f32_16x16x32_bf16 v[38:41], v[182:185], v[158:161], v[38:41]
	v_mfma_f32_16x16x32_bf16 v[34:37], v[204:207], v[158:161], v[34:37]
	v_mfma_f32_16x16x32_bf16 v[22:25], v[182:185], v[166:169], v[22:25]
	v_mfma_f32_16x16x32_bf16 v[18:21], v[204:207], v[166:169], v[18:21]
	v_mfma_f32_16x16x32_bf16 v[6:9], v[182:185], v[174:177], v[6:9]
	v_mfma_f32_16x16x32_bf16 v[2:5], v[204:207], v[174:177], v[2:5]
	s_setprio 0
	s_barrier
	ds_read_b128 v[130:133], v198
	ds_read_b128 v[134:137], v198 offset:1024
	ds_read_b128 v[138:141], v198 offset:2048
	ds_read_b128 v[142:145], v198 offset:3072
	s_mov_b32 m0, s21
	s_add_i32 s33, s78, 0x40000
	ds_read_b128 v[146:149], v196 offset:32768
	ds_read_b128 v[150:153], v196 offset:33792
	ds_read_b128 v[154:157], v196 offset:34816
	ds_read_b128 v[158:161], v196 offset:35840
	ds_read_b128 v[162:165], v196 offset:36864
	ds_read_b128 v[166:169], v196 offset:37888
	ds_read_b128 v[170:173], v196 offset:38912
	ds_read_b128 v[174:177], v196 offset:39936
	buffer_load_dwordx4 v1, s[48:51], s33 offen lds
	s_add_i32 s33, s78, 0x60000
	s_mov_b32 m0, s22
	s_nop 0
	buffer_load_dwordx4 v1, s[48:51], s33 offen lds
	s_waitcnt lgkmcnt(8)
	s_barrier
	s_waitcnt lgkmcnt(0)
	s_setprio 1
	s_waitcnt lgkmcnt(7)
	v_mfma_f32_16x16x32_bf16 v[126:129], v[130:133], v[146:149], v[126:129]
	v_mfma_f32_16x16x32_bf16 v[122:125], v[138:141], v[146:149], v[122:125]
	s_waitcnt lgkmcnt(5)
	v_mfma_f32_16x16x32_bf16 v[110:113], v[130:133], v[154:157], v[110:113]
	v_mfma_f32_16x16x32_bf16 v[106:109], v[138:141], v[154:157], v[106:109]
	s_waitcnt lgkmcnt(3)
	v_mfma_f32_16x16x32_bf16 v[94:97], v[130:133], v[162:165], v[94:97]
	v_mfma_f32_16x16x32_bf16 v[90:93], v[138:141], v[162:165], v[90:93]
	s_waitcnt lgkmcnt(1)
	v_mfma_f32_16x16x32_bf16 v[78:81], v[130:133], v[170:173], v[78:81]
	v_mfma_f32_16x16x32_bf16 v[74:77], v[138:141], v[170:173], v[74:77]
	v_mfma_f32_16x16x32_bf16 v[126:129], v[134:137], v[150:153], v[126:129]
	v_mfma_f32_16x16x32_bf16 v[122:125], v[142:145], v[150:153], v[122:125]
	v_mfma_f32_16x16x32_bf16 v[110:113], v[134:137], v[158:161], v[110:113]
	v_mfma_f32_16x16x32_bf16 v[106:109], v[142:145], v[158:161], v[106:109]
	v_mfma_f32_16x16x32_bf16 v[94:97], v[134:137], v[166:169], v[94:97]
	v_mfma_f32_16x16x32_bf16 v[90:93], v[142:145], v[166:169], v[90:93]
	s_waitcnt lgkmcnt(0)
	v_mfma_f32_16x16x32_bf16 v[78:81], v[134:137], v[174:177], v[78:81]
	v_mfma_f32_16x16x32_bf16 v[74:77], v[142:145], v[174:177], v[74:77]
	s_setprio 0
	s_barrier
	s_mov_b32 m0, s28
	s_add_i32 s33, s73, 0x80
	ds_read_b128 v[178:181], v199
	ds_read_b128 v[182:185], v199 offset:1024
	ds_read_b128 v[200:203], v199 offset:2048
	ds_read_b128 v[204:207], v199 offset:3072
	buffer_load_dwordx4 v192, s[8:11], s33 offen lds
	s_add_i32 s33, s73, 0x20080
	s_mov_b32 m0, s29
	s_nop 0
	buffer_load_dwordx4 v192, s[8:11], s33 offen lds
	s_waitcnt vmcnt(10)
	s_barrier
	s_waitcnt lgkmcnt(0)
	s_setprio 1
	s_waitcnt lgkmcnt(3)
	v_mfma_f32_16x16x32_bf16 v[118:121], v[178:181], v[146:149], v[118:121]
	s_waitcnt lgkmcnt(1)
	v_mfma_f32_16x16x32_bf16 v[114:117], v[200:203], v[146:149], v[114:117]
	v_mfma_f32_16x16x32_bf16 v[102:105], v[178:181], v[154:157], v[102:105]
	v_mfma_f32_16x16x32_bf16 v[98:101], v[200:203], v[154:157], v[98:101]
	v_mfma_f32_16x16x32_bf16 v[86:89], v[178:181], v[162:165], v[86:89]
	v_mfma_f32_16x16x32_bf16 v[82:85], v[200:203], v[162:165], v[82:85]
	v_mfma_f32_16x16x32_bf16 v[70:73], v[178:181], v[170:173], v[70:73]
	v_mfma_f32_16x16x32_bf16 v[66:69], v[200:203], v[170:173], v[66:69]
	v_mfma_f32_16x16x32_bf16 v[118:121], v[182:185], v[150:153], v[118:121]
	s_waitcnt lgkmcnt(0)
	v_mfma_f32_16x16x32_bf16 v[114:117], v[204:207], v[150:153], v[114:117]
	v_mfma_f32_16x16x32_bf16 v[102:105], v[182:185], v[158:161], v[102:105]
	v_mfma_f32_16x16x32_bf16 v[98:101], v[204:207], v[158:161], v[98:101]
	v_mfma_f32_16x16x32_bf16 v[86:89], v[182:185], v[166:169], v[86:89]
	v_mfma_f32_16x16x32_bf16 v[82:85], v[204:207], v[166:169], v[82:85]
	v_mfma_f32_16x16x32_bf16 v[70:73], v[182:185], v[174:177], v[70:73]
	v_mfma_f32_16x16x32_bf16 v[66:69], v[204:207], v[174:177], v[66:69]
	s_setprio 0
	s_mov_b32 m0, s30
	s_barrier
	ds_read_b128 v[146:149], v196 offset:49152
	ds_read_b128 v[150:153], v196 offset:50176
	ds_read_b128 v[154:157], v196 offset:51200
	ds_read_b128 v[158:161], v196 offset:52224
	ds_read_b128 v[162:165], v196 offset:53248
	ds_read_b128 v[166:169], v196 offset:54272
	ds_read_b128 v[170:173], v196 offset:55296
	ds_read_b128 v[174:177], v196 offset:56320
	buffer_load_dwordx4 v1, s[48:51], s79 offen lds
	s_add_i32 s78, s78, 0x20080
	s_mov_b32 m0, s31
	s_nop 0
	buffer_load_dwordx4 v1, s[48:51], s78 offen lds
	s_barrier
	s_waitcnt lgkmcnt(0)
	s_setprio 1
	s_waitcnt lgkmcnt(7)
	v_mfma_f32_16x16x32_bf16 v[62:65], v[130:133], v[146:149], v[62:65]
	v_mfma_f32_16x16x32_bf16 v[58:61], v[138:141], v[146:149], v[58:61]
	s_waitcnt lgkmcnt(5)
	v_mfma_f32_16x16x32_bf16 v[46:49], v[130:133], v[154:157], v[46:49]
	v_mfma_f32_16x16x32_bf16 v[42:45], v[138:141], v[154:157], v[42:45]
	s_waitcnt lgkmcnt(3)
	v_mfma_f32_16x16x32_bf16 v[30:33], v[130:133], v[162:165], v[30:33]
	v_mfma_f32_16x16x32_bf16 v[26:29], v[138:141], v[162:165], v[26:29]
	s_waitcnt lgkmcnt(1)
	v_mfma_f32_16x16x32_bf16 v[14:17], v[130:133], v[170:173], v[14:17]
	v_mfma_f32_16x16x32_bf16 v[10:13], v[138:141], v[170:173], v[10:13]
	v_mfma_f32_16x16x32_bf16 v[62:65], v[134:137], v[150:153], v[62:65]
	v_mfma_f32_16x16x32_bf16 v[58:61], v[142:145], v[150:153], v[58:61]
	v_mfma_f32_16x16x32_bf16 v[46:49], v[134:137], v[158:161], v[46:49]
	v_mfma_f32_16x16x32_bf16 v[42:45], v[142:145], v[158:161], v[42:45]
	v_mfma_f32_16x16x32_bf16 v[30:33], v[134:137], v[166:169], v[30:33]
	v_mfma_f32_16x16x32_bf16 v[26:29], v[142:145], v[166:169], v[26:29]
	s_waitcnt lgkmcnt(0)
	v_mfma_f32_16x16x32_bf16 v[14:17], v[134:137], v[174:177], v[14:17]
	v_mfma_f32_16x16x32_bf16 v[10:13], v[142:145], v[174:177], v[10:13]
	s_setprio 0
	s_barrier
	s_mov_b32 m0, s34
	s_add_i32 s33, s73, 0x40080
	buffer_load_dwordx4 v192, s[8:11], s33 offen lds
	s_add_i32 s73, s73, 0x60080
	s_mov_b32 m0, s35
	s_nop 0
	buffer_load_dwordx4 v192, s[8:11], s73 offen lds
	s_waitcnt vmcnt(6)
	s_barrier
	s_setprio 1
	v_mfma_f32_16x16x32_bf16 v[54:57], v[178:181], v[146:149], v[54:57]
	v_mfma_f32_16x16x32_bf16 v[50:53], v[200:203], v[146:149], v[50:53]
	v_mfma_f32_16x16x32_bf16 v[38:41], v[178:181], v[154:157], v[38:41]
	v_mfma_f32_16x16x32_bf16 v[34:37], v[200:203], v[154:157], v[34:37]
	v_mfma_f32_16x16x32_bf16 v[22:25], v[178:181], v[162:165], v[22:25]
	v_mfma_f32_16x16x32_bf16 v[18:21], v[200:203], v[162:165], v[18:21]
	v_mfma_f32_16x16x32_bf16 v[6:9], v[178:181], v[170:173], v[6:9]
	v_mfma_f32_16x16x32_bf16 v[2:5], v[200:203], v[170:173], v[2:5]
	v_mfma_f32_16x16x32_bf16 v[54:57], v[182:185], v[150:153], v[54:57]
	v_mfma_f32_16x16x32_bf16 v[50:53], v[204:207], v[150:153], v[50:53]
	v_mfma_f32_16x16x32_bf16 v[38:41], v[182:185], v[158:161], v[38:41]
	v_mfma_f32_16x16x32_bf16 v[34:37], v[204:207], v[158:161], v[34:37]
	v_mfma_f32_16x16x32_bf16 v[22:25], v[182:185], v[166:169], v[22:25]
	v_mfma_f32_16x16x32_bf16 v[18:21], v[204:207], v[166:169], v[18:21]
	v_mfma_f32_16x16x32_bf16 v[6:9], v[182:185], v[174:177], v[6:9]
	v_mfma_f32_16x16x32_bf16 v[2:5], v[204:207], v[174:177], v[2:5]
	s_setprio 0
	s_add_i32 s13, s13, 2
	s_addk_i32 s7, 0x100
	s_addk_i32 s12, 0x100
	s_cmp_gt_u32 s13, 13
	s_barrier
	s_cbranch_scc0 .LBB0_2151
	s_cmpk_gt_i32 s59, 0x7f
	s_cselect_b64 s[6:7], -1, 0
	s_and_b64 vcc, exec, s[6:7]
	s_cbranch_vccz .LBB0_2140
	s_mov_b64 s[10:11], 0xc000
	s_mov_b64 s[12:13], 0xcb00000
	s_branch .LBB0_2141

.LBB0_2435:
	s_and_b64 s[14:15], s[6:7], exec
	s_cselect_b32 s58, 0, s9
	s_add_i32 s14, s49, s9
	s_or_b32 s57, s58, 0x80
	s_waitcnt lgkmcnt(8)
	s_barrier
	s_waitcnt lgkmcnt(0)
	s_and_b64 s[6:7], s[6:7], exec
	s_cselect_b32 s6, s45, s14
	s_add_i32 s7, s6, 0x80
	s_setprio 1
	s_waitcnt lgkmcnt(6)
	v_mfma_f32_16x16x128_f8f6f4 v[174:177], v[2:9], v[42:49], v[174:177]
	v_mfma_f32_16x16x128_f8f6f4 v[166:169], v[10:17], v[42:49], v[166:169]
	s_waitcnt lgkmcnt(4)
	v_mfma_f32_16x16x128_f8f6f4 v[158:161], v[2:9], v[34:41], v[158:161]
	v_mfma_f32_16x16x128_f8f6f4 v[150:153], v[10:17], v[34:41], v[150:153]
	s_waitcnt lgkmcnt(2)
	v_mfma_f32_16x16x128_f8f6f4 v[142:145], v[2:9], v[26:33], v[142:145]
	v_mfma_f32_16x16x128_f8f6f4 v[134:137], v[10:17], v[26:33], v[134:137]
	s_waitcnt lgkmcnt(0)
	v_mfma_f32_16x16x128_f8f6f4 v[126:129], v[2:9], v[18:25], v[126:129]
	v_mfma_f32_16x16x128_f8f6f4 v[118:121], v[10:17], v[18:25], v[118:121]
	s_setprio 0
	s_barrier
	s_mov_b32 m0, s17
	v_add_u32_e32 v210, 0x14000, v189
	s_mov_b32 s14, s42
	s_mov_b32 s15, s43
	ds_read_b128 v[198:201], v210
	ds_read_b128 v[202:205], v210 offset:1024
	ds_read_b128 v[206:209], v210 offset:2048
	ds_read_b128 v[210:213], v210 offset:3072
	buffer_load_dwordx4 v184, s[12:15], s6 offen lds
	s_add_i32 s33, s6, 0x10000
	s_mov_b32 m0, s18
	s_nop 0
	buffer_load_dwordx4 v184, s[12:15], s33 offen lds
	s_barrier
	s_waitcnt lgkmcnt(0)
	s_setprio 1
	s_waitcnt lgkmcnt(2)
	v_mfma_f32_16x16x128_f8f6f4 v[170:173], v[198:205], v[42:49], v[170:173]
	s_waitcnt lgkmcnt(0)
	v_mfma_f32_16x16x128_f8f6f4 v[162:165], v[206:213], v[42:49], v[162:165]
	v_mfma_f32_16x16x128_f8f6f4 v[154:157], v[198:205], v[34:41], v[154:157]
	v_mfma_f32_16x16x128_f8f6f4 v[146:149], v[206:213], v[34:41], v[146:149]
	v_mfma_f32_16x16x128_f8f6f4 v[138:141], v[198:205], v[26:33], v[138:141]
	v_mfma_f32_16x16x128_f8f6f4 v[130:133], v[206:213], v[26:33], v[130:133]
	v_mfma_f32_16x16x128_f8f6f4 v[122:125], v[198:205], v[18:25], v[122:125]
	v_mfma_f32_16x16x128_f8f6f4 v[114:117], v[206:213], v[18:25], v[114:117]
	s_setprio 0
	v_lshlrev_b32_e32 v214, 10, v186
	v_and_b32_e32 v214, 0x3fffc00, v214
	v_lshlrev_b32_e32 v215, 10, v185
	s_mov_b32 m0, s16
	v_add_u32_e32 v214, v214, v1
	v_and_b32_e32 v215, 0x3fffc00, v215
	s_barrier
	ds_read_b128 v[18:21], v191 offset:16384
	ds_read_b128 v[22:25], v191 offset:17408
	ds_read_b128 v[26:29], v191 offset:18432
	ds_read_b128 v[30:33], v191 offset:19456
	ds_read_b128 v[34:37], v191 offset:20480
	ds_read_b128 v[38:41], v191 offset:21504
	ds_read_b128 v[42:45], v191 offset:22528
	ds_read_b128 v[46:49], v191 offset:23552
	buffer_load_dwordx4 v214, s[40:43], s58 offen lds
	v_add_u32_e32 v215, v215, v1
	s_mov_b32 m0, s19
	s_nop 0
	buffer_load_dwordx4 v215, s[40:43], s58 offen lds
	s_barrier
	s_waitcnt lgkmcnt(0)
	s_setprio 1
	s_waitcnt lgkmcnt(6)
	v_mfma_f32_16x16x128_f8f6f4 v[110:113], v[2:9], v[18:25], v[110:113]
	v_mfma_f32_16x16x128_f8f6f4 v[102:105], v[10:17], v[18:25], v[102:105]
	s_waitcnt lgkmcnt(4)
	v_mfma_f32_16x16x128_f8f6f4 v[94:97], v[2:9], v[26:33], v[94:97]
	v_mfma_f32_16x16x128_f8f6f4 v[86:89], v[10:17], v[26:33], v[86:89]
	s_waitcnt lgkmcnt(2)
	v_mfma_f32_16x16x128_f8f6f4 v[78:81], v[2:9], v[34:41], v[78:81]
	v_mfma_f32_16x16x128_f8f6f4 v[70:73], v[10:17], v[34:41], v[70:73]
	s_waitcnt lgkmcnt(0)
	v_mfma_f32_16x16x128_f8f6f4 v[62:65], v[2:9], v[42:49], v[62:65]
	v_mfma_f32_16x16x128_f8f6f4 v[54:57], v[10:17], v[42:49], v[54:57]
	s_setprio 0
	s_barrier
	s_mov_b32 m0, s20
	s_add_i32 s33, s6, 0x20000
	buffer_load_dwordx4 v184, s[12:15], s33 offen lds
	s_add_i32 s33, s6, 0x30000
	s_mov_b32 m0, s21
	s_nop 0
	buffer_load_dwordx4 v184, s[12:15], s33 offen lds
	s_waitcnt vmcnt(6)
	s_barrier
	s_setprio 1
	v_mfma_f32_16x16x128_f8f6f4 v[106:109], v[198:205], v[18:25], v[106:109]
	v_mfma_f32_16x16x128_f8f6f4 v[98:101], v[206:213], v[18:25], v[98:101]
	v_mfma_f32_16x16x128_f8f6f4 v[90:93], v[198:205], v[26:33], v[90:93]
	v_mfma_f32_16x16x128_f8f6f4 v[82:85], v[206:213], v[26:33], v[82:85]
	v_mfma_f32_16x16x128_f8f6f4 v[74:77], v[198:205], v[34:41], v[74:77]
	v_mfma_f32_16x16x128_f8f6f4 v[66:69], v[206:213], v[34:41], v[66:69]
	v_mfma_f32_16x16x128_f8f6f4 v[58:61], v[198:205], v[42:49], v[58:61]
	v_mfma_f32_16x16x128_f8f6f4 v[50:53], v[206:213], v[42:49], v[50:53]
	s_setprio 0
	v_add_u32_e32 v14, 0x18000, v189
	s_barrier
	ds_read_b128 v[2:5], v14
	ds_read_b128 v[6:9], v14 offset:1024
	ds_read_b128 v[10:13], v14 offset:2048
	ds_read_b128 v[14:17], v14 offset:3072
	s_mov_b32 m0, s22
	ds_read_b128 v[18:21], v191 offset:32768
	ds_read_b128 v[22:25], v191 offset:33792
	ds_read_b128 v[26:29], v191 offset:34816
	ds_read_b128 v[30:33], v191 offset:35840
	ds_read_b128 v[34:37], v191 offset:36864
	ds_read_b128 v[38:41], v191 offset:37888
	ds_read_b128 v[42:45], v191 offset:38912
	ds_read_b128 v[46:49], v191 offset:39936
	buffer_load_dwordx4 v196, s[40:43], s58 offen lds
	s_mov_b32 m0, s23
	s_nop 0
	buffer_load_dwordx4 v197, s[40:43], s58 offen lds
	s_waitcnt lgkmcnt(8)
	s_barrier
	s_waitcnt lgkmcnt(0)
	s_setprio 1
	s_waitcnt lgkmcnt(6)
	v_mfma_f32_16x16x128_f8f6f4 v[174:177], v[2:9], v[18:25], v[174:177]
	v_mfma_f32_16x16x128_f8f6f4 v[166:169], v[10:17], v[18:25], v[166:169]
	s_waitcnt lgkmcnt(4)
	v_mfma_f32_16x16x128_f8f6f4 v[158:161], v[2:9], v[26:33], v[158:161]
	v_mfma_f32_16x16x128_f8f6f4 v[150:153], v[10:17], v[26:33], v[150:153]
	s_waitcnt lgkmcnt(2)
	v_mfma_f32_16x16x128_f8f6f4 v[142:145], v[2:9], v[34:41], v[142:145]
	v_mfma_f32_16x16x128_f8f6f4 v[134:137], v[10:17], v[34:41], v[134:137]
	s_waitcnt lgkmcnt(0)
	v_mfma_f32_16x16x128_f8f6f4 v[126:129], v[2:9], v[42:49], v[126:129]
	v_mfma_f32_16x16x128_f8f6f4 v[118:121], v[10:17], v[42:49], v[118:121]
	s_setprio 0
	s_barrier
	s_mov_b32 m0, s25
	v_add_u32_e32 v208, 0x1c000, v189
	ds_read_b128 v[196:199], v208
	ds_read_b128 v[200:203], v208 offset:1024
	ds_read_b128 v[204:207], v208 offset:2048
	ds_read_b128 v[208:211], v208 offset:3072
	buffer_load_dwordx4 v184, s[12:15], s7 offen lds
	s_add_i32 s7, s6, 0x10080
	s_mov_b32 m0, s26
	s_nop 0
	buffer_load_dwordx4 v184, s[12:15], s7 offen lds
	s_waitcnt vmcnt(10)
	s_barrier
	s_waitcnt lgkmcnt(0)
	s_setprio 1
	s_waitcnt lgkmcnt(2)
	v_mfma_f32_16x16x128_f8f6f4 v[170:173], v[196:203], v[18:25], v[170:173]
	s_waitcnt lgkmcnt(0)
	v_mfma_f32_16x16x128_f8f6f4 v[162:165], v[204:211], v[18:25], v[162:165]
	v_mfma_f32_16x16x128_f8f6f4 v[154:157], v[196:203], v[26:33], v[154:157]
	v_mfma_f32_16x16x128_f8f6f4 v[146:149], v[204:211], v[26:33], v[146:149]
	v_mfma_f32_16x16x128_f8f6f4 v[138:141], v[196:203], v[34:41], v[138:141]
	v_mfma_f32_16x16x128_f8f6f4 v[130:133], v[204:211], v[34:41], v[130:133]
	v_mfma_f32_16x16x128_f8f6f4 v[122:125], v[196:203], v[42:49], v[122:125]
	v_mfma_f32_16x16x128_f8f6f4 v[114:117], v[204:211], v[42:49], v[114:117]
	s_setprio 0
	s_mov_b32 m0, s27
	s_barrier
	ds_read_b128 v[18:21], v191 offset:49152
	ds_read_b128 v[22:25], v191 offset:50176
	ds_read_b128 v[26:29], v191 offset:51200
	ds_read_b128 v[30:33], v191 offset:52224
	ds_read_b128 v[34:37], v191 offset:53248
	ds_read_b128 v[38:41], v191 offset:54272
	ds_read_b128 v[42:45], v191 offset:55296
	ds_read_b128 v[46:49], v191 offset:56320
	buffer_load_dwordx4 v214, s[40:43], s57 offen lds
	s_mov_b32 m0, s28
	s_nop 0
	buffer_load_dwordx4 v215, s[40:43], s57 offen lds
	s_barrier
	s_waitcnt lgkmcnt(0)
	s_setprio 1
	s_waitcnt lgkmcnt(6)
	v_mfma_f32_16x16x128_f8f6f4 v[110:113], v[2:9], v[18:25], v[110:113]
	v_mfma_f32_16x16x128_f8f6f4 v[102:105], v[10:17], v[18:25], v[102:105]
	s_waitcnt lgkmcnt(4)
	v_mfma_f32_16x16x128_f8f6f4 v[94:97], v[2:9], v[26:33], v[94:97]
	v_mfma_f32_16x16x128_f8f6f4 v[86:89], v[10:17], v[26:33], v[86:89]
	s_waitcnt lgkmcnt(2)
	v_mfma_f32_16x16x128_f8f6f4 v[78:81], v[2:9], v[34:41], v[78:81]
	v_mfma_f32_16x16x128_f8f6f4 v[70:73], v[10:17], v[34:41], v[70:73]
	s_waitcnt lgkmcnt(0)
	v_mfma_f32_16x16x128_f8f6f4 v[62:65], v[2:9], v[42:49], v[62:65]
	v_mfma_f32_16x16x128_f8f6f4 v[54:57], v[10:17], v[42:49], v[54:57]
	s_setprio 0
	s_barrier
	s_mov_b32 m0, s29
	s_add_i32 s7, s6, 0x20080
	buffer_load_dwordx4 v184, s[12:15], s7 offen lds
	s_add_i32 s6, s6, 0x30080
	s_mov_b32 m0, s30
	s_nop 0
	buffer_load_dwordx4 v184, s[12:15], s6 offen lds
	s_waitcnt vmcnt(6)
	s_barrier
	s_setprio 1
	v_mfma_f32_16x16x128_f8f6f4 v[106:109], v[196:203], v[18:25], v[106:109]
	v_mfma_f32_16x16x128_f8f6f4 v[98:101], v[204:211], v[18:25], v[98:101]
	v_mfma_f32_16x16x128_f8f6f4 v[90:93], v[196:203], v[26:33], v[90:93]
	v_mfma_f32_16x16x128_f8f6f4 v[82:85], v[204:211], v[26:33], v[82:85]
	v_mfma_f32_16x16x128_f8f6f4 v[74:77], v[196:203], v[34:41], v[74:77]
	v_mfma_f32_16x16x128_f8f6f4 v[66:69], v[204:211], v[34:41], v[66:69]
	v_mfma_f32_16x16x128_f8f6f4 v[58:61], v[196:203], v[42:49], v[58:61]
	v_mfma_f32_16x16x128_f8f6f4 v[50:53], v[204:211], v[42:49], v[50:53]
	s_setprio 0
	s_add_i32 s8, s8, 2
	s_addk_i32 s9, 0x100
	s_cmp_gt_u32 s8, 5
	s_barrier
	s_cbranch_scc1 .LBB0_2423

.LBB0_2509:
	ds_read_b128 v[142:145], v137
	ds_read_b128 v[146:149], v137 offset:1024
	ds_read_b128 v[150:153], v137 offset:2048
	ds_read_b128 v[154:157], v137 offset:3072
	s_add_i32 s10, s7, 0xfffd0800
	s_cmp_eq_u32 s84, 4
	s_cselect_b32 s86, s6, s10
	s_cselect_b32 s85, s59, s79
	s_or_b32 s87, s86, 0x800
	s_add_i32 s10, s7, 0xffff0000
	s_mov_b32 m0, s38
	ds_read_b128 v[158:161], v138
	ds_read_b128 v[162:165], v138 offset:1024
	ds_read_b128 v[166:169], v138 offset:2048
	ds_read_b128 v[170:173], v138 offset:3072
	ds_read_b128 v[174:177], v138 offset:4096
	ds_read_b128 v[178:181], v138 offset:5120
	ds_read_b128 v[182:185], v138 offset:6144
	ds_read_b128 v[186:189], v138 offset:7168
	buffer_load_dwordx4 v1, s[44:47], s10 offen lds
	s_mov_b32 m0, s39
	s_nop 0
	buffer_load_dwordx4 v1, s[44:47], s7 offen lds
	s_waitcnt lgkmcnt(8)
	s_barrier
	s_waitcnt lgkmcnt(0)
	s_setprio 1
	s_waitcnt lgkmcnt(4)
	v_mfma_f32_16x16x128_f8f6f4 v[114:117], v[142:149], v[166:173], v[114:117]
	v_mfma_f32_16x16x128_f8f6f4 v[106:109], v[150:157], v[166:173], v[106:109]
	s_waitcnt lgkmcnt(2)
	v_mfma_f32_16x16x128_f8f6f4 v[98:101], v[142:149], v[174:181], v[98:101]
	v_mfma_f32_16x16x128_f8f6f4 v[198:201], v[142:149], v[158:165], v[126:129]
	v_mfma_f32_16x16x128_f8f6f4 v[202:205], v[150:157], v[158:165], v[122:125]
	v_mfma_f32_16x16x128_f8f6f4 v[206:209], v[150:157], v[174:181], v[90:93]
	s_waitcnt lgkmcnt(0)
	v_mfma_f32_16x16x128_f8f6f4 v[210:213], v[142:149], v[182:189], v[82:85]
	v_mfma_f32_16x16x128_f8f6f4 v[214:217], v[150:157], v[182:189], v[74:77]
	s_setprio 0
	s_barrier
	s_mov_b32 m0, s22
	s_mov_b32 s10, s46
	s_mov_b32 s11, s47
	ds_read_b128 v[122:125], v139
	ds_read_b128 v[126:129], v139 offset:1024
	ds_read_b128 v[190:193], v139 offset:2048
	ds_read_b128 v[194:197], v139 offset:3072
	buffer_load_dwordx4 v134, s[8:11], s85 offen lds
	s_add_i32 s33, s85, 0x20000
	s_mov_b32 m0, s23
	s_nop 0
	buffer_load_dwordx4 v134, s[8:11], s33 offen lds
	s_barrier
	s_waitcnt lgkmcnt(0)
	s_setprio 1
	s_waitcnt lgkmcnt(2)
	v_mfma_f32_16x16x128_f8f6f4 v[118:121], v[122:129], v[158:165], v[118:121]
	s_waitcnt lgkmcnt(0)
	v_mfma_f32_16x16x128_f8f6f4 v[110:113], v[190:197], v[158:165], v[110:113]
	v_mfma_f32_16x16x128_f8f6f4 v[102:105], v[122:129], v[166:173], v[102:105]
	v_mfma_f32_16x16x128_f8f6f4 v[158:161], v[190:197], v[166:173], v[94:97]
	v_mfma_f32_16x16x128_f8f6f4 v[162:165], v[122:129], v[174:181], v[86:89]
	v_mfma_f32_16x16x128_f8f6f4 v[166:169], v[190:197], v[174:181], v[78:81]
	v_mfma_f32_16x16x128_f8f6f4 v[170:173], v[122:129], v[182:189], v[70:73]
	v_mfma_f32_16x16x128_f8f6f4 v[174:177], v[190:197], v[182:189], v[18:21]
	s_setprio 0
	s_mov_b32 m0, s21
	s_barrier
	ds_read_b128 v[66:69], v138 offset:16384
	s_nop 1
	ds_read_b128 v[70:73], v138 offset:17408
	ds_read_b128 v[74:77], v138 offset:18432
	ds_read_b128 v[78:81], v138 offset:19456
	ds_read_b128 v[82:85], v138 offset:20480
	ds_read_b128 v[86:89], v138 offset:21504
	ds_read_b128 v[90:93], v138 offset:22528
	ds_read_b128 v[94:97], v138 offset:23552
	buffer_load_dwordx4 v1, s[44:47], s86 offen lds
	s_add_i32 s33, s86, 0x10000
	s_mov_b32 m0, s24
	s_nop 0
	buffer_load_dwordx4 v1, s[44:47], s33 offen lds
	s_barrier
	s_waitcnt lgkmcnt(0)
	s_setprio 1
	s_waitcnt lgkmcnt(6)
	v_mfma_f32_16x16x128_f8f6f4 v[62:65], v[142:149], v[66:73], v[62:65]
	v_mfma_f32_16x16x128_f8f6f4 v[58:61], v[150:157], v[66:73], v[58:61]
	s_waitcnt lgkmcnt(4)
	v_mfma_f32_16x16x128_f8f6f4 v[50:53], v[142:149], v[74:81], v[50:53]
	s_waitcnt lgkmcnt(0)
	v_mfma_f32_16x16x128_f8f6f4 v[230:233], v[142:149], v[90:97], v[230:233]
	v_mfma_f32_16x16x128_f8f6f4 v[218:221], v[150:157], v[74:81], v[42:45]
	v_mfma_f32_16x16x128_f8f6f4 v[222:225], v[142:149], v[82:89], v[34:37]
	v_mfma_f32_16x16x128_f8f6f4 v[226:229], v[150:157], v[82:89], v[26:29]
	v_mfma_f32_16x16x128_f8f6f4 v[234:237], v[150:157], v[90:97], v[10:13]
	s_setprio 0
	s_barrier
	s_mov_b32 m0, s25
	s_add_i32 s33, s85, 0x2000
	buffer_load_dwordx4 v134, s[8:11], s33 offen lds
	s_add_i32 s33, s85, 0x22000
	s_mov_b32 m0, s26
	s_nop 0
	buffer_load_dwordx4 v134, s[8:11], s33 offen lds
	s_waitcnt vmcnt(6)
	s_barrier
	s_setprio 1
	v_mfma_f32_16x16x128_f8f6f4 v[54:57], v[122:129], v[66:73], v[54:57]
	v_mfma_f32_16x16x128_f8f6f4 v[238:241], v[190:197], v[66:73], v[46:49]
	v_mfma_f32_16x16x128_f8f6f4 v[242:245], v[122:129], v[74:81], v[38:41]
	v_mfma_f32_16x16x128_f8f6f4 v[246:249], v[190:197], v[74:81], v[30:33]
	v_mfma_f32_16x16x128_f8f6f4 v[250:253], v[122:129], v[82:89], v[22:25]
	v_mfma_f32_16x16x128_f8f6f4 v[130:133], v[190:197], v[82:89], v[14:17]
	v_mfma_f32_16x16x128_f8f6f4 v[66:69], v[122:129], v[90:97], v[6:9]
	v_mfma_f32_16x16x128_f8f6f4 v[190:193], v[190:197], v[90:97], v[2:5]
	s_setprio 0
	s_barrier
	s_nop 4
	ds_read_b128 v[2:5], v140
	ds_read_b128 v[6:9], v140 offset:1024
	ds_read_b128 v[10:13], v140 offset:2048
	ds_read_b128 v[14:17], v140 offset:3072
	s_mov_b32 m0, s27
	s_add_i32 s33, s86, 0x20000
	ds_read_b128 v[18:21], v138 offset:32768
	ds_read_b128 v[22:25], v138 offset:33792
	ds_read_b128 v[26:29], v138 offset:34816
	ds_read_b128 v[30:33], v138 offset:35840
	ds_read_b128 v[34:37], v138 offset:36864
	ds_read_b128 v[38:41], v138 offset:37888
	ds_read_b128 v[42:45], v138 offset:38912
	ds_read_b128 v[46:49], v138 offset:39936
	buffer_load_dwordx4 v1, s[44:47], s33 offen lds
	s_add_i32 s33, s86, 0x30000
	s_mov_b32 m0, s28
	s_nop 0
	buffer_load_dwordx4 v1, s[44:47], s33 offen lds
	s_waitcnt lgkmcnt(8)
	s_barrier
	s_waitcnt lgkmcnt(0)
	s_setprio 1
	s_waitcnt lgkmcnt(6)
	v_mfma_f32_16x16x128_f8f6f4 v[126:129], v[2:9], v[18:25], v[198:201]
	v_mfma_f32_16x16x128_f8f6f4 v[122:125], v[10:17], v[18:25], v[202:205]
	s_waitcnt lgkmcnt(4)
	v_mfma_f32_16x16x128_f8f6f4 v[114:117], v[2:9], v[26:33], v[114:117]
	v_mfma_f32_16x16x128_f8f6f4 v[106:109], v[10:17], v[26:33], v[106:109]
	s_waitcnt lgkmcnt(2)
	v_mfma_f32_16x16x128_f8f6f4 v[98:101], v[2:9], v[34:41], v[98:101]
	v_mfma_f32_16x16x128_f8f6f4 v[90:93], v[10:17], v[34:41], v[206:209]
	s_waitcnt lgkmcnt(0)
	v_mfma_f32_16x16x128_f8f6f4 v[82:85], v[2:9], v[42:49], v[210:213]
	v_mfma_f32_16x16x128_f8f6f4 v[74:77], v[10:17], v[42:49], v[214:217]
	s_setprio 0
	s_barrier
	s_mov_b32 m0, s30
	s_add_i32 s33, s85, 0x80
	ds_read_b128 v[142:145], v141
	ds_read_b128 v[146:149], v141 offset:1024
	ds_read_b128 v[150:153], v141 offset:2048
	ds_read_b128 v[154:157], v141 offset:3072
	buffer_load_dwordx4 v134, s[8:11], s33 offen lds
	s_add_i32 s33, s85, 0x20080
	s_mov_b32 m0, s31
	s_nop 0
	buffer_load_dwordx4 v134, s[8:11], s33 offen lds
	s_waitcnt vmcnt(10)
	s_barrier
	s_waitcnt lgkmcnt(0)
	s_setprio 1
	s_waitcnt lgkmcnt(2)
	v_mfma_f32_16x16x128_f8f6f4 v[118:121], v[142:149], v[18:25], v[118:121]
	s_waitcnt lgkmcnt(0)
	v_mfma_f32_16x16x128_f8f6f4 v[110:113], v[150:157], v[18:25], v[110:113]
	v_mfma_f32_16x16x128_f8f6f4 v[102:105], v[142:149], v[26:33], v[102:105]
	v_mfma_f32_16x16x128_f8f6f4 v[94:97], v[150:157], v[26:33], v[158:161]
	v_mfma_f32_16x16x128_f8f6f4 v[86:89], v[142:149], v[34:41], v[162:165]
	v_mfma_f32_16x16x128_f8f6f4 v[78:81], v[150:157], v[34:41], v[166:169]
	v_mfma_f32_16x16x128_f8f6f4 v[70:73], v[142:149], v[42:49], v[170:173]
	v_mfma_f32_16x16x128_f8f6f4 v[18:21], v[150:157], v[42:49], v[174:177]
	s_setprio 0
	s_mov_b32 m0, s34
	s_barrier
	ds_read_b128 v[158:161], v138 offset:49152
	ds_read_b128 v[162:165], v138 offset:50176
	ds_read_b128 v[166:169], v138 offset:51200
	ds_read_b128 v[170:173], v138 offset:52224
	ds_read_b128 v[174:177], v138 offset:53248
	ds_read_b128 v[178:181], v138 offset:54272
	ds_read_b128 v[182:185], v138 offset:55296
	ds_read_b128 v[186:189], v138 offset:56320
	buffer_load_dwordx4 v1, s[44:47], s87 offen lds
	s_add_i32 s86, s86, 0x10800
	s_mov_b32 m0, s35
	s_nop 0
	buffer_load_dwordx4 v1, s[44:47], s86 offen lds
	s_barrier
	s_waitcnt lgkmcnt(0)
	s_setprio 1
	s_waitcnt lgkmcnt(6)
	v_mfma_f32_16x16x128_f8f6f4 v[62:65], v[2:9], v[158:165], v[62:65]
	v_mfma_f32_16x16x128_f8f6f4 v[58:61], v[10:17], v[158:165], v[58:61]
	s_waitcnt lgkmcnt(4)
	v_mfma_f32_16x16x128_f8f6f4 v[50:53], v[2:9], v[166:173], v[50:53]
	v_mfma_f32_16x16x128_f8f6f4 v[42:45], v[10:17], v[166:173], v[218:221]
	s_waitcnt lgkmcnt(2)
	v_mfma_f32_16x16x128_f8f6f4 v[34:37], v[2:9], v[174:181], v[222:225]
	v_mfma_f32_16x16x128_f8f6f4 v[26:29], v[10:17], v[174:181], v[226:229]
	s_waitcnt lgkmcnt(0)
	v_mfma_f32_16x16x128_f8f6f4 v[230:233], v[2:9], v[182:189], v[230:233]
	v_mfma_f32_16x16x128_f8f6f4 v[10:13], v[10:17], v[182:189], v[234:237]
	s_setprio 0
	s_barrier
	s_mov_b32 m0, s36
	s_add_i32 s33, s85, 0x2080
	buffer_load_dwordx4 v134, s[8:11], s33 offen lds
	s_add_i32 s85, s85, 0x22080
	s_mov_b32 m0, s37
	s_nop 0
	buffer_load_dwordx4 v134, s[8:11], s85 offen lds
	s_waitcnt vmcnt(6)
	s_barrier
	s_setprio 1
	v_mfma_f32_16x16x128_f8f6f4 v[54:57], v[142:149], v[158:165], v[54:57]
	v_mfma_f32_16x16x128_f8f6f4 v[46:49], v[150:157], v[158:165], v[238:241]
	v_mfma_f32_16x16x128_f8f6f4 v[38:41], v[142:149], v[166:173], v[242:245]
	v_mfma_f32_16x16x128_f8f6f4 v[30:33], v[150:157], v[166:173], v[246:249]
	v_mfma_f32_16x16x128_f8f6f4 v[22:25], v[142:149], v[174:181], v[250:253]
	v_mfma_f32_16x16x128_f8f6f4 v[14:17], v[150:157], v[174:181], v[130:133]
	v_mfma_f32_16x16x128_f8f6f4 v[6:9], v[142:149], v[182:189], v[66:69]
	v_mfma_f32_16x16x128_f8f6f4 v[2:5], v[150:157], v[182:189], v[190:193]
	s_setprio 0
	s_add_i32 s84, s84, 2
	s_addk_i32 s7, 0x1000
	s_addk_i32 s79, 0x100
	s_cmp_gt_u32 s84, 5
	s_barrier
	s_cbranch_scc0 .LBB0_2509
	v_lshl_add_u32 v152, s78, 8, v135
	v_lshlrev_b32_e32 v153, 1, v136
	v_lshl_or_b32 v153, s73, 8, v153
	v_lshl_add_u32 v152, v152, 10, v153
	s_mov_b32 s73, s57
	s_mov_b32 s78, s58
	s_mov_b32 s79, s59
	s_mov_b32 s84, s72
	v_pk_mul_f32 v[126:127], v[126:127], 0.5 op_sel_hi:[1,0]
	v_pk_mul_f32 v[128:129], v[128:129], 0.5 op_sel_hi:[1,0]
	v_pk_mul_f32 v[122:123], v[122:123], 0.5 op_sel_hi:[1,0]
	v_pk_mul_f32 v[124:125], v[124:125], 0.5 op_sel_hi:[1,0]
	v_pk_mul_f32 v[118:119], v[118:119], 0.5 op_sel_hi:[1,0]
	v_pk_mul_f32 v[120:121], v[120:121], 0.5 op_sel_hi:[1,0]
	v_pk_mul_f32 v[110:111], v[110:111], 0.5 op_sel_hi:[1,0]
	v_pk_mul_f32 v[112:113], v[112:113], 0.5 op_sel_hi:[1,0]
	v_cvt_pk_fp8_f32 v144, v126, v127
	v_cvt_pk_fp8_f32 v145, v122, v123
	v_cvt_pk_fp8_f32 v146, v118, v119
	v_cvt_pk_fp8_f32 v147, v110, v111
	v_cvt_pk_fp8_f32 v144, v128, v129 op_sel:[0,0,1]
	v_cvt_pk_fp8_f32 v145, v124, v125 op_sel:[0,0,1]
	v_cvt_pk_fp8_f32 v146, v120, v121 op_sel:[0,0,1]
	v_cvt_pk_fp8_f32 v147, v112, v113 op_sel:[0,0,1]
	v_mov_b32_e32 v154, v152
	s_nop 0
	global_store_dwordx4 v154, v[144:147], s[68:69]
	s_mov_b32 s100, 1
	v_pk_mul_f32 v[114:115], v[114:115], 0.5 op_sel_hi:[1,0]
	v_pk_mul_f32 v[116:117], v[116:117], 0.5 op_sel_hi:[1,0]
	v_pk_mul_f32 v[106:107], v[106:107], 0.5 op_sel_hi:[1,0]
	v_pk_mul_f32 v[108:109], v[108:109], 0.5 op_sel_hi:[1,0]
	v_pk_mul_f32 v[102:103], v[102:103], 0.5 op_sel_hi:[1,0]
	v_pk_mul_f32 v[104:105], v[104:105], 0.5 op_sel_hi:[1,0]
	v_pk_mul_f32 v[94:95], v[94:95], 0.5 op_sel_hi:[1,0]
	v_pk_mul_f32 v[96:97], v[96:97], 0.5 op_sel_hi:[1,0]
	v_cvt_pk_fp8_f32 v148, v114, v115
	v_cvt_pk_fp8_f32 v149, v106, v107
	v_cvt_pk_fp8_f32 v150, v102, v103
	v_cvt_pk_fp8_f32 v151, v94, v95
	v_cvt_pk_fp8_f32 v148, v116, v117 op_sel:[0,0,1]
	v_cvt_pk_fp8_f32 v149, v108, v109 op_sel:[0,0,1]
	v_cvt_pk_fp8_f32 v150, v104, v105 op_sel:[0,0,1]
	v_cvt_pk_fp8_f32 v151, v96, v97 op_sel:[0,0,1]
	v_add_u32_e32 v155, 0x4000, v152
	s_nop 0
	global_store_dwordx4 v155, v[148:151], s[68:69]
	s_mov_b32 s100, 1
	v_pk_mul_f32 v[98:99], v[98:99], 0.5 op_sel_hi:[1,0]
	v_pk_mul_f32 v[100:101], v[100:101], 0.5 op_sel_hi:[1,0]
	v_pk_mul_f32 v[90:91], v[90:91], 0.5 op_sel_hi:[1,0]
	v_pk_mul_f32 v[92:93], v[92:93], 0.5 op_sel_hi:[1,0]
	v_pk_mul_f32 v[86:87], v[86:87], 0.5 op_sel_hi:[1,0]
	v_pk_mul_f32 v[88:89], v[88:89], 0.5 op_sel_hi:[1,0]
	v_pk_mul_f32 v[78:79], v[78:79], 0.5 op_sel_hi:[1,0]
	v_pk_mul_f32 v[80:81], v[80:81], 0.5 op_sel_hi:[1,0]
	v_cvt_pk_fp8_f32 v144, v98, v99
	v_cvt_pk_fp8_f32 v145, v90, v91
	v_cvt_pk_fp8_f32 v146, v86, v87
	v_cvt_pk_fp8_f32 v147, v78, v79
	v_cvt_pk_fp8_f32 v144, v100, v101 op_sel:[0,0,1]
	v_cvt_pk_fp8_f32 v145, v92, v93 op_sel:[0,0,1]
	v_cvt_pk_fp8_f32 v146, v88, v89 op_sel:[0,0,1]
	v_cvt_pk_fp8_f32 v147, v80, v81 op_sel:[0,0,1]
	v_add_u32_e32 v154, 0x8000, v152
	s_nop 0
	global_store_dwordx4 v154, v[144:147], s[68:69]
	s_mov_b32 s100, 1
	v_pk_mul_f32 v[82:83], v[82:83], 0.5 op_sel_hi:[1,0]
	v_pk_mul_f32 v[84:85], v[84:85], 0.5 op_sel_hi:[1,0]
	v_pk_mul_f32 v[74:75], v[74:75], 0.5 op_sel_hi:[1,0]
	v_pk_mul_f32 v[76:77], v[76:77], 0.5 op_sel_hi:[1,0]
	v_pk_mul_f32 v[70:71], v[70:71], 0.5 op_sel_hi:[1,0]
	v_pk_mul_f32 v[72:73], v[72:73], 0.5 op_sel_hi:[1,0]
	v_pk_mul_f32 v[18:19], v[18:19], 0.5 op_sel_hi:[1,0]
	v_pk_mul_f32 v[20:21], v[20:21], 0.5 op_sel_hi:[1,0]
	v_cvt_pk_fp8_f32 v148, v82, v83
	v_cvt_pk_fp8_f32 v149, v74, v75
	v_cvt_pk_fp8_f32 v150, v70, v71
	v_cvt_pk_fp8_f32 v151, v18, v19
	v_cvt_pk_fp8_f32 v148, v84, v85 op_sel:[0,0,1]
	v_cvt_pk_fp8_f32 v149, v76, v77 op_sel:[0,0,1]
	v_cvt_pk_fp8_f32 v150, v72, v73 op_sel:[0,0,1]
	v_cvt_pk_fp8_f32 v151, v20, v21 op_sel:[0,0,1]
	v_add_u32_e32 v155, 0xc000, v152
	s_nop 0
	global_store_dwordx4 v155, v[148:151], s[68:69]
	s_mov_b32 s100, 1
	v_pk_mul_f32 v[62:63], v[62:63], 0.5 op_sel_hi:[1,0]
	v_pk_mul_f32 v[64:65], v[64:65], 0.5 op_sel_hi:[1,0]
	v_pk_mul_f32 v[58:59], v[58:59], 0.5 op_sel_hi:[1,0]
	v_pk_mul_f32 v[60:61], v[60:61], 0.5 op_sel_hi:[1,0]
	v_pk_mul_f32 v[54:55], v[54:55], 0.5 op_sel_hi:[1,0]
	v_pk_mul_f32 v[56:57], v[56:57], 0.5 op_sel_hi:[1,0]
	v_pk_mul_f32 v[46:47], v[46:47], 0.5 op_sel_hi:[1,0]
	v_pk_mul_f32 v[48:49], v[48:49], 0.5 op_sel_hi:[1,0]
	v_cvt_pk_fp8_f32 v144, v62, v63
	v_cvt_pk_fp8_f32 v145, v58, v59
	v_cvt_pk_fp8_f32 v146, v54, v55
	v_cvt_pk_fp8_f32 v147, v46, v47
	v_cvt_pk_fp8_f32 v144, v64, v65 op_sel:[0,0,1]
	v_cvt_pk_fp8_f32 v145, v60, v61 op_sel:[0,0,1]
	v_cvt_pk_fp8_f32 v146, v56, v57 op_sel:[0,0,1]
	v_cvt_pk_fp8_f32 v147, v48, v49 op_sel:[0,0,1]
	v_add_u32_e32 v154, 0x20000, v152
	s_nop 0
	global_store_dwordx4 v154, v[144:147], s[68:69]
	s_mov_b32 s100, 1
	v_pk_mul_f32 v[50:51], v[50:51], 0.5 op_sel_hi:[1,0]
	v_pk_mul_f32 v[52:53], v[52:53], 0.5 op_sel_hi:[1,0]
	v_pk_mul_f32 v[42:43], v[42:43], 0.5 op_sel_hi:[1,0]
	v_pk_mul_f32 v[44:45], v[44:45], 0.5 op_sel_hi:[1,0]
	v_pk_mul_f32 v[38:39], v[38:39], 0.5 op_sel_hi:[1,0]
	v_pk_mul_f32 v[40:41], v[40:41], 0.5 op_sel_hi:[1,0]
	v_pk_mul_f32 v[30:31], v[30:31], 0.5 op_sel_hi:[1,0]
	v_pk_mul_f32 v[32:33], v[32:33], 0.5 op_sel_hi:[1,0]
	v_cvt_pk_fp8_f32 v148, v50, v51
	v_cvt_pk_fp8_f32 v149, v42, v43
	v_cvt_pk_fp8_f32 v150, v38, v39
	v_cvt_pk_fp8_f32 v151, v30, v31
	v_cvt_pk_fp8_f32 v148, v52, v53 op_sel:[0,0,1]
	v_cvt_pk_fp8_f32 v149, v44, v45 op_sel:[0,0,1]
	v_cvt_pk_fp8_f32 v150, v40, v41 op_sel:[0,0,1]
	v_cvt_pk_fp8_f32 v151, v32, v33 op_sel:[0,0,1]
	v_add_u32_e32 v155, 0x24000, v152
	s_nop 0
	global_store_dwordx4 v155, v[148:151], s[68:69]
	s_mov_b32 s100, 1
	v_pk_mul_f32 v[34:35], v[34:35], 0.5 op_sel_hi:[1,0]
	v_pk_mul_f32 v[36:37], v[36:37], 0.5 op_sel_hi:[1,0]
	v_pk_mul_f32 v[26:27], v[26:27], 0.5 op_sel_hi:[1,0]
	v_pk_mul_f32 v[28:29], v[28:29], 0.5 op_sel_hi:[1,0]
	v_pk_mul_f32 v[22:23], v[22:23], 0.5 op_sel_hi:[1,0]
	v_pk_mul_f32 v[24:25], v[24:25], 0.5 op_sel_hi:[1,0]
	v_pk_mul_f32 v[14:15], v[14:15], 0.5 op_sel_hi:[1,0]
	v_pk_mul_f32 v[16:17], v[16:17], 0.5 op_sel_hi:[1,0]
	v_cvt_pk_fp8_f32 v144, v34, v35
	v_cvt_pk_fp8_f32 v145, v26, v27
	v_cvt_pk_fp8_f32 v146, v22, v23
	v_cvt_pk_fp8_f32 v147, v14, v15
	v_cvt_pk_fp8_f32 v144, v36, v37 op_sel:[0,0,1]
	v_cvt_pk_fp8_f32 v145, v28, v29 op_sel:[0,0,1]
	v_cvt_pk_fp8_f32 v146, v24, v25 op_sel:[0,0,1]
	v_cvt_pk_fp8_f32 v147, v16, v17 op_sel:[0,0,1]
	v_add_u32_e32 v154, 0x28000, v152
	s_nop 0
	global_store_dwordx4 v154, v[144:147], s[68:69]
	s_mov_b32 s100, 1
	v_pk_mul_f32 v[230:231], v[230:231], 0.5 op_sel_hi:[1,0]
	v_pk_mul_f32 v[232:233], v[232:233], 0.5 op_sel_hi:[1,0]
	v_pk_mul_f32 v[10:11], v[10:11], 0.5 op_sel_hi:[1,0]
	v_pk_mul_f32 v[12:13], v[12:13], 0.5 op_sel_hi:[1,0]
	v_pk_mul_f32 v[6:7], v[6:7], 0.5 op_sel_hi:[1,0]
	v_pk_mul_f32 v[8:9], v[8:9], 0.5 op_sel_hi:[1,0]
	v_pk_mul_f32 v[2:3], v[2:3], 0.5 op_sel_hi:[1,0]
	v_pk_mul_f32 v[4:5], v[4:5], 0.5 op_sel_hi:[1,0]
	v_cvt_pk_fp8_f32 v148, v230, v231
	v_cvt_pk_fp8_f32 v149, v10, v11
	v_cvt_pk_fp8_f32 v150, v6, v7
	v_cvt_pk_fp8_f32 v151, v2, v3
	v_cvt_pk_fp8_f32 v148, v232, v233 op_sel:[0,0,1]
	v_cvt_pk_fp8_f32 v149, v12, v13 op_sel:[0,0,1]
	v_cvt_pk_fp8_f32 v150, v8, v9 op_sel:[0,0,1]
	v_cvt_pk_fp8_f32 v151, v4, v5 op_sel:[0,0,1]
	v_add_u32_e32 v155, 0x2c000, v152
	s_nop 0
	global_store_dwordx4 v155, v[148:151], s[68:69]
	s_mov_b32 s100, 1
	s_and_b64 vcc, exec, s[4:5]
	s_cbranch_vccz .LBB0_2500
	s_waitcnt vmcnt(0)
	s_cmpk_gt_u32 s3, 0xff
	s_cbranch_scc1 .LBB0_2513
	s_barrier

.LBB0_2682:
	ds_read_b128 v[136:139], v147
	ds_read_b128 v[140:143], v147 offset:1024
	ds_read_b128 v[152:155], v147 offset:2048
	ds_read_b128 v[156:159], v147 offset:3072
	s_add_i32 s10, s7, 0xfffa0080
	s_cmp_eq_u32 s84, 12
	s_cselect_b32 s86, s6, s10
	s_cselect_b32 s85, s59, s79
	s_or_b32 s87, s86, 0x80
	s_add_i32 s10, s7, 0xfffe0000
	s_mov_b32 m0, s39
	ds_read_b128 v[160:163], v148
	ds_read_b128 v[164:167], v148 offset:1024
	ds_read_b128 v[168:171], v148 offset:2048
	ds_read_b128 v[172:175], v148 offset:3072
	ds_read_b128 v[176:179], v148 offset:4096
	ds_read_b128 v[180:183], v148 offset:5120
	ds_read_b128 v[184:187], v148 offset:6144
	ds_read_b128 v[188:191], v148 offset:7168
	buffer_load_dwordx4 v1, s[40:43], s10 offen lds
	s_mov_b32 m0, s45
	s_nop 0
	buffer_load_dwordx4 v1, s[40:43], s7 offen lds
	s_waitcnt lgkmcnt(8)
	s_barrier
	s_waitcnt lgkmcnt(0)
	s_setprio 1
	s_waitcnt lgkmcnt(7)
	v_mfma_f32_16x16x32_bf16 v[126:129], v[136:139], v[160:163], v[126:129]
	v_mfma_f32_16x16x32_bf16 v[122:125], v[152:155], v[160:163], v[122:125]
	s_waitcnt lgkmcnt(5)
	v_mfma_f32_16x16x32_bf16 v[118:121], v[136:139], v[168:171], v[118:121]
	v_mfma_f32_16x16x32_bf16 v[110:113], v[152:155], v[168:171], v[110:113]
	s_waitcnt lgkmcnt(3)
	v_mfma_f32_16x16x32_bf16 v[102:105], v[136:139], v[176:179], v[102:105]
	v_mfma_f32_16x16x32_bf16 v[94:97], v[152:155], v[176:179], v[94:97]
	s_waitcnt lgkmcnt(1)
	v_mfma_f32_16x16x32_bf16 v[86:89], v[136:139], v[184:187], v[86:89]
	v_mfma_f32_16x16x32_bf16 v[78:81], v[152:155], v[184:187], v[78:81]
	v_mfma_f32_16x16x32_bf16 v[126:129], v[140:143], v[164:167], v[126:129]
	v_mfma_f32_16x16x32_bf16 v[122:125], v[156:159], v[164:167], v[122:125]
	v_mfma_f32_16x16x32_bf16 v[118:121], v[140:143], v[172:175], v[118:121]
	v_mfma_f32_16x16x32_bf16 v[110:113], v[156:159], v[172:175], v[110:113]
	v_mfma_f32_16x16x32_bf16 v[102:105], v[140:143], v[180:183], v[102:105]
	v_mfma_f32_16x16x32_bf16 v[94:97], v[156:159], v[180:183], v[94:97]
	s_waitcnt lgkmcnt(0)
	v_mfma_f32_16x16x32_bf16 v[86:89], v[140:143], v[188:191], v[86:89]
	v_mfma_f32_16x16x32_bf16 v[78:81], v[156:159], v[188:191], v[78:81]
	s_setprio 0
	s_barrier
	s_mov_b32 m0, s23
	s_mov_b32 s10, s42
	s_mov_b32 s11, s43
	ds_read_b128 v[192:195], v149
	ds_read_b128 v[196:199], v149 offset:1024
	ds_read_b128 v[200:203], v149 offset:2048
	ds_read_b128 v[204:207], v149 offset:3072
	buffer_load_dwordx4 v144, s[8:11], s85 offen lds
	s_add_i32 s33, s85, 0x20000
	s_mov_b32 m0, s24
	s_nop 0
	buffer_load_dwordx4 v144, s[8:11], s33 offen lds
	s_barrier
	s_waitcnt lgkmcnt(0)
	s_setprio 1
	s_waitcnt lgkmcnt(3)
	v_mfma_f32_16x16x32_bf16 v[114:117], v[192:195], v[160:163], v[114:117]
	s_waitcnt lgkmcnt(1)
	v_mfma_f32_16x16x32_bf16 v[106:109], v[200:203], v[160:163], v[106:109]
	v_mfma_f32_16x16x32_bf16 v[98:101], v[192:195], v[168:171], v[98:101]
	v_mfma_f32_16x16x32_bf16 v[90:93], v[200:203], v[168:171], v[90:93]
	v_mfma_f32_16x16x32_bf16 v[82:85], v[192:195], v[176:179], v[82:85]
	v_mfma_f32_16x16x32_bf16 v[74:77], v[200:203], v[176:179], v[74:77]
	v_mfma_f32_16x16x32_bf16 v[70:73], v[192:195], v[184:187], v[70:73]
	v_mfma_f32_16x16x32_bf16 v[66:69], v[200:203], v[184:187], v[66:69]
	v_mfma_f32_16x16x32_bf16 v[114:117], v[196:199], v[164:167], v[114:117]
	s_waitcnt lgkmcnt(0)
	v_mfma_f32_16x16x32_bf16 v[106:109], v[204:207], v[164:167], v[106:109]
	v_mfma_f32_16x16x32_bf16 v[98:101], v[196:199], v[172:175], v[98:101]
	v_mfma_f32_16x16x32_bf16 v[90:93], v[204:207], v[172:175], v[90:93]
	v_mfma_f32_16x16x32_bf16 v[82:85], v[196:199], v[180:183], v[82:85]
	v_mfma_f32_16x16x32_bf16 v[74:77], v[204:207], v[180:183], v[74:77]
	v_mfma_f32_16x16x32_bf16 v[70:73], v[196:199], v[188:191], v[70:73]
	v_mfma_f32_16x16x32_bf16 v[66:69], v[204:207], v[188:191], v[66:69]
	s_setprio 0
	s_mov_b32 m0, s22
	s_barrier
	ds_read_b128 v[160:163], v148 offset:16384
	ds_read_b128 v[164:167], v148 offset:17408
	ds_read_b128 v[168:171], v148 offset:18432
	ds_read_b128 v[172:175], v148 offset:19456
	ds_read_b128 v[176:179], v148 offset:20480
	ds_read_b128 v[180:183], v148 offset:21504
	ds_read_b128 v[184:187], v148 offset:22528
	ds_read_b128 v[188:191], v148 offset:23552
	buffer_load_dwordx4 v1, s[40:43], s86 offen lds
	s_add_i32 s33, s86, 0x20000
	s_mov_b32 m0, s25
	s_nop 0
	buffer_load_dwordx4 v1, s[40:43], s33 offen lds
	s_barrier
	s_waitcnt lgkmcnt(0)
	s_setprio 1
	s_waitcnt lgkmcnt(7)
	v_mfma_f32_16x16x32_bf16 v[62:65], v[136:139], v[160:163], v[62:65]
	v_mfma_f32_16x16x32_bf16 v[58:61], v[152:155], v[160:163], v[58:61]
	s_waitcnt lgkmcnt(5)
	v_mfma_f32_16x16x32_bf16 v[54:57], v[136:139], v[168:171], v[54:57]
	v_mfma_f32_16x16x32_bf16 v[46:49], v[152:155], v[168:171], v[46:49]
	s_waitcnt lgkmcnt(3)
	v_mfma_f32_16x16x32_bf16 v[38:41], v[136:139], v[176:179], v[38:41]
	v_mfma_f32_16x16x32_bf16 v[30:33], v[152:155], v[176:179], v[30:33]
	s_waitcnt lgkmcnt(1)
	v_mfma_f32_16x16x32_bf16 v[22:25], v[136:139], v[184:187], v[22:25]
	v_mfma_f32_16x16x32_bf16 v[14:17], v[152:155], v[184:187], v[14:17]
	v_mfma_f32_16x16x32_bf16 v[62:65], v[140:143], v[164:167], v[62:65]
	v_mfma_f32_16x16x32_bf16 v[58:61], v[156:159], v[164:167], v[58:61]
	v_mfma_f32_16x16x32_bf16 v[54:57], v[140:143], v[172:175], v[54:57]
	v_mfma_f32_16x16x32_bf16 v[46:49], v[156:159], v[172:175], v[46:49]
	v_mfma_f32_16x16x32_bf16 v[38:41], v[140:143], v[180:183], v[38:41]
	v_mfma_f32_16x16x32_bf16 v[30:33], v[156:159], v[180:183], v[30:33]
	s_waitcnt lgkmcnt(0)
	v_mfma_f32_16x16x32_bf16 v[22:25], v[140:143], v[188:191], v[22:25]
	v_mfma_f32_16x16x32_bf16 v[14:17], v[156:159], v[188:191], v[14:17]
	s_setprio 0
	s_barrier
	s_mov_b32 m0, s26
	s_add_i32 s33, s85, 0x40000
	buffer_load_dwordx4 v144, s[8:11], s33 offen lds
	s_add_i32 s33, s85, 0x60000
	s_mov_b32 m0, s27
	s_nop 0
	buffer_load_dwordx4 v144, s[8:11], s33 offen lds
	s_waitcnt vmcnt(6)
	s_barrier
	s_setprio 1
	v_mfma_f32_16x16x32_bf16 v[50:53], v[192:195], v[160:163], v[50:53]
	v_mfma_f32_16x16x32_bf16 v[42:45], v[200:203], v[160:163], v[42:45]
	v_mfma_f32_16x16x32_bf16 v[34:37], v[192:195], v[168:171], v[34:37]
	v_mfma_f32_16x16x32_bf16 v[26:29], v[200:203], v[168:171], v[26:29]
	v_mfma_f32_16x16x32_bf16 v[18:21], v[192:195], v[176:179], v[18:21]
	v_mfma_f32_16x16x32_bf16 v[10:13], v[200:203], v[176:179], v[10:13]
	v_mfma_f32_16x16x32_bf16 v[6:9], v[192:195], v[184:187], v[6:9]
	v_mfma_f32_16x16x32_bf16 v[2:5], v[200:203], v[184:187], v[2:5]
	v_mfma_f32_16x16x32_bf16 v[50:53], v[196:199], v[164:167], v[50:53]
	v_mfma_f32_16x16x32_bf16 v[42:45], v[204:207], v[164:167], v[42:45]
	v_mfma_f32_16x16x32_bf16 v[34:37], v[196:199], v[172:175], v[34:37]
	v_mfma_f32_16x16x32_bf16 v[26:29], v[204:207], v[172:175], v[26:29]
	v_mfma_f32_16x16x32_bf16 v[18:21], v[196:199], v[180:183], v[18:21]
	v_mfma_f32_16x16x32_bf16 v[10:13], v[204:207], v[180:183], v[10:13]
	v_mfma_f32_16x16x32_bf16 v[6:9], v[196:199], v[188:191], v[6:9]
	v_mfma_f32_16x16x32_bf16 v[2:5], v[204:207], v[188:191], v[2:5]
	s_setprio 0
	s_barrier
	ds_read_b128 v[136:139], v150
	ds_read_b128 v[140:143], v150 offset:1024
	ds_read_b128 v[152:155], v150 offset:2048
	ds_read_b128 v[156:159], v150 offset:3072
	s_mov_b32 m0, s28
	s_add_i32 s33, s86, 0x40000
	ds_read_b128 v[160:163], v148 offset:32768
	ds_read_b128 v[164:167], v148 offset:33792
	ds_read_b128 v[168:171], v148 offset:34816
	ds_read_b128 v[172:175], v148 offset:35840
	ds_read_b128 v[176:179], v148 offset:36864
	ds_read_b128 v[180:183], v148 offset:37888
	ds_read_b128 v[184:187], v148 offset:38912
	ds_read_b128 v[188:191], v148 offset:39936
	buffer_load_dwordx4 v1, s[40:43], s33 offen lds
	s_add_i32 s33, s86, 0x60000
	s_mov_b32 m0, s29
	s_nop 0
	buffer_load_dwordx4 v1, s[40:43], s33 offen lds
	s_waitcnt lgkmcnt(8)
	s_barrier
	s_waitcnt lgkmcnt(0)
	s_setprio 1
	s_waitcnt lgkmcnt(7)
	v_mfma_f32_16x16x32_bf16 v[126:129], v[136:139], v[160:163], v[126:129]
	v_mfma_f32_16x16x32_bf16 v[122:125], v[152:155], v[160:163], v[122:125]
	s_waitcnt lgkmcnt(5)
	v_mfma_f32_16x16x32_bf16 v[118:121], v[136:139], v[168:171], v[118:121]
	v_mfma_f32_16x16x32_bf16 v[110:113], v[152:155], v[168:171], v[110:113]
	s_waitcnt lgkmcnt(3)
	v_mfma_f32_16x16x32_bf16 v[102:105], v[136:139], v[176:179], v[102:105]
	v_mfma_f32_16x16x32_bf16 v[94:97], v[152:155], v[176:179], v[94:97]
	s_waitcnt lgkmcnt(1)
	v_mfma_f32_16x16x32_bf16 v[86:89], v[136:139], v[184:187], v[86:89]
	v_mfma_f32_16x16x32_bf16 v[78:81], v[152:155], v[184:187], v[78:81]
	v_mfma_f32_16x16x32_bf16 v[126:129], v[140:143], v[164:167], v[126:129]
	v_mfma_f32_16x16x32_bf16 v[122:125], v[156:159], v[164:167], v[122:125]
	v_mfma_f32_16x16x32_bf16 v[118:121], v[140:143], v[172:175], v[118:121]
	v_mfma_f32_16x16x32_bf16 v[110:113], v[156:159], v[172:175], v[110:113]
	v_mfma_f32_16x16x32_bf16 v[102:105], v[140:143], v[180:183], v[102:105]
	v_mfma_f32_16x16x32_bf16 v[94:97], v[156:159], v[180:183], v[94:97]
	s_waitcnt lgkmcnt(0)
	v_mfma_f32_16x16x32_bf16 v[86:89], v[140:143], v[188:191], v[86:89]
	v_mfma_f32_16x16x32_bf16 v[78:81], v[156:159], v[188:191], v[78:81]
	s_setprio 0
	s_barrier
	s_mov_b32 m0, s31
	s_or_b32 s33, s85, 0x80
	ds_read_b128 v[192:195], v151
	ds_read_b128 v[196:199], v151 offset:1024
	ds_read_b128 v[200:203], v151 offset:2048
	ds_read_b128 v[204:207], v151 offset:3072
	buffer_load_dwordx4 v144, s[8:11], s33 offen lds
	s_add_i32 s33, s85, 0x20080
	s_mov_b32 m0, s34
	s_nop 0
	buffer_load_dwordx4 v144, s[8:11], s33 offen lds
	s_waitcnt vmcnt(10)
	s_barrier
	s_waitcnt lgkmcnt(0)
	s_setprio 1
	s_waitcnt lgkmcnt(3)
	v_mfma_f32_16x16x32_bf16 v[114:117], v[192:195], v[160:163], v[114:117]
	s_waitcnt lgkmcnt(1)
	v_mfma_f32_16x16x32_bf16 v[106:109], v[200:203], v[160:163], v[106:109]
	v_mfma_f32_16x16x32_bf16 v[98:101], v[192:195], v[168:171], v[98:101]
	v_mfma_f32_16x16x32_bf16 v[90:93], v[200:203], v[168:171], v[90:93]
	v_mfma_f32_16x16x32_bf16 v[82:85], v[192:195], v[176:179], v[82:85]
	v_mfma_f32_16x16x32_bf16 v[74:77], v[200:203], v[176:179], v[74:77]
	v_mfma_f32_16x16x32_bf16 v[70:73], v[192:195], v[184:187], v[70:73]
	v_mfma_f32_16x16x32_bf16 v[66:69], v[200:203], v[184:187], v[66:69]
	v_mfma_f32_16x16x32_bf16 v[114:117], v[196:199], v[164:167], v[114:117]
	s_waitcnt lgkmcnt(0)
	v_mfma_f32_16x16x32_bf16 v[106:109], v[204:207], v[164:167], v[106:109]
	v_mfma_f32_16x16x32_bf16 v[98:101], v[196:199], v[172:175], v[98:101]
	v_mfma_f32_16x16x32_bf16 v[90:93], v[204:207], v[172:175], v[90:93]
	v_mfma_f32_16x16x32_bf16 v[82:85], v[196:199], v[180:183], v[82:85]
	v_mfma_f32_16x16x32_bf16 v[74:77], v[204:207], v[180:183], v[74:77]
	v_mfma_f32_16x16x32_bf16 v[70:73], v[196:199], v[188:191], v[70:73]
	v_mfma_f32_16x16x32_bf16 v[66:69], v[204:207], v[188:191], v[66:69]
	s_setprio 0
	s_mov_b32 m0, s35
	s_barrier
	ds_read_b128 v[160:163], v148 offset:49152
	ds_read_b128 v[164:167], v148 offset:50176
	ds_read_b128 v[168:171], v148 offset:51200
	ds_read_b128 v[172:175], v148 offset:52224
	ds_read_b128 v[176:179], v148 offset:53248
	ds_read_b128 v[180:183], v148 offset:54272
	ds_read_b128 v[184:187], v148 offset:55296
	ds_read_b128 v[188:191], v148 offset:56320
	buffer_load_dwordx4 v1, s[40:43], s87 offen lds
	s_add_i32 s86, s86, 0x20080
	s_mov_b32 m0, s36
	s_nop 0
	buffer_load_dwordx4 v1, s[40:43], s86 offen lds
	s_barrier
	s_waitcnt lgkmcnt(0)
	s_setprio 1
	s_waitcnt lgkmcnt(7)
	v_mfma_f32_16x16x32_bf16 v[62:65], v[136:139], v[160:163], v[62:65]
	v_mfma_f32_16x16x32_bf16 v[58:61], v[152:155], v[160:163], v[58:61]
	s_waitcnt lgkmcnt(5)
	v_mfma_f32_16x16x32_bf16 v[54:57], v[136:139], v[168:171], v[54:57]
	v_mfma_f32_16x16x32_bf16 v[46:49], v[152:155], v[168:171], v[46:49]
	s_waitcnt lgkmcnt(3)
	v_mfma_f32_16x16x32_bf16 v[38:41], v[136:139], v[176:179], v[38:41]
	v_mfma_f32_16x16x32_bf16 v[30:33], v[152:155], v[176:179], v[30:33]
	s_waitcnt lgkmcnt(1)
	v_mfma_f32_16x16x32_bf16 v[22:25], v[136:139], v[184:187], v[22:25]
	v_mfma_f32_16x16x32_bf16 v[14:17], v[152:155], v[184:187], v[14:17]
	v_mfma_f32_16x16x32_bf16 v[62:65], v[140:143], v[164:167], v[62:65]
	v_mfma_f32_16x16x32_bf16 v[58:61], v[156:159], v[164:167], v[58:61]
	v_mfma_f32_16x16x32_bf16 v[54:57], v[140:143], v[172:175], v[54:57]
	v_mfma_f32_16x16x32_bf16 v[46:49], v[156:159], v[172:175], v[46:49]
	v_mfma_f32_16x16x32_bf16 v[38:41], v[140:143], v[180:183], v[38:41]
	v_mfma_f32_16x16x32_bf16 v[30:33], v[156:159], v[180:183], v[30:33]
	s_waitcnt lgkmcnt(0)
	v_mfma_f32_16x16x32_bf16 v[22:25], v[140:143], v[188:191], v[22:25]
	v_mfma_f32_16x16x32_bf16 v[14:17], v[156:159], v[188:191], v[14:17]
	s_setprio 0
	s_barrier
	s_mov_b32 m0, s37
	s_add_i32 s33, s85, 0x40080
	buffer_load_dwordx4 v144, s[8:11], s33 offen lds
	s_add_i32 s85, s85, 0x60080
	s_mov_b32 m0, s38
	s_nop 0
	buffer_load_dwordx4 v144, s[8:11], s85 offen lds
	s_waitcnt vmcnt(6)
	s_barrier
	s_setprio 1
	v_mfma_f32_16x16x32_bf16 v[50:53], v[192:195], v[160:163], v[50:53]
	v_mfma_f32_16x16x32_bf16 v[42:45], v[200:203], v[160:163], v[42:45]
	v_mfma_f32_16x16x32_bf16 v[34:37], v[192:195], v[168:171], v[34:37]
	v_mfma_f32_16x16x32_bf16 v[26:29], v[200:203], v[168:171], v[26:29]
	v_mfma_f32_16x16x32_bf16 v[18:21], v[192:195], v[176:179], v[18:21]
	v_mfma_f32_16x16x32_bf16 v[10:13], v[200:203], v[176:179], v[10:13]
	v_mfma_f32_16x16x32_bf16 v[6:9], v[192:195], v[184:187], v[6:9]
	v_mfma_f32_16x16x32_bf16 v[2:5], v[200:203], v[184:187], v[2:5]
	v_mfma_f32_16x16x32_bf16 v[50:53], v[196:199], v[164:167], v[50:53]
	v_mfma_f32_16x16x32_bf16 v[42:45], v[204:207], v[164:167], v[42:45]
	v_mfma_f32_16x16x32_bf16 v[34:37], v[196:199], v[172:175], v[34:37]
	v_mfma_f32_16x16x32_bf16 v[26:29], v[204:207], v[172:175], v[26:29]
	v_mfma_f32_16x16x32_bf16 v[18:21], v[196:199], v[180:183], v[18:21]
	v_mfma_f32_16x16x32_bf16 v[10:13], v[204:207], v[180:183], v[10:13]
	v_mfma_f32_16x16x32_bf16 v[6:9], v[196:199], v[188:191], v[6:9]
	v_mfma_f32_16x16x32_bf16 v[2:5], v[204:207], v[188:191], v[2:5]
	s_setprio 0
	s_add_i32 s84, s84, 2
	s_addk_i32 s7, 0x100
	s_addk_i32 s79, 0x100
	s_cmp_gt_u32 s84, 13
	s_barrier
	s_cbranch_scc0 .LBB0_2682
	v_lshl_add_u32 v142, s78, 8, v145
	v_or_b32_e32 v140, 16, v142
	v_or_b32_e32 v138, 32, v142
	v_or_b32_e32 v136, 48, v142
	s_mov_b64 s[6:7], -1
	s_cmp_gt_i32 s73, 3
	v_ashrrev_i32_e32 v143, 31, v142
	v_ashrrev_i32_e32 v141, 31, v140
	v_ashrrev_i32_e32 v139, 31, v138
	v_ashrrev_i32_e32 v137, 31, v136
	s_cbranch_scc0 .LBB0_2685
	v_pk_mul_f32 v[154:155], v[128:129], v[116:117]
	v_pk_mul_f32 v[152:153], v[126:127], v[114:115]
	v_pk_mul_f32 v[156:157], v[124:125], v[108:109]
	v_pk_mul_f32 v[158:159], v[122:123], v[106:107]
	v_cvt_pk_bf16_f32 v152, v152, v153
	v_cvt_pk_bf16_f32 v153, v154, v155
	v_lshlrev_b32_e32 v134, 1, v146
	v_cvt_pk_bf16_f32 v154, v158, v159
	v_cvt_pk_bf16_f32 v155, v156, v157
	v_lshlrev_b64 v[156:157], 12, v[142:143]
	v_lshl_add_u64 v[156:157], s[82:83], 0, v[156:157]
	v_lshl_or_b32 v134, s73, 8, v134
	v_lshl_add_u64 v[156:157], v[156:157], 0, v[134:135]
	global_store_dwordx4 v[156:157], v[152:155], off offset:1024
	s_mov_b32 s100, 1
	v_pk_mul_f32 v[158:159], v[112:113], v[92:93]
	v_pk_mul_f32 v[160:161], v[110:111], v[90:91]
	v_pk_mul_f32 v[154:155], v[120:121], v[100:101]
	v_pk_mul_f32 v[152:153], v[118:119], v[98:99]
	s_mov_b64 s[6:7], 0
	v_cvt_pk_bf16_f32 v152, v152, v153
	v_cvt_pk_bf16_f32 v153, v154, v155
	v_cvt_pk_bf16_f32 v154, v160, v161
	v_cvt_pk_bf16_f32 v155, v158, v159
	v_lshlrev_b64 v[158:159], 12, v[140:141]
	v_lshl_add_u64 v[158:159], s[82:83], 0, v[158:159]
	v_lshl_add_u64 v[158:159], v[158:159], 0, v[134:135]
	global_store_dwordx4 v[158:159], v[152:155], off offset:1024
	s_mov_b32 s100, 1
	v_pk_mul_f32 v[158:159], v[96:97], v[76:77]
	v_pk_mul_f32 v[160:161], v[94:95], v[74:75]
	v_pk_mul_f32 v[154:155], v[104:105], v[84:85]
	v_pk_mul_f32 v[152:153], v[102:103], v[82:83]
	s_nop 0
	v_cvt_pk_bf16_f32 v152, v152, v153
	v_cvt_pk_bf16_f32 v153, v154, v155
	v_cvt_pk_bf16_f32 v154, v160, v161
	v_cvt_pk_bf16_f32 v155, v158, v159
	v_lshlrev_b64 v[158:159], 12, v[138:139]
	v_lshl_add_u64 v[158:159], s[82:83], 0, v[158:159]
	v_lshl_add_u64 v[158:159], v[158:159], 0, v[134:135]
	global_store_dwordx4 v[158:159], v[152:155], off offset:1024
	s_mov_b32 s100, 1
	v_pk_mul_f32 v[158:159], v[80:81], v[68:69]
	v_pk_mul_f32 v[160:161], v[78:79], v[66:67]
	v_pk_mul_f32 v[154:155], v[88:89], v[72:73]
	v_pk_mul_f32 v[152:153], v[86:87], v[70:71]
	s_nop 0
	v_cvt_pk_bf16_f32 v152, v152, v153
	v_cvt_pk_bf16_f32 v153, v154, v155
	v_cvt_pk_bf16_f32 v154, v160, v161
	v_cvt_pk_bf16_f32 v155, v158, v159
	v_lshlrev_b64 v[158:159], 12, v[136:137]
	v_lshl_add_u64 v[158:159], s[82:83], 0, v[158:159]
	v_lshl_add_u64 v[158:159], v[158:159], 0, v[134:135]
	global_store_dwordx4 v[158:159], v[152:155], off offset:1024
	s_mov_b32 s100, 1
	v_pk_mul_f32 v[158:159], v[60:61], v[44:45]
	v_pk_mul_f32 v[160:161], v[58:59], v[42:43]
	v_pk_mul_f32 v[154:155], v[64:65], v[52:53]
	v_pk_mul_f32 v[152:153], v[62:63], v[50:51]
	s_nop 0
	v_cvt_pk_bf16_f32 v152, v152, v153
	v_cvt_pk_bf16_f32 v153, v154, v155
	v_cvt_pk_bf16_f32 v154, v160, v161
	v_cvt_pk_bf16_f32 v155, v158, v159
	v_add_co_u32_e32 v158, vcc, s47, v156
	v_pk_mul_f32 v[160:161], v[46:47], v[26:27]
	s_nop 0
	v_addc_co_u32_e32 v159, vcc, 0, v157, vcc
	global_store_dwordx4 v[158:159], v[152:155], off offset:1024
	s_mov_b32 s100, 1
	v_pk_mul_f32 v[158:159], v[48:49], v[28:29]
	s_nop 0
	v_pk_mul_f32 v[154:155], v[56:57], v[36:37]
	v_pk_mul_f32 v[152:153], v[54:55], v[34:35]
	s_nop 0
	v_cvt_pk_bf16_f32 v152, v152, v153
	v_cvt_pk_bf16_f32 v153, v154, v155
	v_cvt_pk_bf16_f32 v154, v160, v161
	v_cvt_pk_bf16_f32 v155, v158, v159
	v_add_co_u32_e32 v158, vcc, s49, v156
	v_pk_mul_f32 v[160:161], v[30:31], v[10:11]
	s_nop 0
	v_addc_co_u32_e32 v159, vcc, 0, v157, vcc
	global_store_dwordx4 v[158:159], v[152:155], off offset:1024
	s_mov_b32 s100, 1
	v_pk_mul_f32 v[158:159], v[32:33], v[12:13]
	s_nop 0
	v_pk_mul_f32 v[154:155], v[40:41], v[20:21]
	v_pk_mul_f32 v[152:153], v[38:39], v[18:19]
	s_nop 0
	v_cvt_pk_bf16_f32 v152, v152, v153
	v_cvt_pk_bf16_f32 v153, v154, v155
	v_cvt_pk_bf16_f32 v154, v160, v161
	v_cvt_pk_bf16_f32 v155, v158, v159
	v_add_co_u32_e32 v158, vcc, s50, v156
	v_pk_mul_f32 v[160:161], v[14:15], v[2:3]
	s_nop 0
	v_addc_co_u32_e32 v159, vcc, 0, v157, vcc
	v_add_co_u32_e32 v156, vcc, 0xb0000, v156
	global_store_dwordx4 v[158:159], v[152:155], off offset:1024
	s_mov_b32 s100, 1
	s_nop 0
	v_addc_co_u32_e32 v157, vcc, 0, v157, vcc
	v_pk_mul_f32 v[154:155], v[24:25], v[8:9]
	v_pk_mul_f32 v[152:153], v[22:23], v[6:7]
	v_pk_mul_f32 v[158:159], v[16:17], v[4:5]
	v_cvt_pk_bf16_f32 v152, v152, v153
	v_cvt_pk_bf16_f32 v153, v154, v155
	v_cvt_pk_bf16_f32 v154, v160, v161
	s_nop 0
	v_cvt_pk_bf16_f32 v155, v158, v159
	global_store_dwordx4 v[156:157], v[152:155], off offset:1024
	s_mov_b32 s100, 1

.LBB0_2827:
	ds_read_b128 v[130:133], v196
	ds_read_b128 v[134:137], v196 offset:1024
	ds_read_b128 v[138:141], v196 offset:2048
	ds_read_b128 v[142:145], v196 offset:3072
	s_add_i32 s10, s7, 0xfffa0080
	s_cmp_eq_u32 s13, 12
	s_cselect_b32 s78, s6, s10
	s_cselect_b32 s73, s57, s12
	s_or_b32 s79, s78, 0x80
	s_add_i32 s10, s7, 0xfffe0000
	s_mov_b32 m0, s38
	ds_read_b128 v[146:149], v197
	ds_read_b128 v[150:153], v197 offset:1024
	ds_read_b128 v[154:157], v197 offset:2048
	ds_read_b128 v[158:161], v197 offset:3072
	ds_read_b128 v[162:165], v197 offset:4096
	ds_read_b128 v[166:169], v197 offset:5120
	ds_read_b128 v[170:173], v197 offset:6144
	ds_read_b128 v[174:177], v197 offset:7168
	buffer_load_dwordx4 v192, s[48:51], s10 offen lds
	s_mov_b32 m0, s39
	s_nop 0
	buffer_load_dwordx4 v192, s[48:51], s7 offen lds
	s_waitcnt lgkmcnt(8)
	s_barrier
	s_waitcnt lgkmcnt(0)
	s_setprio 1
	s_waitcnt lgkmcnt(7)
	v_mfma_f32_16x16x32_bf16 v[126:129], v[130:133], v[146:149], v[126:129]
	v_mfma_f32_16x16x32_bf16 v[122:125], v[138:141], v[146:149], v[122:125]
	s_waitcnt lgkmcnt(5)
	v_mfma_f32_16x16x32_bf16 v[110:113], v[130:133], v[154:157], v[110:113]
	v_mfma_f32_16x16x32_bf16 v[106:109], v[138:141], v[154:157], v[106:109]
	s_waitcnt lgkmcnt(3)
	v_mfma_f32_16x16x32_bf16 v[94:97], v[130:133], v[162:165], v[94:97]
	v_mfma_f32_16x16x32_bf16 v[90:93], v[138:141], v[162:165], v[90:93]
	s_waitcnt lgkmcnt(1)
	v_mfma_f32_16x16x32_bf16 v[78:81], v[130:133], v[170:173], v[78:81]
	v_mfma_f32_16x16x32_bf16 v[74:77], v[138:141], v[170:173], v[74:77]
	v_mfma_f32_16x16x32_bf16 v[126:129], v[134:137], v[150:153], v[126:129]
	v_mfma_f32_16x16x32_bf16 v[122:125], v[142:145], v[150:153], v[122:125]
	v_mfma_f32_16x16x32_bf16 v[110:113], v[134:137], v[158:161], v[110:113]
	v_mfma_f32_16x16x32_bf16 v[106:109], v[142:145], v[158:161], v[106:109]
	v_mfma_f32_16x16x32_bf16 v[94:97], v[134:137], v[166:169], v[94:97]
	v_mfma_f32_16x16x32_bf16 v[90:93], v[142:145], v[166:169], v[90:93]
	s_waitcnt lgkmcnt(0)
	v_mfma_f32_16x16x32_bf16 v[78:81], v[134:137], v[174:177], v[78:81]
	v_mfma_f32_16x16x32_bf16 v[74:77], v[142:145], v[174:177], v[74:77]
	s_setprio 0
	s_barrier
	s_mov_b32 m0, s16
	s_mov_b32 s10, s50
	s_mov_b32 s11, s51
	ds_read_b128 v[178:181], v198
	ds_read_b128 v[182:185], v198 offset:1024
	ds_read_b128 v[202:205], v198 offset:2048
	ds_read_b128 v[206:209], v198 offset:3072
	buffer_load_dwordx4 v193, s[8:11], s73 offen lds
	s_add_i32 s33, s73, 0x20000
	s_mov_b32 m0, s17
	s_nop 0
	buffer_load_dwordx4 v193, s[8:11], s33 offen lds
	s_barrier
	s_waitcnt lgkmcnt(0)
	s_setprio 1
	s_waitcnt lgkmcnt(3)
	v_mfma_f32_16x16x32_bf16 v[118:121], v[178:181], v[146:149], v[118:121]
	s_waitcnt lgkmcnt(1)
	v_mfma_f32_16x16x32_bf16 v[114:117], v[202:205], v[146:149], v[114:117]
	v_mfma_f32_16x16x32_bf16 v[102:105], v[178:181], v[154:157], v[102:105]
	v_mfma_f32_16x16x32_bf16 v[98:101], v[202:205], v[154:157], v[98:101]
	v_mfma_f32_16x16x32_bf16 v[86:89], v[178:181], v[162:165], v[86:89]
	v_mfma_f32_16x16x32_bf16 v[82:85], v[202:205], v[162:165], v[82:85]
	v_mfma_f32_16x16x32_bf16 v[70:73], v[178:181], v[170:173], v[70:73]
	v_mfma_f32_16x16x32_bf16 v[66:69], v[202:205], v[170:173], v[66:69]
	v_mfma_f32_16x16x32_bf16 v[118:121], v[182:185], v[150:153], v[118:121]
	s_waitcnt lgkmcnt(0)
	v_mfma_f32_16x16x32_bf16 v[114:117], v[206:209], v[150:153], v[114:117]
	v_mfma_f32_16x16x32_bf16 v[102:105], v[182:185], v[158:161], v[102:105]
	v_mfma_f32_16x16x32_bf16 v[98:101], v[206:209], v[158:161], v[98:101]
	v_mfma_f32_16x16x32_bf16 v[86:89], v[182:185], v[166:169], v[86:89]
	v_mfma_f32_16x16x32_bf16 v[82:85], v[206:209], v[166:169], v[82:85]
	v_mfma_f32_16x16x32_bf16 v[70:73], v[182:185], v[174:177], v[70:73]
	v_mfma_f32_16x16x32_bf16 v[66:69], v[206:209], v[174:177], v[66:69]
	s_setprio 0
	s_mov_b32 m0, s15
	s_barrier
	ds_read_b128 v[146:149], v197 offset:16384
	ds_read_b128 v[150:153], v197 offset:17408
	ds_read_b128 v[154:157], v197 offset:18432
	ds_read_b128 v[158:161], v197 offset:19456
	ds_read_b128 v[162:165], v197 offset:20480
	ds_read_b128 v[166:169], v197 offset:21504
	ds_read_b128 v[170:173], v197 offset:22528
	ds_read_b128 v[174:177], v197 offset:23552
	buffer_load_dwordx4 v192, s[48:51], s78 offen lds
	s_add_i32 s33, s78, 0x20000
	s_mov_b32 m0, s18
	s_nop 0
	buffer_load_dwordx4 v192, s[48:51], s33 offen lds
	s_barrier
	s_waitcnt lgkmcnt(0)
	s_setprio 1
	s_waitcnt lgkmcnt(7)
	v_mfma_f32_16x16x32_bf16 v[62:65], v[130:133], v[146:149], v[62:65]
	v_mfma_f32_16x16x32_bf16 v[58:61], v[138:141], v[146:149], v[58:61]
	s_waitcnt lgkmcnt(5)
	v_mfma_f32_16x16x32_bf16 v[46:49], v[130:133], v[154:157], v[46:49]
	v_mfma_f32_16x16x32_bf16 v[42:45], v[138:141], v[154:157], v[42:45]
	s_waitcnt lgkmcnt(3)
	v_mfma_f32_16x16x32_bf16 v[30:33], v[130:133], v[162:165], v[30:33]
	v_mfma_f32_16x16x32_bf16 v[26:29], v[138:141], v[162:165], v[26:29]
	s_waitcnt lgkmcnt(1)
	v_mfma_f32_16x16x32_bf16 v[14:17], v[130:133], v[170:173], v[14:17]
	v_mfma_f32_16x16x32_bf16 v[10:13], v[138:141], v[170:173], v[10:13]
	v_mfma_f32_16x16x32_bf16 v[62:65], v[134:137], v[150:153], v[62:65]
	v_mfma_f32_16x16x32_bf16 v[58:61], v[142:145], v[150:153], v[58:61]
	v_mfma_f32_16x16x32_bf16 v[46:49], v[134:137], v[158:161], v[46:49]
	v_mfma_f32_16x16x32_bf16 v[42:45], v[142:145], v[158:161], v[42:45]
	v_mfma_f32_16x16x32_bf16 v[30:33], v[134:137], v[166:169], v[30:33]
	v_mfma_f32_16x16x32_bf16 v[26:29], v[142:145], v[166:169], v[26:29]
	s_waitcnt lgkmcnt(0)
	v_mfma_f32_16x16x32_bf16 v[14:17], v[134:137], v[174:177], v[14:17]
	v_mfma_f32_16x16x32_bf16 v[10:13], v[142:145], v[174:177], v[10:13]
	s_setprio 0
	s_barrier
	s_mov_b32 m0, s19
	s_add_i32 s33, s73, 0x40000
	buffer_load_dwordx4 v193, s[8:11], s33 offen lds
	s_add_i32 s33, s73, 0x60000
	s_mov_b32 m0, s20
	s_nop 0
	buffer_load_dwordx4 v193, s[8:11], s33 offen lds
	s_waitcnt vmcnt(6)
	s_barrier
	s_setprio 1
	v_mfma_f32_16x16x32_bf16 v[54:57], v[178:181], v[146:149], v[54:57]
	v_mfma_f32_16x16x32_bf16 v[50:53], v[202:205], v[146:149], v[50:53]
	v_mfma_f32_16x16x32_bf16 v[38:41], v[178:181], v[154:157], v[38:41]
	v_mfma_f32_16x16x32_bf16 v[34:37], v[202:205], v[154:157], v[34:37]
	v_mfma_f32_16x16x32_bf16 v[22:25], v[178:181], v[162:165], v[22:25]
	v_mfma_f32_16x16x32_bf16 v[18:21], v[202:205], v[162:165], v[18:21]
	v_mfma_f32_16x16x32_bf16 v[6:9], v[178:181], v[170:173], v[6:9]
	v_mfma_f32_16x16x32_bf16 v[2:5], v[202:205], v[170:173], v[2:5]
	v_mfma_f32_16x16x32_bf16 v[54:57], v[182:185], v[150:153], v[54:57]
	v_mfma_f32_16x16x32_bf16 v[50:53], v[206:209], v[150:153], v[50:53]
	v_mfma_f32_16x16x32_bf16 v[38:41], v[182:185], v[158:161], v[38:41]
	v_mfma_f32_16x16x32_bf16 v[34:37], v[206:209], v[158:161], v[34:37]
	v_mfma_f32_16x16x32_bf16 v[22:25], v[182:185], v[166:169], v[22:25]
	v_mfma_f32_16x16x32_bf16 v[18:21], v[206:209], v[166:169], v[18:21]
	v_mfma_f32_16x16x32_bf16 v[6:9], v[182:185], v[174:177], v[6:9]
	v_mfma_f32_16x16x32_bf16 v[2:5], v[206:209], v[174:177], v[2:5]
	s_setprio 0
	s_barrier
	ds_read_b128 v[130:133], v199
	ds_read_b128 v[134:137], v199 offset:1024
	ds_read_b128 v[138:141], v199 offset:2048
	ds_read_b128 v[142:145], v199 offset:3072
	s_mov_b32 m0, s21
	s_add_i32 s33, s78, 0x40000
	ds_read_b128 v[146:149], v197 offset:32768
	ds_read_b128 v[150:153], v197 offset:33792
	ds_read_b128 v[154:157], v197 offset:34816
	ds_read_b128 v[158:161], v197 offset:35840
	ds_read_b128 v[162:165], v197 offset:36864
	ds_read_b128 v[166:169], v197 offset:37888
	ds_read_b128 v[170:173], v197 offset:38912
	ds_read_b128 v[174:177], v197 offset:39936
	buffer_load_dwordx4 v192, s[48:51], s33 offen lds
	s_add_i32 s33, s78, 0x60000
	s_mov_b32 m0, s22
	s_nop 0
	buffer_load_dwordx4 v192, s[48:51], s33 offen lds
	s_waitcnt lgkmcnt(8)
	s_barrier
	s_waitcnt lgkmcnt(0)
	s_setprio 1
	s_waitcnt lgkmcnt(7)
	v_mfma_f32_16x16x32_bf16 v[126:129], v[130:133], v[146:149], v[126:129]
	v_mfma_f32_16x16x32_bf16 v[122:125], v[138:141], v[146:149], v[122:125]
	s_waitcnt lgkmcnt(5)
	v_mfma_f32_16x16x32_bf16 v[110:113], v[130:133], v[154:157], v[110:113]
	v_mfma_f32_16x16x32_bf16 v[106:109], v[138:141], v[154:157], v[106:109]
	s_waitcnt lgkmcnt(3)
	v_mfma_f32_16x16x32_bf16 v[94:97], v[130:133], v[162:165], v[94:97]
	v_mfma_f32_16x16x32_bf16 v[90:93], v[138:141], v[162:165], v[90:93]
	s_waitcnt lgkmcnt(1)
	v_mfma_f32_16x16x32_bf16 v[78:81], v[130:133], v[170:173], v[78:81]
	v_mfma_f32_16x16x32_bf16 v[74:77], v[138:141], v[170:173], v[74:77]
	v_mfma_f32_16x16x32_bf16 v[126:129], v[134:137], v[150:153], v[126:129]
	v_mfma_f32_16x16x32_bf16 v[122:125], v[142:145], v[150:153], v[122:125]
	v_mfma_f32_16x16x32_bf16 v[110:113], v[134:137], v[158:161], v[110:113]
	v_mfma_f32_16x16x32_bf16 v[106:109], v[142:145], v[158:161], v[106:109]
	v_mfma_f32_16x16x32_bf16 v[94:97], v[134:137], v[166:169], v[94:97]
	v_mfma_f32_16x16x32_bf16 v[90:93], v[142:145], v[166:169], v[90:93]
	s_waitcnt lgkmcnt(0)
	v_mfma_f32_16x16x32_bf16 v[78:81], v[134:137], v[174:177], v[78:81]
	v_mfma_f32_16x16x32_bf16 v[74:77], v[142:145], v[174:177], v[74:77]
	s_setprio 0
	s_barrier
	s_mov_b32 m0, s28
	s_add_i32 s33, s73, 0x80
	ds_read_b128 v[178:181], v200
	ds_read_b128 v[182:185], v200 offset:1024
	ds_read_b128 v[202:205], v200 offset:2048
	ds_read_b128 v[206:209], v200 offset:3072
	buffer_load_dwordx4 v193, s[8:11], s33 offen lds
	s_add_i32 s33, s73, 0x20080
	s_mov_b32 m0, s29
	s_nop 0
	buffer_load_dwordx4 v193, s[8:11], s33 offen lds
	s_waitcnt vmcnt(10)
	s_barrier
	s_waitcnt lgkmcnt(0)
	s_setprio 1
	s_waitcnt lgkmcnt(3)
	v_mfma_f32_16x16x32_bf16 v[118:121], v[178:181], v[146:149], v[118:121]
	s_waitcnt lgkmcnt(1)
	v_mfma_f32_16x16x32_bf16 v[114:117], v[202:205], v[146:149], v[114:117]
	v_mfma_f32_16x16x32_bf16 v[102:105], v[178:181], v[154:157], v[102:105]
	v_mfma_f32_16x16x32_bf16 v[98:101], v[202:205], v[154:157], v[98:101]
	v_mfma_f32_16x16x32_bf16 v[86:89], v[178:181], v[162:165], v[86:89]
	v_mfma_f32_16x16x32_bf16 v[82:85], v[202:205], v[162:165], v[82:85]
	v_mfma_f32_16x16x32_bf16 v[70:73], v[178:181], v[170:173], v[70:73]
	v_mfma_f32_16x16x32_bf16 v[66:69], v[202:205], v[170:173], v[66:69]
	v_mfma_f32_16x16x32_bf16 v[118:121], v[182:185], v[150:153], v[118:121]
	s_waitcnt lgkmcnt(0)
	v_mfma_f32_16x16x32_bf16 v[114:117], v[206:209], v[150:153], v[114:117]
	v_mfma_f32_16x16x32_bf16 v[102:105], v[182:185], v[158:161], v[102:105]
	v_mfma_f32_16x16x32_bf16 v[98:101], v[206:209], v[158:161], v[98:101]
	v_mfma_f32_16x16x32_bf16 v[86:89], v[182:185], v[166:169], v[86:89]
	v_mfma_f32_16x16x32_bf16 v[82:85], v[206:209], v[166:169], v[82:85]
	v_mfma_f32_16x16x32_bf16 v[70:73], v[182:185], v[174:177], v[70:73]
	v_mfma_f32_16x16x32_bf16 v[66:69], v[206:209], v[174:177], v[66:69]
	s_setprio 0
	s_mov_b32 m0, s30
	s_barrier
	ds_read_b128 v[146:149], v197 offset:49152
	ds_read_b128 v[150:153], v197 offset:50176
	ds_read_b128 v[154:157], v197 offset:51200
	ds_read_b128 v[158:161], v197 offset:52224
	ds_read_b128 v[162:165], v197 offset:53248
	ds_read_b128 v[166:169], v197 offset:54272
	ds_read_b128 v[170:173], v197 offset:55296
	ds_read_b128 v[174:177], v197 offset:56320
	buffer_load_dwordx4 v192, s[48:51], s79 offen lds
	s_add_i32 s78, s78, 0x20080
	s_mov_b32 m0, s31
	s_nop 0
	buffer_load_dwordx4 v192, s[48:51], s78 offen lds
	s_barrier
	s_waitcnt lgkmcnt(0)
	s_setprio 1
	s_waitcnt lgkmcnt(7)
	v_mfma_f32_16x16x32_bf16 v[62:65], v[130:133], v[146:149], v[62:65]
	v_mfma_f32_16x16x32_bf16 v[58:61], v[138:141], v[146:149], v[58:61]
	s_waitcnt lgkmcnt(5)
	v_mfma_f32_16x16x32_bf16 v[46:49], v[130:133], v[154:157], v[46:49]
	v_mfma_f32_16x16x32_bf16 v[42:45], v[138:141], v[154:157], v[42:45]
	s_waitcnt lgkmcnt(3)
	v_mfma_f32_16x16x32_bf16 v[30:33], v[130:133], v[162:165], v[30:33]
	v_mfma_f32_16x16x32_bf16 v[26:29], v[138:141], v[162:165], v[26:29]
	s_waitcnt lgkmcnt(1)
	v_mfma_f32_16x16x32_bf16 v[14:17], v[130:133], v[170:173], v[14:17]
	v_mfma_f32_16x16x32_bf16 v[10:13], v[138:141], v[170:173], v[10:13]
	v_mfma_f32_16x16x32_bf16 v[62:65], v[134:137], v[150:153], v[62:65]
	v_mfma_f32_16x16x32_bf16 v[58:61], v[142:145], v[150:153], v[58:61]
	v_mfma_f32_16x16x32_bf16 v[46:49], v[134:137], v[158:161], v[46:49]
	v_mfma_f32_16x16x32_bf16 v[42:45], v[142:145], v[158:161], v[42:45]
	v_mfma_f32_16x16x32_bf16 v[30:33], v[134:137], v[166:169], v[30:33]
	v_mfma_f32_16x16x32_bf16 v[26:29], v[142:145], v[166:169], v[26:29]
	s_waitcnt lgkmcnt(0)
	v_mfma_f32_16x16x32_bf16 v[14:17], v[134:137], v[174:177], v[14:17]
	v_mfma_f32_16x16x32_bf16 v[10:13], v[142:145], v[174:177], v[10:13]
	s_setprio 0
	s_barrier
	s_mov_b32 m0, s34
	s_add_i32 s33, s73, 0x40080
	buffer_load_dwordx4 v193, s[8:11], s33 offen lds
	s_add_i32 s73, s73, 0x60080
	s_mov_b32 m0, s35
	s_nop 0
	buffer_load_dwordx4 v193, s[8:11], s73 offen lds
	s_waitcnt vmcnt(6)
	s_barrier
	s_setprio 1
	v_mfma_f32_16x16x32_bf16 v[54:57], v[178:181], v[146:149], v[54:57]
	v_mfma_f32_16x16x32_bf16 v[50:53], v[202:205], v[146:149], v[50:53]
	v_mfma_f32_16x16x32_bf16 v[38:41], v[178:181], v[154:157], v[38:41]
	v_mfma_f32_16x16x32_bf16 v[34:37], v[202:205], v[154:157], v[34:37]
	v_mfma_f32_16x16x32_bf16 v[22:25], v[178:181], v[162:165], v[22:25]
	v_mfma_f32_16x16x32_bf16 v[18:21], v[202:205], v[162:165], v[18:21]
	v_mfma_f32_16x16x32_bf16 v[6:9], v[178:181], v[170:173], v[6:9]
	v_mfma_f32_16x16x32_bf16 v[2:5], v[202:205], v[170:173], v[2:5]
	v_mfma_f32_16x16x32_bf16 v[54:57], v[182:185], v[150:153], v[54:57]
	v_mfma_f32_16x16x32_bf16 v[50:53], v[206:209], v[150:153], v[50:53]
	v_mfma_f32_16x16x32_bf16 v[38:41], v[182:185], v[158:161], v[38:41]
	v_mfma_f32_16x16x32_bf16 v[34:37], v[206:209], v[158:161], v[34:37]
	v_mfma_f32_16x16x32_bf16 v[22:25], v[182:185], v[166:169], v[22:25]
	v_mfma_f32_16x16x32_bf16 v[18:21], v[206:209], v[166:169], v[18:21]
	v_mfma_f32_16x16x32_bf16 v[6:9], v[182:185], v[174:177], v[6:9]
	v_mfma_f32_16x16x32_bf16 v[2:5], v[206:209], v[174:177], v[2:5]
	s_setprio 0
	s_add_i32 s13, s13, 2
	s_addk_i32 s7, 0x100
	s_addk_i32 s12, 0x100
	s_cmp_gt_u32 s13, 13
	s_barrier
	s_cbranch_scc0 .LBB0_2827
	s_cmpk_gt_i32 s59, 0x7f
	s_cselect_b64 s[6:7], -1, 0
	s_and_b64 vcc, exec, s[6:7]
	s_cbranch_vccz .LBB0_2816
	s_mov_b64 s[10:11], 0xc000
	s_mov_b64 s[12:13], 0xcb00000
	s_branch .LBB0_2817

.LBB0_3111:
	s_and_b64 s[14:15], s[6:7], exec
	s_cselect_b32 s57, 0, s9
	s_add_i32 s14, s50, s9
	s_or_b32 s51, s57, 0x80
	s_waitcnt lgkmcnt(8)
	s_barrier
	s_waitcnt lgkmcnt(0)
	s_and_b64 s[6:7], s[6:7], exec
	s_cselect_b32 s6, s45, s14
	s_add_i32 s7, s6, 0x80
	s_setprio 1
	s_waitcnt lgkmcnt(6)
	v_mfma_f32_16x16x128_f8f6f4 v[174:177], v[2:9], v[42:49], v[174:177]
	v_mfma_f32_16x16x128_f8f6f4 v[166:169], v[10:17], v[42:49], v[166:169]
	s_waitcnt lgkmcnt(4)
	v_mfma_f32_16x16x128_f8f6f4 v[158:161], v[2:9], v[34:41], v[158:161]
	v_mfma_f32_16x16x128_f8f6f4 v[150:153], v[10:17], v[34:41], v[150:153]
	s_waitcnt lgkmcnt(2)
	v_mfma_f32_16x16x128_f8f6f4 v[142:145], v[2:9], v[26:33], v[142:145]
	v_mfma_f32_16x16x128_f8f6f4 v[134:137], v[10:17], v[26:33], v[134:137]
	s_waitcnt lgkmcnt(0)
	v_mfma_f32_16x16x128_f8f6f4 v[126:129], v[2:9], v[18:25], v[126:129]
	v_mfma_f32_16x16x128_f8f6f4 v[118:121], v[10:17], v[18:25], v[118:121]
	s_setprio 0
	s_barrier
	s_mov_b32 m0, s17
	v_add_u32_e32 v199, 0x14000, v190
	s_mov_b32 s14, s42
	s_mov_b32 s15, s43
	ds_read_b128 v[200:203], v199
	ds_read_b128 v[204:207], v199 offset:1024
	ds_read_b128 v[208:211], v199 offset:2048
	ds_read_b128 v[212:215], v199 offset:3072
	buffer_load_dwordx4 v185, s[12:15], s6 offen lds
	s_add_i32 s33, s6, 0x10000
	s_mov_b32 m0, s18
	s_nop 0
	buffer_load_dwordx4 v185, s[12:15], s33 offen lds
	s_barrier
	s_waitcnt lgkmcnt(0)
	s_setprio 1
	s_waitcnt lgkmcnt(2)
	v_mfma_f32_16x16x128_f8f6f4 v[170:173], v[200:207], v[42:49], v[170:173]
	s_waitcnt lgkmcnt(0)
	v_mfma_f32_16x16x128_f8f6f4 v[162:165], v[208:215], v[42:49], v[162:165]
	v_mfma_f32_16x16x128_f8f6f4 v[154:157], v[200:207], v[34:41], v[154:157]
	v_mfma_f32_16x16x128_f8f6f4 v[146:149], v[208:215], v[34:41], v[146:149]
	v_mfma_f32_16x16x128_f8f6f4 v[138:141], v[200:207], v[26:33], v[138:141]
	v_mfma_f32_16x16x128_f8f6f4 v[130:133], v[208:215], v[26:33], v[130:133]
	v_mfma_f32_16x16x128_f8f6f4 v[122:125], v[200:207], v[18:25], v[122:125]
	v_mfma_f32_16x16x128_f8f6f4 v[114:117], v[208:215], v[18:25], v[114:117]
	s_setprio 0
	v_lshlrev_b32_e32 v199, 10, v187
	v_and_b32_e32 v199, 0x3fffc00, v199
	v_add_u32_e32 v216, v199, v184
	v_lshlrev_b32_e32 v199, 10, v186
	s_mov_b32 m0, s16
	v_and_b32_e32 v199, 0x3fffc00, v199
	s_barrier
	ds_read_b128 v[18:21], v192 offset:16384
	ds_read_b128 v[22:25], v192 offset:17408
	ds_read_b128 v[26:29], v192 offset:18432
	ds_read_b128 v[30:33], v192 offset:19456
	ds_read_b128 v[34:37], v192 offset:20480
	ds_read_b128 v[38:41], v192 offset:21504
	ds_read_b128 v[42:45], v192 offset:22528
	ds_read_b128 v[46:49], v192 offset:23552
	buffer_load_dwordx4 v216, s[40:43], s57 offen lds
	v_add_u32_e32 v217, v199, v184
	s_mov_b32 m0, s19
	s_nop 0
	buffer_load_dwordx4 v217, s[40:43], s57 offen lds
	s_barrier
	s_waitcnt lgkmcnt(0)
	s_setprio 1
	s_waitcnt lgkmcnt(6)
	v_mfma_f32_16x16x128_f8f6f4 v[110:113], v[2:9], v[18:25], v[110:113]
	v_mfma_f32_16x16x128_f8f6f4 v[102:105], v[10:17], v[18:25], v[102:105]
	s_waitcnt lgkmcnt(4)
	v_mfma_f32_16x16x128_f8f6f4 v[94:97], v[2:9], v[26:33], v[94:97]
	v_mfma_f32_16x16x128_f8f6f4 v[86:89], v[10:17], v[26:33], v[86:89]
	s_waitcnt lgkmcnt(2)
	v_mfma_f32_16x16x128_f8f6f4 v[78:81], v[2:9], v[34:41], v[78:81]
	v_mfma_f32_16x16x128_f8f6f4 v[70:73], v[10:17], v[34:41], v[70:73]
	s_waitcnt lgkmcnt(0)
	v_mfma_f32_16x16x128_f8f6f4 v[62:65], v[2:9], v[42:49], v[62:65]
	v_mfma_f32_16x16x128_f8f6f4 v[54:57], v[10:17], v[42:49], v[54:57]
	s_setprio 0
	s_barrier
	s_mov_b32 m0, s20
	s_add_i32 s33, s6, 0x20000
	buffer_load_dwordx4 v185, s[12:15], s33 offen lds
	s_add_i32 s33, s6, 0x30000
	s_mov_b32 m0, s21
	s_nop 0
	buffer_load_dwordx4 v185, s[12:15], s33 offen lds
	s_waitcnt vmcnt(6)
	s_barrier
	s_setprio 1
	v_mfma_f32_16x16x128_f8f6f4 v[106:109], v[200:207], v[18:25], v[106:109]
	v_mfma_f32_16x16x128_f8f6f4 v[98:101], v[208:215], v[18:25], v[98:101]
	v_mfma_f32_16x16x128_f8f6f4 v[90:93], v[200:207], v[26:33], v[90:93]
	v_mfma_f32_16x16x128_f8f6f4 v[82:85], v[208:215], v[26:33], v[82:85]
	v_mfma_f32_16x16x128_f8f6f4 v[74:77], v[200:207], v[34:41], v[74:77]
	v_mfma_f32_16x16x128_f8f6f4 v[66:69], v[208:215], v[34:41], v[66:69]
	v_mfma_f32_16x16x128_f8f6f4 v[58:61], v[200:207], v[42:49], v[58:61]
	v_mfma_f32_16x16x128_f8f6f4 v[50:53], v[208:215], v[42:49], v[50:53]
	s_setprio 0
	v_add_u32_e32 v14, 0x18000, v190
	s_barrier
	ds_read_b128 v[2:5], v14
	ds_read_b128 v[6:9], v14 offset:1024
	ds_read_b128 v[10:13], v14 offset:2048
	ds_read_b128 v[14:17], v14 offset:3072
	s_mov_b32 m0, s22
	ds_read_b128 v[18:21], v192 offset:32768
	ds_read_b128 v[22:25], v192 offset:33792
	ds_read_b128 v[26:29], v192 offset:34816
	ds_read_b128 v[30:33], v192 offset:35840
	ds_read_b128 v[34:37], v192 offset:36864
	ds_read_b128 v[38:41], v192 offset:37888
	ds_read_b128 v[42:45], v192 offset:38912
	ds_read_b128 v[46:49], v192 offset:39936
	buffer_load_dwordx4 v197, s[40:43], s57 offen lds
	s_mov_b32 m0, s23
	s_nop 0
	buffer_load_dwordx4 v198, s[40:43], s57 offen lds
	s_waitcnt lgkmcnt(8)
	s_barrier
	s_waitcnt lgkmcnt(0)
	s_setprio 1
	s_waitcnt lgkmcnt(6)
	v_mfma_f32_16x16x128_f8f6f4 v[174:177], v[2:9], v[18:25], v[174:177]
	v_mfma_f32_16x16x128_f8f6f4 v[166:169], v[10:17], v[18:25], v[166:169]
	s_waitcnt lgkmcnt(4)
	v_mfma_f32_16x16x128_f8f6f4 v[158:161], v[2:9], v[26:33], v[158:161]
	v_mfma_f32_16x16x128_f8f6f4 v[150:153], v[10:17], v[26:33], v[150:153]
	s_waitcnt lgkmcnt(2)
	v_mfma_f32_16x16x128_f8f6f4 v[142:145], v[2:9], v[34:41], v[142:145]
	v_mfma_f32_16x16x128_f8f6f4 v[134:137], v[10:17], v[34:41], v[134:137]
	s_waitcnt lgkmcnt(0)
	v_mfma_f32_16x16x128_f8f6f4 v[126:129], v[2:9], v[42:49], v[126:129]
	v_mfma_f32_16x16x128_f8f6f4 v[118:121], v[10:17], v[42:49], v[118:121]
	s_setprio 0
	s_barrier
	s_mov_b32 m0, s25
	v_add_u32_e32 v197, 0x1c000, v190
	ds_read_b128 v[198:201], v197
	ds_read_b128 v[202:205], v197 offset:1024
	ds_read_b128 v[206:209], v197 offset:2048
	ds_read_b128 v[210:213], v197 offset:3072
	buffer_load_dwordx4 v185, s[12:15], s7 offen lds
	s_add_i32 s7, s6, 0x10080
	s_mov_b32 m0, s26
	s_nop 0
	buffer_load_dwordx4 v185, s[12:15], s7 offen lds
	s_waitcnt vmcnt(10)
	s_barrier
	s_waitcnt lgkmcnt(0)
	s_setprio 1
	s_waitcnt lgkmcnt(2)
	v_mfma_f32_16x16x128_f8f6f4 v[170:173], v[198:205], v[18:25], v[170:173]
	s_waitcnt lgkmcnt(0)
	v_mfma_f32_16x16x128_f8f6f4 v[162:165], v[206:213], v[18:25], v[162:165]
	v_mfma_f32_16x16x128_f8f6f4 v[154:157], v[198:205], v[26:33], v[154:157]
	v_mfma_f32_16x16x128_f8f6f4 v[146:149], v[206:213], v[26:33], v[146:149]
	v_mfma_f32_16x16x128_f8f6f4 v[138:141], v[198:205], v[34:41], v[138:141]
	v_mfma_f32_16x16x128_f8f6f4 v[130:133], v[206:213], v[34:41], v[130:133]
	v_mfma_f32_16x16x128_f8f6f4 v[122:125], v[198:205], v[42:49], v[122:125]
	v_mfma_f32_16x16x128_f8f6f4 v[114:117], v[206:213], v[42:49], v[114:117]
	s_setprio 0
	s_mov_b32 m0, s27
	s_barrier
	ds_read_b128 v[18:21], v192 offset:49152
	ds_read_b128 v[22:25], v192 offset:50176
	ds_read_b128 v[26:29], v192 offset:51200
	ds_read_b128 v[30:33], v192 offset:52224
	ds_read_b128 v[34:37], v192 offset:53248
	ds_read_b128 v[38:41], v192 offset:54272
	ds_read_b128 v[42:45], v192 offset:55296
	ds_read_b128 v[46:49], v192 offset:56320
	buffer_load_dwordx4 v216, s[40:43], s51 offen lds
	s_mov_b32 m0, s28
	s_nop 0
	buffer_load_dwordx4 v217, s[40:43], s51 offen lds
	s_barrier
	s_waitcnt lgkmcnt(0)
	s_setprio 1
	s_waitcnt lgkmcnt(6)
	v_mfma_f32_16x16x128_f8f6f4 v[110:113], v[2:9], v[18:25], v[110:113]
	v_mfma_f32_16x16x128_f8f6f4 v[102:105], v[10:17], v[18:25], v[102:105]
	s_waitcnt lgkmcnt(4)
	v_mfma_f32_16x16x128_f8f6f4 v[94:97], v[2:9], v[26:33], v[94:97]
	v_mfma_f32_16x16x128_f8f6f4 v[86:89], v[10:17], v[26:33], v[86:89]
	s_waitcnt lgkmcnt(2)
	v_mfma_f32_16x16x128_f8f6f4 v[78:81], v[2:9], v[34:41], v[78:81]
	v_mfma_f32_16x16x128_f8f6f4 v[70:73], v[10:17], v[34:41], v[70:73]
	s_waitcnt lgkmcnt(0)
	v_mfma_f32_16x16x128_f8f6f4 v[62:65], v[2:9], v[42:49], v[62:65]
	v_mfma_f32_16x16x128_f8f6f4 v[54:57], v[10:17], v[42:49], v[54:57]
	s_setprio 0
	s_barrier
	s_mov_b32 m0, s29
	s_add_i32 s7, s6, 0x20080
	buffer_load_dwordx4 v185, s[12:15], s7 offen lds
	s_add_i32 s6, s6, 0x30080
	s_mov_b32 m0, s30
	s_nop 0
	buffer_load_dwordx4 v185, s[12:15], s6 offen lds
	s_waitcnt vmcnt(6)
	s_barrier
	s_setprio 1
	v_mfma_f32_16x16x128_f8f6f4 v[106:109], v[198:205], v[18:25], v[106:109]
	v_mfma_f32_16x16x128_f8f6f4 v[98:101], v[206:213], v[18:25], v[98:101]
	v_mfma_f32_16x16x128_f8f6f4 v[90:93], v[198:205], v[26:33], v[90:93]
	v_mfma_f32_16x16x128_f8f6f4 v[82:85], v[206:213], v[26:33], v[82:85]
	v_mfma_f32_16x16x128_f8f6f4 v[74:77], v[198:205], v[34:41], v[74:77]
	v_mfma_f32_16x16x128_f8f6f4 v[66:69], v[206:213], v[34:41], v[66:69]
	v_mfma_f32_16x16x128_f8f6f4 v[58:61], v[198:205], v[42:49], v[58:61]
	v_mfma_f32_16x16x128_f8f6f4 v[50:53], v[206:213], v[42:49], v[50:53]
	s_setprio 0
	s_add_i32 s8, s8, 2
	s_addk_i32 s9, 0x100
	s_cmp_gt_u32 s8, 5
	s_barrier
	s_cbranch_scc1 .LBB0_3099

.LBB0_3185:
	ds_read_b128 v[144:147], v138
	ds_read_b128 v[148:151], v138 offset:1024
	ds_read_b128 v[152:155], v138 offset:2048
	ds_read_b128 v[156:159], v138 offset:3072
	s_add_i32 s10, s7, 0xfffd0800
	s_cmp_eq_u32 s72, 4
	s_cselect_b32 s74, s6, s10
	s_cselect_b32 s73, s57, s71
	s_or_b32 s75, s74, 0x800
	s_add_i32 s10, s7, 0xffff0000
	s_mov_b32 m0, s38
	ds_read_b128 v[160:163], v139
	ds_read_b128 v[164:167], v139 offset:1024
	ds_read_b128 v[168:171], v139 offset:2048
	ds_read_b128 v[172:175], v139 offset:3072
	ds_read_b128 v[176:179], v139 offset:4096
	ds_read_b128 v[180:183], v139 offset:5120
	ds_read_b128 v[184:187], v139 offset:6144
	ds_read_b128 v[188:191], v139 offset:7168
	buffer_load_dwordx4 v134, s[44:47], s10 offen lds
	s_mov_b32 m0, s39
	s_nop 0
	buffer_load_dwordx4 v134, s[44:47], s7 offen lds
	s_waitcnt lgkmcnt(8)
	s_barrier
	s_waitcnt lgkmcnt(0)
	s_setprio 1
	s_waitcnt lgkmcnt(4)
	v_mfma_f32_16x16x128_f8f6f4 v[114:117], v[144:151], v[168:175], v[114:117]
	v_mfma_f32_16x16x128_f8f6f4 v[106:109], v[152:159], v[168:175], v[106:109]
	s_waitcnt lgkmcnt(2)
	v_mfma_f32_16x16x128_f8f6f4 v[98:101], v[144:151], v[176:183], v[98:101]
	v_mfma_f32_16x16x128_f8f6f4 v[200:203], v[144:151], v[160:167], v[126:129]
	v_mfma_f32_16x16x128_f8f6f4 v[204:207], v[152:159], v[160:167], v[122:125]
	v_mfma_f32_16x16x128_f8f6f4 v[208:211], v[152:159], v[176:183], v[90:93]
	s_waitcnt lgkmcnt(0)
	v_mfma_f32_16x16x128_f8f6f4 v[212:215], v[144:151], v[184:191], v[82:85]
	v_mfma_f32_16x16x128_f8f6f4 v[216:219], v[152:159], v[184:191], v[74:77]
	s_setprio 0
	s_barrier
	s_mov_b32 m0, s22
	s_mov_b32 s10, s46
	s_mov_b32 s11, s47
	ds_read_b128 v[122:125], v254
	ds_read_b128 v[126:129], v254 offset:1024
	ds_read_b128 v[192:195], v254 offset:2048
	ds_read_b128 v[196:199], v254 offset:3072
	buffer_load_dwordx4 v135, s[8:11], s73 offen lds
	s_add_i32 s33, s73, 0x20000
	s_mov_b32 m0, s23
	s_nop 0
	buffer_load_dwordx4 v135, s[8:11], s33 offen lds
	s_barrier
	s_waitcnt lgkmcnt(0)
	s_setprio 1
	s_waitcnt lgkmcnt(2)
	v_mfma_f32_16x16x128_f8f6f4 v[118:121], v[122:129], v[160:167], v[118:121]
	s_waitcnt lgkmcnt(0)
	v_mfma_f32_16x16x128_f8f6f4 v[110:113], v[192:199], v[160:167], v[110:113]
	v_mfma_f32_16x16x128_f8f6f4 v[102:105], v[122:129], v[168:175], v[102:105]
	v_mfma_f32_16x16x128_f8f6f4 v[160:163], v[192:199], v[168:175], v[94:97]
	v_mfma_f32_16x16x128_f8f6f4 v[164:167], v[122:129], v[176:183], v[86:89]
	v_mfma_f32_16x16x128_f8f6f4 v[168:171], v[192:199], v[176:183], v[78:81]
	v_mfma_f32_16x16x128_f8f6f4 v[172:175], v[122:129], v[184:191], v[70:73]
	v_mfma_f32_16x16x128_f8f6f4 v[176:179], v[192:199], v[184:191], v[18:21]
	s_setprio 0
	s_mov_b32 m0, s21
	s_barrier
	ds_read_b128 v[66:69], v139 offset:16384
	s_nop 1
	ds_read_b128 v[70:73], v139 offset:17408
	ds_read_b128 v[74:77], v139 offset:18432
	ds_read_b128 v[78:81], v139 offset:19456
	ds_read_b128 v[82:85], v139 offset:20480
	ds_read_b128 v[86:89], v139 offset:21504
	ds_read_b128 v[90:93], v139 offset:22528
	ds_read_b128 v[94:97], v139 offset:23552
	buffer_load_dwordx4 v134, s[44:47], s74 offen lds
	s_add_i32 s33, s74, 0x10000
	s_mov_b32 m0, s24
	s_nop 0
	buffer_load_dwordx4 v134, s[44:47], s33 offen lds
	s_barrier
	s_waitcnt lgkmcnt(0)
	s_setprio 1
	s_waitcnt lgkmcnt(6)
	v_mfma_f32_16x16x128_f8f6f4 v[62:65], v[144:151], v[66:73], v[62:65]
	v_mfma_f32_16x16x128_f8f6f4 v[58:61], v[152:159], v[66:73], v[58:61]
	s_waitcnt lgkmcnt(4)
	v_mfma_f32_16x16x128_f8f6f4 v[50:53], v[144:151], v[74:81], v[50:53]
	s_waitcnt lgkmcnt(0)
	v_mfma_f32_16x16x128_f8f6f4 v[232:235], v[144:151], v[90:97], v[232:235]
	v_mfma_f32_16x16x128_f8f6f4 v[220:223], v[152:159], v[74:81], v[42:45]
	v_mfma_f32_16x16x128_f8f6f4 v[224:227], v[144:151], v[82:89], v[34:37]
	v_mfma_f32_16x16x128_f8f6f4 v[228:231], v[152:159], v[82:89], v[26:29]
	v_mfma_f32_16x16x128_f8f6f4 v[236:239], v[152:159], v[90:97], v[10:13]
	s_setprio 0
	s_barrier
	s_mov_b32 m0, s25
	s_add_i32 s33, s73, 0x2000
	buffer_load_dwordx4 v135, s[8:11], s33 offen lds
	s_add_i32 s33, s73, 0x22000
	s_mov_b32 m0, s26
	s_nop 0
	buffer_load_dwordx4 v135, s[8:11], s33 offen lds
	s_waitcnt vmcnt(6)
	s_barrier
	s_setprio 1
	v_mfma_f32_16x16x128_f8f6f4 v[54:57], v[122:129], v[66:73], v[54:57]
	v_mfma_f32_16x16x128_f8f6f4 v[240:243], v[192:199], v[66:73], v[46:49]
	v_mfma_f32_16x16x128_f8f6f4 v[244:247], v[122:129], v[74:81], v[38:41]
	v_mfma_f32_16x16x128_f8f6f4 v[248:251], v[192:199], v[74:81], v[30:33]
	v_mfma_f32_16x16x128_f8f6f4 v[130:133], v[122:129], v[82:89], v[22:25]
	v_mfma_f32_16x16x128_f8f6f4 v[140:143], v[192:199], v[82:89], v[14:17]
	v_mfma_f32_16x16x128_f8f6f4 v[66:69], v[122:129], v[90:97], v[6:9]
	v_mfma_f32_16x16x128_f8f6f4 v[192:195], v[192:199], v[90:97], v[2:5]
	s_setprio 0
	s_barrier
	s_nop 4
	ds_read_b128 v[2:5], v252
	ds_read_b128 v[6:9], v252 offset:1024
	ds_read_b128 v[10:13], v252 offset:2048
	ds_read_b128 v[14:17], v252 offset:3072
	s_mov_b32 m0, s27
	s_add_i32 s33, s74, 0x20000
	ds_read_b128 v[18:21], v139 offset:32768
	ds_read_b128 v[22:25], v139 offset:33792
	ds_read_b128 v[26:29], v139 offset:34816
	ds_read_b128 v[30:33], v139 offset:35840
	ds_read_b128 v[34:37], v139 offset:36864
	ds_read_b128 v[38:41], v139 offset:37888
	ds_read_b128 v[42:45], v139 offset:38912
	ds_read_b128 v[46:49], v139 offset:39936
	buffer_load_dwordx4 v134, s[44:47], s33 offen lds
	s_add_i32 s33, s74, 0x30000
	s_mov_b32 m0, s28
	s_nop 0
	buffer_load_dwordx4 v134, s[44:47], s33 offen lds
	s_waitcnt lgkmcnt(8)
	s_barrier
	s_waitcnt lgkmcnt(0)
	s_setprio 1
	s_waitcnt lgkmcnt(6)
	v_mfma_f32_16x16x128_f8f6f4 v[126:129], v[2:9], v[18:25], v[200:203]
	v_mfma_f32_16x16x128_f8f6f4 v[122:125], v[10:17], v[18:25], v[204:207]
	s_waitcnt lgkmcnt(4)
	v_mfma_f32_16x16x128_f8f6f4 v[114:117], v[2:9], v[26:33], v[114:117]
	v_mfma_f32_16x16x128_f8f6f4 v[106:109], v[10:17], v[26:33], v[106:109]
	s_waitcnt lgkmcnt(2)
	v_mfma_f32_16x16x128_f8f6f4 v[98:101], v[2:9], v[34:41], v[98:101]
	v_mfma_f32_16x16x128_f8f6f4 v[90:93], v[10:17], v[34:41], v[208:211]
	s_waitcnt lgkmcnt(0)
	v_mfma_f32_16x16x128_f8f6f4 v[82:85], v[2:9], v[42:49], v[212:215]
	v_mfma_f32_16x16x128_f8f6f4 v[74:77], v[10:17], v[42:49], v[216:219]
	s_setprio 0
	s_barrier
	s_mov_b32 m0, s30
	s_add_i32 s33, s73, 0x80
	ds_read_b128 v[144:147], v253
	ds_read_b128 v[148:151], v253 offset:1024
	ds_read_b128 v[152:155], v253 offset:2048
	ds_read_b128 v[156:159], v253 offset:3072
	buffer_load_dwordx4 v135, s[8:11], s33 offen lds
	s_add_i32 s33, s73, 0x20080
	s_mov_b32 m0, s31
	s_nop 0
	buffer_load_dwordx4 v135, s[8:11], s33 offen lds
	s_waitcnt vmcnt(10)
	s_barrier
	s_waitcnt lgkmcnt(0)
	s_setprio 1
	s_waitcnt lgkmcnt(2)
	v_mfma_f32_16x16x128_f8f6f4 v[118:121], v[144:151], v[18:25], v[118:121]
	s_waitcnt lgkmcnt(0)
	v_mfma_f32_16x16x128_f8f6f4 v[110:113], v[152:159], v[18:25], v[110:113]
	v_mfma_f32_16x16x128_f8f6f4 v[102:105], v[144:151], v[26:33], v[102:105]
	v_mfma_f32_16x16x128_f8f6f4 v[94:97], v[152:159], v[26:33], v[160:163]
	v_mfma_f32_16x16x128_f8f6f4 v[86:89], v[144:151], v[34:41], v[164:167]
	v_mfma_f32_16x16x128_f8f6f4 v[78:81], v[152:159], v[34:41], v[168:171]
	v_mfma_f32_16x16x128_f8f6f4 v[70:73], v[144:151], v[42:49], v[172:175]
	v_mfma_f32_16x16x128_f8f6f4 v[18:21], v[152:159], v[42:49], v[176:179]
	s_setprio 0
	s_mov_b32 m0, s34
	s_barrier
	ds_read_b128 v[160:163], v139 offset:49152
	ds_read_b128 v[164:167], v139 offset:50176
	ds_read_b128 v[168:171], v139 offset:51200
	ds_read_b128 v[172:175], v139 offset:52224
	ds_read_b128 v[176:179], v139 offset:53248
	ds_read_b128 v[180:183], v139 offset:54272
	ds_read_b128 v[184:187], v139 offset:55296
	ds_read_b128 v[188:191], v139 offset:56320
	buffer_load_dwordx4 v134, s[44:47], s75 offen lds
	s_add_i32 s74, s74, 0x10800
	s_mov_b32 m0, s35
	s_nop 0
	buffer_load_dwordx4 v134, s[44:47], s74 offen lds
	s_barrier
	s_waitcnt lgkmcnt(0)
	s_setprio 1
	s_waitcnt lgkmcnt(6)
	v_mfma_f32_16x16x128_f8f6f4 v[62:65], v[2:9], v[160:167], v[62:65]
	v_mfma_f32_16x16x128_f8f6f4 v[58:61], v[10:17], v[160:167], v[58:61]
	s_waitcnt lgkmcnt(4)
	v_mfma_f32_16x16x128_f8f6f4 v[50:53], v[2:9], v[168:175], v[50:53]
	v_mfma_f32_16x16x128_f8f6f4 v[42:45], v[10:17], v[168:175], v[220:223]
	s_waitcnt lgkmcnt(2)
	v_mfma_f32_16x16x128_f8f6f4 v[34:37], v[2:9], v[176:183], v[224:227]
	v_mfma_f32_16x16x128_f8f6f4 v[26:29], v[10:17], v[176:183], v[228:231]
	s_waitcnt lgkmcnt(0)
	v_mfma_f32_16x16x128_f8f6f4 v[232:235], v[2:9], v[184:191], v[232:235]
	v_mfma_f32_16x16x128_f8f6f4 v[10:13], v[10:17], v[184:191], v[236:239]
	s_setprio 0
	s_barrier
	s_mov_b32 m0, s36
	s_add_i32 s33, s73, 0x2080
	buffer_load_dwordx4 v135, s[8:11], s33 offen lds
	s_add_i32 s73, s73, 0x22080
	s_mov_b32 m0, s37
	s_nop 0
	buffer_load_dwordx4 v135, s[8:11], s73 offen lds
	s_waitcnt vmcnt(6)
	s_barrier
	s_setprio 1
	v_mfma_f32_16x16x128_f8f6f4 v[54:57], v[144:151], v[160:167], v[54:57]
	v_mfma_f32_16x16x128_f8f6f4 v[46:49], v[152:159], v[160:167], v[240:243]
	v_mfma_f32_16x16x128_f8f6f4 v[38:41], v[144:151], v[168:175], v[244:247]
	v_mfma_f32_16x16x128_f8f6f4 v[30:33], v[152:159], v[168:175], v[248:251]
	v_mfma_f32_16x16x128_f8f6f4 v[22:25], v[144:151], v[176:183], v[130:133]
	v_mfma_f32_16x16x128_f8f6f4 v[14:17], v[152:159], v[176:183], v[140:143]
	v_mfma_f32_16x16x128_f8f6f4 v[6:9], v[144:151], v[184:191], v[66:69]
	v_mfma_f32_16x16x128_f8f6f4 v[2:5], v[152:159], v[184:191], v[192:195]
	s_setprio 0
	s_add_i32 s72, s72, 2
	s_addk_i32 s7, 0x1000
	s_addk_i32 s71, 0x100
	s_cmp_gt_u32 s72, 5
	s_barrier
	s_cbranch_scc0 .LBB0_3185
	v_lshl_add_u32 v152, s70, 8, v136
	v_lshlrev_b32_e32 v153, 1, v137
	v_lshl_or_b32 v153, s59, 8, v153
	v_lshl_add_u32 v152, v152, 10, v153
	s_mov_b32 s59, s50
	s_mov_b32 s70, s51
	s_mov_b32 s71, s57
	s_mov_b32 s72, s58
	v_pk_mul_f32 v[126:127], v[126:127], 0.5 op_sel_hi:[1,0]
	v_pk_mul_f32 v[128:129], v[128:129], 0.5 op_sel_hi:[1,0]
	v_pk_mul_f32 v[122:123], v[122:123], 0.5 op_sel_hi:[1,0]
	v_pk_mul_f32 v[124:125], v[124:125], 0.5 op_sel_hi:[1,0]
	v_pk_mul_f32 v[118:119], v[118:119], 0.5 op_sel_hi:[1,0]
	v_pk_mul_f32 v[120:121], v[120:121], 0.5 op_sel_hi:[1,0]
	v_pk_mul_f32 v[110:111], v[110:111], 0.5 op_sel_hi:[1,0]
	v_pk_mul_f32 v[112:113], v[112:113], 0.5 op_sel_hi:[1,0]
	v_cvt_pk_fp8_f32 v144, v126, v127
	v_cvt_pk_fp8_f32 v145, v122, v123
	v_cvt_pk_fp8_f32 v146, v118, v119
	v_cvt_pk_fp8_f32 v147, v110, v111
	v_cvt_pk_fp8_f32 v144, v128, v129 op_sel:[0,0,1]
	v_cvt_pk_fp8_f32 v145, v124, v125 op_sel:[0,0,1]
	v_cvt_pk_fp8_f32 v146, v120, v121 op_sel:[0,0,1]
	v_cvt_pk_fp8_f32 v147, v112, v113 op_sel:[0,0,1]
	v_mov_b32_e32 v154, v152
	s_nop 0
	global_store_dwordx4 v154, v[144:147], s[68:69]
	s_mov_b32 s100, 1
	v_pk_mul_f32 v[114:115], v[114:115], 0.5 op_sel_hi:[1,0]
	v_pk_mul_f32 v[116:117], v[116:117], 0.5 op_sel_hi:[1,0]
	v_pk_mul_f32 v[106:107], v[106:107], 0.5 op_sel_hi:[1,0]
	v_pk_mul_f32 v[108:109], v[108:109], 0.5 op_sel_hi:[1,0]
	v_pk_mul_f32 v[102:103], v[102:103], 0.5 op_sel_hi:[1,0]
	v_pk_mul_f32 v[104:105], v[104:105], 0.5 op_sel_hi:[1,0]
	v_pk_mul_f32 v[94:95], v[94:95], 0.5 op_sel_hi:[1,0]
	v_pk_mul_f32 v[96:97], v[96:97], 0.5 op_sel_hi:[1,0]
	v_cvt_pk_fp8_f32 v148, v114, v115
	v_cvt_pk_fp8_f32 v149, v106, v107
	v_cvt_pk_fp8_f32 v150, v102, v103
	v_cvt_pk_fp8_f32 v151, v94, v95
	v_cvt_pk_fp8_f32 v148, v116, v117 op_sel:[0,0,1]
	v_cvt_pk_fp8_f32 v149, v108, v109 op_sel:[0,0,1]
	v_cvt_pk_fp8_f32 v150, v104, v105 op_sel:[0,0,1]
	v_cvt_pk_fp8_f32 v151, v96, v97 op_sel:[0,0,1]
	v_add_u32_e32 v155, 0x4000, v152
	s_nop 0
	global_store_dwordx4 v155, v[148:151], s[68:69]
	s_mov_b32 s100, 1
	v_pk_mul_f32 v[98:99], v[98:99], 0.5 op_sel_hi:[1,0]
	v_pk_mul_f32 v[100:101], v[100:101], 0.5 op_sel_hi:[1,0]
	v_pk_mul_f32 v[90:91], v[90:91], 0.5 op_sel_hi:[1,0]
	v_pk_mul_f32 v[92:93], v[92:93], 0.5 op_sel_hi:[1,0]
	v_pk_mul_f32 v[86:87], v[86:87], 0.5 op_sel_hi:[1,0]
	v_pk_mul_f32 v[88:89], v[88:89], 0.5 op_sel_hi:[1,0]
	v_pk_mul_f32 v[78:79], v[78:79], 0.5 op_sel_hi:[1,0]
	v_pk_mul_f32 v[80:81], v[80:81], 0.5 op_sel_hi:[1,0]
	v_cvt_pk_fp8_f32 v144, v98, v99
	v_cvt_pk_fp8_f32 v145, v90, v91
	v_cvt_pk_fp8_f32 v146, v86, v87
	v_cvt_pk_fp8_f32 v147, v78, v79
	v_cvt_pk_fp8_f32 v144, v100, v101 op_sel:[0,0,1]
	v_cvt_pk_fp8_f32 v145, v92, v93 op_sel:[0,0,1]
	v_cvt_pk_fp8_f32 v146, v88, v89 op_sel:[0,0,1]
	v_cvt_pk_fp8_f32 v147, v80, v81 op_sel:[0,0,1]
	v_add_u32_e32 v154, 0x8000, v152
	s_nop 0
	global_store_dwordx4 v154, v[144:147], s[68:69]
	s_mov_b32 s100, 1
	v_pk_mul_f32 v[82:83], v[82:83], 0.5 op_sel_hi:[1,0]
	v_pk_mul_f32 v[84:85], v[84:85], 0.5 op_sel_hi:[1,0]
	v_pk_mul_f32 v[74:75], v[74:75], 0.5 op_sel_hi:[1,0]
	v_pk_mul_f32 v[76:77], v[76:77], 0.5 op_sel_hi:[1,0]
	v_pk_mul_f32 v[70:71], v[70:71], 0.5 op_sel_hi:[1,0]
	v_pk_mul_f32 v[72:73], v[72:73], 0.5 op_sel_hi:[1,0]
	v_pk_mul_f32 v[18:19], v[18:19], 0.5 op_sel_hi:[1,0]
	v_pk_mul_f32 v[20:21], v[20:21], 0.5 op_sel_hi:[1,0]
	v_cvt_pk_fp8_f32 v148, v82, v83
	v_cvt_pk_fp8_f32 v149, v74, v75
	v_cvt_pk_fp8_f32 v150, v70, v71
	v_cvt_pk_fp8_f32 v151, v18, v19
	v_cvt_pk_fp8_f32 v148, v84, v85 op_sel:[0,0,1]
	v_cvt_pk_fp8_f32 v149, v76, v77 op_sel:[0,0,1]
	v_cvt_pk_fp8_f32 v150, v72, v73 op_sel:[0,0,1]
	v_cvt_pk_fp8_f32 v151, v20, v21 op_sel:[0,0,1]
	v_add_u32_e32 v155, 0xc000, v152
	s_nop 0
	global_store_dwordx4 v155, v[148:151], s[68:69]
	s_mov_b32 s100, 1
	v_pk_mul_f32 v[62:63], v[62:63], 0.5 op_sel_hi:[1,0]
	v_pk_mul_f32 v[64:65], v[64:65], 0.5 op_sel_hi:[1,0]
	v_pk_mul_f32 v[58:59], v[58:59], 0.5 op_sel_hi:[1,0]
	v_pk_mul_f32 v[60:61], v[60:61], 0.5 op_sel_hi:[1,0]
	v_pk_mul_f32 v[54:55], v[54:55], 0.5 op_sel_hi:[1,0]
	v_pk_mul_f32 v[56:57], v[56:57], 0.5 op_sel_hi:[1,0]
	v_pk_mul_f32 v[46:47], v[46:47], 0.5 op_sel_hi:[1,0]
	v_pk_mul_f32 v[48:49], v[48:49], 0.5 op_sel_hi:[1,0]
	v_cvt_pk_fp8_f32 v144, v62, v63
	v_cvt_pk_fp8_f32 v145, v58, v59
	v_cvt_pk_fp8_f32 v146, v54, v55
	v_cvt_pk_fp8_f32 v147, v46, v47
	v_cvt_pk_fp8_f32 v144, v64, v65 op_sel:[0,0,1]
	v_cvt_pk_fp8_f32 v145, v60, v61 op_sel:[0,0,1]
	v_cvt_pk_fp8_f32 v146, v56, v57 op_sel:[0,0,1]
	v_cvt_pk_fp8_f32 v147, v48, v49 op_sel:[0,0,1]
	v_add_u32_e32 v154, 0x20000, v152
	s_nop 0
	global_store_dwordx4 v154, v[144:147], s[68:69]
	s_mov_b32 s100, 1
	v_pk_mul_f32 v[50:51], v[50:51], 0.5 op_sel_hi:[1,0]
	v_pk_mul_f32 v[52:53], v[52:53], 0.5 op_sel_hi:[1,0]
	v_pk_mul_f32 v[42:43], v[42:43], 0.5 op_sel_hi:[1,0]
	v_pk_mul_f32 v[44:45], v[44:45], 0.5 op_sel_hi:[1,0]
	v_pk_mul_f32 v[38:39], v[38:39], 0.5 op_sel_hi:[1,0]
	v_pk_mul_f32 v[40:41], v[40:41], 0.5 op_sel_hi:[1,0]
	v_pk_mul_f32 v[30:31], v[30:31], 0.5 op_sel_hi:[1,0]
	v_pk_mul_f32 v[32:33], v[32:33], 0.5 op_sel_hi:[1,0]
	v_cvt_pk_fp8_f32 v148, v50, v51
	v_cvt_pk_fp8_f32 v149, v42, v43
	v_cvt_pk_fp8_f32 v150, v38, v39
	v_cvt_pk_fp8_f32 v151, v30, v31
	v_cvt_pk_fp8_f32 v148, v52, v53 op_sel:[0,0,1]
	v_cvt_pk_fp8_f32 v149, v44, v45 op_sel:[0,0,1]
	v_cvt_pk_fp8_f32 v150, v40, v41 op_sel:[0,0,1]
	v_cvt_pk_fp8_f32 v151, v32, v33 op_sel:[0,0,1]
	v_add_u32_e32 v155, 0x24000, v152
	s_nop 0
	global_store_dwordx4 v155, v[148:151], s[68:69]
	s_mov_b32 s100, 1
	v_pk_mul_f32 v[34:35], v[34:35], 0.5 op_sel_hi:[1,0]
	v_pk_mul_f32 v[36:37], v[36:37], 0.5 op_sel_hi:[1,0]
	v_pk_mul_f32 v[26:27], v[26:27], 0.5 op_sel_hi:[1,0]
	v_pk_mul_f32 v[28:29], v[28:29], 0.5 op_sel_hi:[1,0]
	v_pk_mul_f32 v[22:23], v[22:23], 0.5 op_sel_hi:[1,0]
	v_pk_mul_f32 v[24:25], v[24:25], 0.5 op_sel_hi:[1,0]
	v_pk_mul_f32 v[14:15], v[14:15], 0.5 op_sel_hi:[1,0]
	v_pk_mul_f32 v[16:17], v[16:17], 0.5 op_sel_hi:[1,0]
	v_cvt_pk_fp8_f32 v144, v34, v35
	v_cvt_pk_fp8_f32 v145, v26, v27
	v_cvt_pk_fp8_f32 v146, v22, v23
	v_cvt_pk_fp8_f32 v147, v14, v15
	v_cvt_pk_fp8_f32 v144, v36, v37 op_sel:[0,0,1]
	v_cvt_pk_fp8_f32 v145, v28, v29 op_sel:[0,0,1]
	v_cvt_pk_fp8_f32 v146, v24, v25 op_sel:[0,0,1]
	v_cvt_pk_fp8_f32 v147, v16, v17 op_sel:[0,0,1]
	v_add_u32_e32 v154, 0x28000, v152
	s_nop 0
	global_store_dwordx4 v154, v[144:147], s[68:69]
	s_mov_b32 s100, 1
	v_pk_mul_f32 v[232:233], v[232:233], 0.5 op_sel_hi:[1,0]
	v_pk_mul_f32 v[234:235], v[234:235], 0.5 op_sel_hi:[1,0]
	v_pk_mul_f32 v[10:11], v[10:11], 0.5 op_sel_hi:[1,0]
	v_pk_mul_f32 v[12:13], v[12:13], 0.5 op_sel_hi:[1,0]
	v_pk_mul_f32 v[6:7], v[6:7], 0.5 op_sel_hi:[1,0]
	v_pk_mul_f32 v[8:9], v[8:9], 0.5 op_sel_hi:[1,0]
	v_pk_mul_f32 v[2:3], v[2:3], 0.5 op_sel_hi:[1,0]
	v_pk_mul_f32 v[4:5], v[4:5], 0.5 op_sel_hi:[1,0]
	v_cvt_pk_fp8_f32 v148, v232, v233
	v_cvt_pk_fp8_f32 v149, v10, v11
	v_cvt_pk_fp8_f32 v150, v6, v7
	v_cvt_pk_fp8_f32 v151, v2, v3
	v_cvt_pk_fp8_f32 v148, v234, v235 op_sel:[0,0,1]
	v_cvt_pk_fp8_f32 v149, v12, v13 op_sel:[0,0,1]
	v_cvt_pk_fp8_f32 v150, v8, v9 op_sel:[0,0,1]
	v_cvt_pk_fp8_f32 v151, v4, v5 op_sel:[0,0,1]
	v_add_u32_e32 v155, 0x2c000, v152
	s_nop 0
	global_store_dwordx4 v155, v[148:151], s[68:69]
	s_mov_b32 s100, 1
	s_and_b64 vcc, exec, s[4:5]
	s_cbranch_vccz .LBB0_3176
	s_waitcnt vmcnt(0)
	s_cmpk_gt_u32 s3, 0xff
	s_cbranch_scc1 .LBB0_3189
	s_barrier
